# ABI and SGI epilogue output stores (UG / Z, consumed cross-XCD) with sc1 nt like the H stores (on top of v70)
# speedup vs baseline: 1.1680x; 1.0004x over previous
;     __device__ __forceinline__ void operator()(const f32x4 (&acc)[2][2][4][2], const Unit& u, int ui, int wr, int wc, int fr, int fq) const {
;         asm volatile("" : "+v"(fr), "+v"(fq));
;         const int row0 = u.pm * BM + wr * 64 + fr, col0 = u.pn * BM + wc * 32 + 8 * fq;
;         float rs[2][4];
; #pragma unroll
;         for (int ai = 0; ai < 2; ++ai)
; #pragma unroll
;             for (int m = 0; m < 4; ++m) rs[ai][m] = row_rstd(lds, ui, ai * HALF + wr * 64 + m * 16 + fr);
; #pragma unroll
;         for (int ai = 0; ai < 2; ++ai)
; #pragma unroll
;             for (int m = 0; m < 4; ++m) { const float r = rs[ai][m]; const int row = row0 + ai * HALF + m * 16; bf16_t* rowp = Z + (size_t)row * 2048 + col0; float s1 = 0.f, s2 = 0.f;
; #pragma unroll
;                 for (int bj = 0; bj < 2; ++bj) { const f32x4 v0 = acc[ai][bj][m][0] * r, v1 = acc[ai][bj][m][1] * r;
;                     const f32x2 a = gelu_pk((f32x2){v0[0], v0[1]}), b = gelu_pk((f32x2){v0[2], v0[3]}), c = gelu_pk((f32x2){v1[0], v1[1]}), d = gelu_pk((f32x2){v1[2], v1[3]});
.LBB0_752:
	v_mov_b32_e32 v140, v176
	v_mov_b32_e32 v141, v177
	s_lshl_b32 s0, s10, 8
	v_add_u32_e32 v142, s45, v140
	v_lshl_add_u32 v140, s11, 8, v142
	v_lshlrev_b32_e32 v142, 2, v142
	v_lshl_add_u32 v142, s12, 10, v142
	v_add_u32_e32 v142, 0x20400, v142
	ds_read2_b32 v[168:169], v142 offset1:16
	ds_read2_b32 v[166:167], v142 offset0:32 offset1:48
	ds_read2_b32 v[164:165], v142 offset0:128 offset1:144
	ds_read2_b32 v[142:143], v142 offset0:160 offset1:176
	s_mov_b32 s56, 0x3e6d3388
	s_waitcnt lgkmcnt(0)
	v_pk_mul_f32 v[172:173], v[124:125], v[168:169] op_sel_hi:[1,0]
	s_or_b32 s0, s0, s47
	v_and_b32_e32 v125, 0x7fffffff, v173
	v_and_b32_e32 v124, 0x7fffffff, v172
	v_pk_fma_f32 v[124:125], v[124:125], s[56:57], 1.0 op_sel_hi:[1,0,0]
	s_cmp_gt_i32 s10, 3
	v_rcp_f32_e32 v174, v124
	v_rcp_f32_e32 v175, v125
	v_lshl_add_u32 v162, v141, 3, s0
	s_cselect_b64 s[0:1], -1, 0
	s_lshl_b32 s2, s10, 2
	s_add_i32 s38, s2, -16
	s_mov_b32 s2, 0xbf3a00e3
	v_mov_b64_e32 v[124:125], s[2:3]
	s_mov_b32 s2, 0x3f07dc22
	v_pk_mul_f32 v[182:183], v[120:121], v[168:169] op_sel_hi:[1,0]
	v_pk_fma_f32 v[120:121], v[174:175], s[2:3], v[124:125] op_sel_hi:[1,0,0]
	s_mov_b32 s4, 0x3f35f0e3
	v_pk_fma_f32 v[120:121], v[174:175], v[120:121], s[4:5] op_sel_hi:[1,1,0]
	s_mov_b32 s12, 0xbe11a98e
	v_pk_fma_f32 v[120:121], v[174:175], v[120:121], s[12:13] op_sel_hi:[1,1,0]
	s_mov_b32 s88, 0x3e027906
	v_pk_fma_f32 v[120:121], v[174:175], v[120:121], s[88:89] op_sel_hi:[1,1,0]
	v_pk_mul_f32 v[126:127], v[126:127], v[168:169] op_sel_hi:[1,0]
	v_pk_mul_f32 v[120:121], v[174:175], v[120:121]
	v_pk_mul_f32 v[174:175], v[172:173], v[172:173]
	s_mov_b32 s86, 0xbf38aa3b
	v_pk_mul_f32 v[174:175], v[174:175], s[86:87] op_sel_hi:[1,0]
	v_and_b32_e32 v181, 0x7fffffff, v127
	v_and_b32_e32 v180, 0x7fffffff, v126
	v_exp_f32_e32 v174, v174
	v_exp_f32_e32 v175, v175
	v_pk_fma_f32 v[180:181], v[180:181], s[56:57], 1.0 op_sel_hi:[1,0,0]
	v_pk_mul_f32 v[184:185], v[122:123], v[168:169] op_sel_hi:[1,0]
	v_rcp_f32_e32 v180, v180
	v_rcp_f32_e32 v181, v181
	v_pk_mul_f32 v[122:123], v[126:127], v[126:127]
	v_pk_mul_f32 v[120:121], v[174:175], v[120:121]
	v_pk_mul_f32 v[122:123], v[122:123], s[86:87] op_sel_hi:[1,0]
	v_pk_mul_f32 v[174:175], v[172:173], v[120:121]
	v_pk_fma_f32 v[186:187], v[172:173], v[120:121], v[172:173] neg_lo:[1,0,0] neg_hi:[1,0,0]
	v_pk_fma_f32 v[120:121], v[180:181], s[2:3], v[124:125] op_sel_hi:[1,0,0]
	v_exp_f32_e32 v122, v122
	v_pk_fma_f32 v[120:121], v[180:181], v[120:121], s[4:5] op_sel_hi:[1,1,0]
	v_exp_f32_e32 v123, v123
	v_pk_fma_f32 v[120:121], v[180:181], v[120:121], s[12:13] op_sel_hi:[1,1,0]
	v_and_b32_e32 v189, 0x7fffffff, v183
	v_pk_fma_f32 v[120:121], v[180:181], v[120:121], s[88:89] op_sel_hi:[1,1,0]
	v_and_b32_e32 v188, 0x7fffffff, v182
	v_pk_mul_f32 v[120:121], v[180:181], v[120:121]
	v_cmp_gt_f32_e32 vcc, 0, v126
	v_pk_mul_f32 v[120:121], v[122:123], v[120:121]
	v_pk_fma_f32 v[188:189], v[188:189], s[56:57], 1.0 op_sel_hi:[1,0,0]
	v_pk_mul_f32 v[122:123], v[126:127], v[120:121]
	v_pk_fma_f32 v[180:181], v[126:127], v[120:121], v[126:127] neg_lo:[1,0,0] neg_hi:[1,0,0]
	v_rcp_f32_e32 v188, v188
	v_cndmask_b32_e32 v121, v180, v122, vcc
	v_cmp_gt_f32_e32 vcc, 0, v172
	v_rcp_f32_e32 v189, v189
	v_and_b32_e32 v180, 0x7fffffff, v184
	v_cndmask_b32_e32 v120, v186, v174, vcc
	v_cmp_gt_f32_e32 vcc, 0, v127
	v_pk_fma_f32 v[126:127], v[188:189], s[2:3], v[124:125] op_sel_hi:[1,0,0]
	v_pk_mul_f32 v[116:117], v[116:117], v[168:169] op_sel_hi:[1,0]
	v_cndmask_b32_e32 v123, v181, v123, vcc
	v_cmp_gt_f32_e32 vcc, 0, v173
	v_and_b32_e32 v181, 0x7fffffff, v185
	v_pk_fma_f32 v[126:127], v[188:189], v[126:127], s[4:5] op_sel_hi:[1,1,0]
	v_cndmask_b32_e32 v122, v187, v175, vcc
	v_pk_mul_f32 v[174:175], v[182:183], v[182:183]
	v_pk_fma_f32 v[180:181], v[180:181], s[56:57], 1.0 op_sel_hi:[1,0,0]
	v_pk_mul_f32 v[174:175], v[174:175], s[86:87] op_sel_hi:[1,0]
	v_pk_fma_f32 v[126:127], v[188:189], v[126:127], s[12:13] op_sel_hi:[1,1,0]
	v_exp_f32_e32 v174, v174
	v_exp_f32_e32 v175, v175
	v_rcp_f32_e32 v180, v180
	v_rcp_f32_e32 v181, v181
	v_pk_fma_f32 v[126:127], v[188:189], v[126:127], s[88:89] op_sel_hi:[1,1,0]
	v_pk_mul_f32 v[172:173], v[184:185], v[184:185]
	v_pk_mul_f32 v[126:127], v[188:189], v[126:127]
	v_pk_mul_f32 v[172:173], v[172:173], s[86:87] op_sel_hi:[1,0]
	v_pk_mul_f32 v[126:127], v[174:175], v[126:127]
	v_exp_f32_e32 v172, v172
	v_pk_mul_f32 v[174:175], v[182:183], v[126:127]
	v_pk_fma_f32 v[186:187], v[182:183], v[126:127], v[182:183] neg_lo:[1,0,0] neg_hi:[1,0,0]
	v_pk_fma_f32 v[126:127], v[180:181], s[2:3], v[124:125] op_sel_hi:[1,0,0]
	v_exp_f32_e32 v173, v173
	v_pk_fma_f32 v[126:127], v[180:181], v[126:127], s[4:5] op_sel_hi:[1,1,0]
	v_pk_mul_f32 v[210:211], v[112:113], v[168:169] op_sel_hi:[1,0]
	v_pk_fma_f32 v[126:127], v[180:181], v[126:127], s[12:13] op_sel_hi:[1,1,0]
	v_pk_mul_f32 v[118:119], v[118:119], v[168:169] op_sel_hi:[1,0]
	v_pk_fma_f32 v[126:127], v[180:181], v[126:127], s[88:89] op_sel_hi:[1,1,0]
	v_and_b32_e32 v213, 0x7fffffff, v119
	v_pk_mul_f32 v[126:127], v[180:181], v[126:127]
	v_and_b32_e32 v212, 0x7fffffff, v118
	v_pk_mul_f32 v[126:127], v[172:173], v[126:127]
	v_and_b32_e32 v173, 0x7fffffff, v117
	v_and_b32_e32 v172, 0x7fffffff, v116
	v_pk_fma_f32 v[172:173], v[172:173], s[56:57], 1.0 op_sel_hi:[1,0,0]
	v_pk_fma_f32 v[212:213], v[212:213], s[56:57], 1.0 op_sel_hi:[1,0,0]
	v_rcp_f32_e32 v172, v172
	v_rcp_f32_e32 v173, v173
	v_rcp_f32_e32 v212, v212
	v_rcp_f32_e32 v213, v213
	v_pk_mul_f32 v[208:209], v[114:115], v[168:169] op_sel_hi:[1,0]
	v_pk_fma_f32 v[112:113], v[172:173], s[2:3], v[124:125] op_sel_hi:[1,0,0]
	v_pk_mul_f32 v[114:115], v[118:119], v[118:119]
; __device__ __forceinline__ u32x4 pack8(const f32x4& a, const f32x4& b) { u32x4 w; w.x = cvt_pk_bf16(a[0], a[1]); w.y = cvt_pk_bf16(a[2], a[3]); w.z = cvt_pk_bf16(b[0], b[1]); w.w = cvt_pk_bf16(b[2], b[3]); return w; }
;     __device__ __forceinline__ void operator()(const f32x4 (&acc)[2][2][4][2], const Unit& u, int ui, int wr, int wc, int fr, int fq) const {
;     ...
;             for (int m = 0; m < 4; ++m) { const float r = rs[ai][m]; const int row = row0 + ai * HALF + m * 16; bf16_t* rowp = Z + (size_t)row * 2048 + col0; float s1 = 0.f, s2 = 0.f;
; #pragma unroll
;                 for (int bj = 0; bj < 2; ++bj) { const f32x4 v0 = acc[ai][bj][m][0] * r, v1 = acc[ai][bj][m][1] * r;
;                     const f32x2 a = gelu_pk((f32x2){v0[0], v0[1]}), b = gelu_pk((f32x2){v0[2], v0[3]}), c = gelu_pk((f32x2){v1[0], v1[1]}), d = gelu_pk((f32x2){v1[2], v1[3]});
;                     const f32x4 z0 = (f32x4){a.x, a.y, b.x, b.y}, z1 = (f32x4){c.x, c.y, d.x, d.y};
;                     *(u32x4*)(rowp + bj * HALF) = pack8(z0, z1);
;                     s1 += (z0[0] + z0[1]) + (z0[2] + z0[3]) + (z1[0] + z1[1]) + (z1[2] + z1[3]);
;                     s2 += (z0[0] * z0[0] + z0[1] * z0[1]) + (z0[2] * z0[2] + z0[3] * z0[3]) + (z1[0] * z1[0] + z1[1] * z1[1]) + (z1[2] * z1[2] + z1[3] * z1[3]); }
	v_pk_fma_f32 v[112:113], v[172:173], v[112:113], s[4:5] op_sel_hi:[1,1,0]
	v_pk_mul_f32 v[114:115], v[114:115], s[86:87] op_sel_hi:[1,0]
	v_pk_fma_f32 v[112:113], v[172:173], v[112:113], s[12:13] op_sel_hi:[1,1,0]
	v_exp_f32_e32 v114, v114
	v_pk_fma_f32 v[112:113], v[172:173], v[112:113], s[88:89] op_sel_hi:[1,1,0]
	v_exp_f32_e32 v115, v115
	v_pk_mul_f32 v[112:113], v[172:173], v[112:113]
	v_pk_mul_f32 v[172:173], v[116:117], v[116:117]
	v_and_b32_e32 v217, 0x7fffffff, v211
	v_pk_mul_f32 v[172:173], v[172:173], s[86:87] op_sel_hi:[1,0]
	v_and_b32_e32 v216, 0x7fffffff, v210
	v_exp_f32_e32 v172, v172
	v_exp_f32_e32 v173, v173
	v_pk_fma_f32 v[216:217], v[216:217], s[56:57], 1.0 op_sel_hi:[1,0,0]
	v_pk_mul_f32 v[188:189], v[184:185], v[126:127]
	v_pk_fma_f32 v[190:191], v[184:185], v[126:127], v[184:185] neg_lo:[1,0,0] neg_hi:[1,0,0]
	v_pk_mul_f32 v[112:113], v[172:173], v[112:113]
	v_cmp_gt_f32_e32 vcc, 0, v185
	v_pk_mul_f32 v[172:173], v[116:117], v[112:113]
	v_pk_fma_f32 v[214:215], v[116:117], v[112:113], v[116:117] neg_lo:[1,0,0] neg_hi:[1,0,0]
	v_pk_fma_f32 v[112:113], v[212:213], s[2:3], v[124:125] op_sel_hi:[1,0,0]
	v_rcp_f32_e32 v216, v216
	v_pk_fma_f32 v[112:113], v[212:213], v[112:113], s[4:5] op_sel_hi:[1,1,0]
	v_rcp_f32_e32 v217, v217
	v_pk_fma_f32 v[112:113], v[212:213], v[112:113], s[12:13] op_sel_hi:[1,1,0]
	v_cndmask_b32_e32 v126, v191, v189, vcc
	v_pk_fma_f32 v[112:113], v[212:213], v[112:113], s[88:89] op_sel_hi:[1,1,0]
	v_cmp_gt_f32_e32 vcc, 0, v118
	v_pk_mul_f32 v[112:113], v[212:213], v[112:113]
	s_ashr_i32 s39, s38, 31
	v_pk_mul_f32 v[112:113], v[114:115], v[112:113]
	s_cmp_lt_i32 s10, 4
	v_pk_mul_f32 v[114:115], v[118:119], v[112:113]
	v_pk_fma_f32 v[212:213], v[118:119], v[112:113], v[118:119] neg_lo:[1,0,0] neg_hi:[1,0,0]
	v_cmp_eq_u32_e64 s[10:11], 0, v141
	v_cndmask_b32_e32 v113, v212, v114, vcc
	v_cmp_gt_f32_e32 vcc, 0, v116
	v_ashrrev_i32_e32 v141, 31, v140
	v_lshlrev_b64 v[170:171], 12, v[140:141]
	v_cndmask_b32_e32 v112, v214, v172, vcc
	v_cmp_gt_f32_e32 vcc, 0, v119
	v_pk_mul_f32 v[118:119], v[210:211], v[210:211]
	v_ashrrev_i32_e32 v163, 31, v162
	v_cndmask_b32_e32 v115, v213, v115, vcc
	v_cmp_gt_f32_e32 vcc, 0, v117
	v_pk_fma_f32 v[116:117], v[216:217], s[2:3], v[124:125] op_sel_hi:[1,0,0]
	v_pk_mul_f32 v[118:119], v[118:119], s[86:87] op_sel_hi:[1,0]
	v_pk_fma_f32 v[116:117], v[216:217], v[116:117], s[4:5] op_sel_hi:[1,1,0]
	v_exp_f32_e32 v118, v118
	v_exp_f32_e32 v119, v119
	v_pk_fma_f32 v[116:117], v[216:217], v[116:117], s[12:13] op_sel_hi:[1,1,0]
	v_cndmask_b32_e32 v114, v215, v173, vcc
	v_pk_fma_f32 v[116:117], v[216:217], v[116:117], s[88:89] op_sel_hi:[1,1,0]
	v_cmp_gt_f32_e32 vcc, 0, v182
	v_pk_mul_f32 v[116:117], v[216:217], v[116:117]
	v_lshl_add_u64 v[170:171], s[20:21], 0, v[170:171]
	v_pk_mul_f32 v[116:117], v[118:119], v[116:117]
	v_cndmask_b32_e32 v118, v186, v174, vcc
	v_pk_mul_f32 v[172:173], v[210:211], v[116:117]
	v_pk_fma_f32 v[214:215], v[210:211], v[116:117], v[210:211] neg_lo:[1,0,0] neg_hi:[1,0,0]
	v_cmp_gt_f32_e32 vcc, 0, v210
	v_and_b32_e32 v174, 0x7fffffff, v208
	v_lshl_add_u64 v[170:171], v[162:163], 1, v[170:171]
	v_cndmask_b32_e32 v119, v214, v172, vcc
	v_cmp_gt_f32_e32 vcc, 0, v183
	v_cvt_pk_bf16_f32 v180, v120, v122
	v_cvt_pk_bf16_f32 v181, v121, v123
	v_pk_mul_f32 v[212:213], v[208:209], v[208:209]
	s_nop 0
	v_cndmask_b32_e32 v172, v187, v175, vcc
	v_and_b32_e32 v175, 0x7fffffff, v209
	v_pk_fma_f32 v[174:175], v[174:175], s[56:57], 1.0 op_sel_hi:[1,0,0]
	v_cmp_gt_f32_e32 vcc, 0, v184
	v_rcp_f32_e32 v184, v174
	v_rcp_f32_e32 v185, v175
	v_cvt_pk_bf16_f32 v182, v118, v172
	v_cndmask_b32_e32 v117, v190, v188, vcc
	v_cvt_pk_bf16_f32 v183, v117, v126
	global_store_dwordx4 v[170:171], v[180:183], off sc1 nt
	v_pk_fma_f32 v[124:125], v[184:185], s[2:3], v[124:125] op_sel_hi:[1,0,0]
	v_cmp_gt_f32_e32 vcc, 0, v211
	v_pk_mul_f32 v[180:181], v[212:213], s[86:87] op_sel_hi:[1,0]
	v_pk_fma_f32 v[124:125], v[184:185], v[124:125], s[4:5] op_sel_hi:[1,1,0]
	v_exp_f32_e32 v180, v180
	v_exp_f32_e32 v181, v181
	v_pk_fma_f32 v[124:125], v[184:185], v[124:125], s[12:13] op_sel_hi:[1,1,0]
	v_cndmask_b32_e32 v174, v215, v173, vcc
	v_pk_fma_f32 v[124:125], v[184:185], v[124:125], s[88:89] op_sel_hi:[1,1,0]
	v_cmp_gt_f32_e32 vcc, 0, v209
	v_pk_mul_f32 v[124:125], v[184:185], v[124:125]
	s_nop 0
	v_pk_mul_f32 v[124:125], v[180:181], v[124:125]
	s_nop 0
	v_pk_mul_f32 v[180:181], v[208:209], v[124:125]
	v_pk_fma_f32 v[124:125], v[208:209], v[124:125], v[208:209] neg_lo:[1,0,0] neg_hi:[1,0,0]
	s_nop 0
	v_cndmask_b32_e32 v125, v125, v181, vcc
	v_cmp_gt_f32_e32 vcc, 0, v208
	s_nop 1
	v_cndmask_b32_e32 v124, v124, v180, vcc
	v_cvt_pk_bf16_f32 v180, v112, v114
	v_cvt_pk_bf16_f32 v181, v113, v115
	v_cvt_pk_bf16_f32 v182, v119, v174
	v_cvt_pk_bf16_f32 v183, v124, v125
	global_store_dwordx4 v[170:171], v[180:183], off offset:256 sc1 nt
	s_cbranch_scc1 .LBB0_756
;     __device__ __forceinline__ void operator()(const f32x4 (&acc)[2][2][4][2], const Unit& u, int ui, int wr, int wc, int fr, int fq) const {
;     ...
;                     s1 += (z0[0] + z0[1]) + (z0[2] + z0[3]) + (z1[0] + z1[1]) + (z1[2] + z1[3]);
;                     s2 += (z0[0] * z0[0] + z0[1] * z0[1]) + (z0[2] * z0[2] + z0[3] * z0[3]) + (z1[0] * z1[0] + z1[1] * z1[1]) + (z1[2] * z1[2] + z1[3] * z1[3]); }
;                 if (u.pn >= 4) { s1 += __shfl_xor(s1, 16); s1 += __shfl_xor(s1, 32); s2 += __shfl_xor(s2, 16); s2 += __shfl_xor(s2, 32);
;                     if (fq == 0) vst[(size_t)row * 16 + (u.pn - 4) * 4 + wc] = (f32x2){s1, s2}; } }
	v_mov_b32_e32 v116, v119
	v_mov_b32_e32 v175, v117
	v_pk_add_f32 v[170:171], v[116:117], v[174:175]
	v_pk_mul_f32 v[180:181], v[116:117], v[174:175]
	v_mov_b32_e32 v182, v118
	v_mov_b32_e32 v183, v172
	v_mul_f32_e32 v116, v118, v118
	v_mov_b32_e32 v173, v119
	v_pk_fma_f32 v[182:183], v[182:183], v[182:183], v[116:117] op_sel_hi:[1,1,0]
	v_mul_f32_e32 v116, v124, v124
	v_pk_fma_f32 v[184:185], v[124:125], v[124:125], v[116:117] op_sel_hi:[1,1,0]
	v_mov_b32_e32 v186, v112
	v_mov_b32_e32 v187, v114
	v_mul_f32_e32 v116, v112, v112
	v_pk_add_f32 v[190:191], v[118:119], v[172:173]
	v_pk_mul_f32 v[118:119], v[118:119], v[172:173]
	v_mov_b32_e32 v171, v181
	v_pk_mul_f32 v[180:181], v[122:123], v[122:123]
	v_pk_fma_f32 v[186:187], v[186:187], v[186:187], v[116:117] op_sel_hi:[1,1,0]
	v_mov_b32_e32 v188, v113
	v_mov_b32_e32 v189, v115
	v_mul_f32_e32 v116, v113, v113
	v_mov_b32_e32 v191, v119
	v_pk_mul_f32 v[118:119], v[174:175], v[174:175]
	v_pk_add_f32 v[112:113], v[112:113], v[114:115]
	v_and_b32_e32 v115, 64, v192
	v_pk_fma_f32 v[180:181], v[120:121], v[120:121], v[180:181]
	v_pk_add_f32 v[120:121], v[120:121], v[122:123]
	v_xor_b32_e32 v114, 16, v192
	v_add_u32_e32 v119, 64, v115
	v_pk_fma_f32 v[188:189], v[188:189], v[188:189], v[116:117] op_sel_hi:[1,1,0]
	v_pk_add_f32 v[120:121], v[120:121], v[120:121] op_sel:[0,1] op_sel_hi:[1,0]
	v_cmp_lt_i32_e32 vcc, v114, v119
	v_mul_f32_e32 v168, v126, v126
	v_pk_add_f32 v[180:181], v[180:181], v[180:181] op_sel_hi:[0,1]
	v_cndmask_b32_e32 v114, v192, v114, vcc
	v_mov_b32_e32 v186, v117
	v_mov_b32_e32 v127, v189
	v_mov_b32_e32 v121, v118
	v_pk_add_f32 v[112:113], v[112:113], v[112:113] op_sel:[0,1] op_sel_hi:[1,0]
	v_lshlrev_b32_e32 v122, 2, v114
	v_pk_add_f32 v[114:115], v[186:187], v[126:127]
	v_pk_add_f32 v[116:117], v[190:191], v[120:121]
	v_mov_b32_e32 v182, v124
	v_mov_b32_e32 v180, v125
	v_mov_b32_e32 v113, v168
	v_pk_add_f32 v[114:115], v[116:117], v[114:115]
	v_mov_b32_e32 v147, v185
	v_pk_add_f32 v[116:117], v[182:183], v[180:181]
	v_pk_add_f32 v[112:113], v[170:171], v[112:113]
	v_pk_add_f32 v[114:115], v[114:115], v[146:147]
	v_pk_add_f32 v[112:113], v[112:113], v[116:117]
	v_xor_b32_e32 v116, 32, v192
	v_pk_add_f32 v[112:113], v[112:113], v[114:115]
	ds_bpermute_b32 v114, v122, v112
	ds_bpermute_b32 v115, v122, v113
	v_cmp_lt_i32_e32 vcc, v116, v119
	s_waitcnt lgkmcnt(0)
	v_pk_add_f32 v[112:113], v[112:113], v[114:115]
	v_cndmask_b32_e32 v116, v192, v116, vcc
	v_lshlrev_b32_e32 v116, 2, v116
	ds_bpermute_b32 v114, v116, v112
	ds_bpermute_b32 v115, v116, v113
	s_and_saveexec_b64 s[2:3], s[10:11]
	s_cbranch_execz .LBB0_755
	s_waitcnt lgkmcnt(0)
	v_pk_add_f32 v[112:113], v[112:113], v[114:115]
	v_lshlrev_b64 v[114:115], 7, v[140:141]
	v_lshl_add_u64 v[114:115], s[16:17], 0, v[114:115]
	v_lshl_add_u64 v[114:115], s[38:39], 3, v[114:115]
	s_lshl_b32 s88, s44, 3
	v_lshl_add_u64 v[114:115], v[114:115], 0, s[88:89]
	global_store_dwordx2 v[114:115], v[112:113], off

;     __device__ __forceinline__ void operator()(const f32x4 (&acc)[2][2][4][2], const Unit& u, int ui, int wr, int wc, int fr, int fq) const {
;     ...
;             for (int m = 0; m < 4; ++m) { const float r = rs[ai][m]; const int row = row0 + ai * HALF + m * 16; bf16_t* rowp = Z + (size_t)row * 2048 + col0; float s1 = 0.f, s2 = 0.f;
; #pragma unroll
;                 for (int bj = 0; bj < 2; ++bj) { const f32x4 v0 = acc[ai][bj][m][0] * r, v1 = acc[ai][bj][m][1] * r;
;                     const f32x2 a = gelu_pk((f32x2){v0[0], v0[1]}), b = gelu_pk((f32x2){v0[2], v0[3]}), c = gelu_pk((f32x2){v1[0], v1[1]}), d = gelu_pk((f32x2){v1[2], v1[3]});
.LBB0_756:
	v_mov_b32_e32 v116, v169
	v_pk_mul_f32 v[118:119], v[108:109], v[116:117] op_sel_hi:[1,0]
	s_mov_b32 s2, 0xbf3a00e3
	v_and_b32_e32 v109, 0x7fffffff, v119
	v_and_b32_e32 v108, 0x7fffffff, v118
	v_pk_fma_f32 v[108:109], v[108:109], s[56:57], 1.0 op_sel_hi:[1,0,0]
	v_pk_mul_f32 v[122:123], v[104:105], v[116:117] op_sel_hi:[1,0]
	v_rcp_f32_e32 v120, v108
	v_rcp_f32_e32 v121, v109
	v_mov_b64_e32 v[108:109], s[2:3]
	s_mov_b32 s2, 0x3f07dc22
	s_mov_b32 s88, 0x3e027906
	v_pk_fma_f32 v[104:105], v[120:121], s[2:3], v[108:109] op_sel_hi:[1,0,0]
	v_pk_mul_f32 v[110:111], v[110:111], v[116:117] op_sel_hi:[1,0]
	v_pk_fma_f32 v[104:105], v[120:121], v[104:105], s[4:5] op_sel_hi:[1,1,0]
	v_and_b32_e32 v127, 0x7fffffff, v111
	v_pk_fma_f32 v[104:105], v[120:121], v[104:105], s[12:13] op_sel_hi:[1,1,0]
	v_and_b32_e32 v126, 0x7fffffff, v110
	v_pk_fma_f32 v[104:105], v[120:121], v[104:105], s[88:89] op_sel_hi:[1,1,0]
	v_pk_fma_f32 v[126:127], v[126:127], s[56:57], 1.0 op_sel_hi:[1,0,0]
	v_pk_mul_f32 v[104:105], v[120:121], v[104:105]
	v_pk_mul_f32 v[120:121], v[118:119], v[118:119]
	v_rcp_f32_e32 v126, v126
	v_pk_mul_f32 v[120:121], v[120:121], s[86:87] op_sel_hi:[1,0]
	v_rcp_f32_e32 v127, v127
	v_exp_f32_e32 v120, v120
	v_exp_f32_e32 v121, v121
	v_pk_mul_f32 v[124:125], v[106:107], v[116:117] op_sel_hi:[1,0]
	v_pk_mul_f32 v[106:107], v[110:111], v[110:111]
	v_pk_mul_f32 v[100:101], v[100:101], v[116:117] op_sel_hi:[1,0]
	v_pk_mul_f32 v[104:105], v[120:121], v[104:105]
	v_pk_mul_f32 v[106:107], v[106:107], s[86:87] op_sel_hi:[1,0]
	v_pk_mul_f32 v[120:121], v[118:119], v[104:105]
	v_pk_fma_f32 v[168:169], v[118:119], v[104:105], v[118:119] neg_lo:[1,0,0] neg_hi:[1,0,0]
	v_pk_fma_f32 v[104:105], v[126:127], s[2:3], v[108:109] op_sel_hi:[1,0,0]
	v_exp_f32_e32 v106, v106
	v_pk_fma_f32 v[104:105], v[126:127], v[104:105], s[4:5] op_sel_hi:[1,1,0]
	v_exp_f32_e32 v107, v107
	v_and_b32_e32 v173, 0x7fffffff, v101
	v_and_b32_e32 v172, 0x7fffffff, v100
	v_pk_fma_f32 v[104:105], v[126:127], v[104:105], s[12:13] op_sel_hi:[1,1,0]
	v_pk_fma_f32 v[172:173], v[172:173], s[56:57], 1.0 op_sel_hi:[1,0,0]
	v_pk_fma_f32 v[104:105], v[126:127], v[104:105], s[88:89] op_sel_hi:[1,1,0]
	v_rcp_f32_e32 v172, v172
	v_rcp_f32_e32 v173, v173
	v_pk_mul_f32 v[104:105], v[126:127], v[104:105]
	v_and_b32_e32 v171, 0x7fffffff, v123
	v_pk_mul_f32 v[104:105], v[106:107], v[104:105]
	v_and_b32_e32 v170, 0x7fffffff, v122
	v_pk_mul_f32 v[106:107], v[110:111], v[104:105]
	v_pk_fma_f32 v[126:127], v[110:111], v[104:105], v[110:111] neg_lo:[1,0,0] neg_hi:[1,0,0]
	v_cmp_gt_f32_e32 vcc, 0, v110
	v_pk_fma_f32 v[170:171], v[170:171], s[56:57], 1.0 op_sel_hi:[1,0,0]
	v_pk_mul_f32 v[102:103], v[102:103], v[116:117] op_sel_hi:[1,0]
	v_cndmask_b32_e32 v105, v126, v106, vcc
	v_cmp_gt_f32_e32 vcc, 0, v118
	v_rcp_f32_e32 v170, v170
	v_rcp_f32_e32 v171, v171
	v_pk_mul_f32 v[174:175], v[98:99], v[116:117] op_sel_hi:[1,0]
	v_pk_mul_f32 v[116:117], v[96:97], v[116:117] op_sel_hi:[1,0]
	v_pk_fma_f32 v[96:97], v[172:173], s[2:3], v[108:109] op_sel_hi:[1,0,0]
	v_cndmask_b32_e32 v104, v168, v120, vcc
	v_cmp_gt_f32_e32 vcc, 0, v111
	v_pk_fma_f32 v[96:97], v[172:173], v[96:97], s[4:5] op_sel_hi:[1,1,0]
	v_pk_fma_f32 v[110:111], v[170:171], s[2:3], v[108:109] op_sel_hi:[1,0,0]
	v_cndmask_b32_e32 v107, v127, v107, vcc
	v_cmp_gt_f32_e32 vcc, 0, v119
	v_pk_fma_f32 v[96:97], v[172:173], v[96:97], s[12:13] op_sel_hi:[1,1,0]
	v_and_b32_e32 v127, 0x7fffffff, v125
	v_cndmask_b32_e32 v106, v169, v121, vcc
	v_pk_mul_f32 v[120:121], v[122:123], v[122:123]
	v_pk_fma_f32 v[96:97], v[172:173], v[96:97], s[88:89] op_sel_hi:[1,1,0]
	v_pk_mul_f32 v[120:121], v[120:121], s[86:87] op_sel_hi:[1,0]
	v_and_b32_e32 v126, 0x7fffffff, v124
	v_pk_mul_f32 v[96:97], v[172:173], v[96:97]
	v_pk_mul_f32 v[172:173], v[100:101], v[100:101]
	v_pk_fma_f32 v[110:111], v[170:171], v[110:111], s[4:5] op_sel_hi:[1,1,0]
	v_exp_f32_e32 v120, v120
	v_exp_f32_e32 v121, v121
	v_pk_fma_f32 v[126:127], v[126:127], s[56:57], 1.0 op_sel_hi:[1,0,0]
	v_pk_mul_f32 v[172:173], v[172:173], s[86:87] op_sel_hi:[1,0]
	v_and_b32_e32 v181, 0x7fffffff, v103
	v_and_b32_e32 v180, 0x7fffffff, v102
	v_pk_fma_f32 v[110:111], v[170:171], v[110:111], s[12:13] op_sel_hi:[1,1,0]
	v_rcp_f32_e32 v126, v126
	v_rcp_f32_e32 v127, v127
	v_exp_f32_e32 v172, v172
	v_exp_f32_e32 v173, v173
	v_pk_fma_f32 v[180:181], v[180:181], s[56:57], 1.0 op_sel_hi:[1,0,0]
	v_pk_fma_f32 v[110:111], v[170:171], v[110:111], s[88:89] op_sel_hi:[1,1,0]
	v_rcp_f32_e32 v180, v180
	v_rcp_f32_e32 v181, v181
	v_pk_mul_f32 v[110:111], v[170:171], v[110:111]
	v_pk_mul_f32 v[118:119], v[124:125], v[124:125]
	v_pk_mul_f32 v[110:111], v[120:121], v[110:111]
	v_pk_mul_f32 v[118:119], v[118:119], s[86:87] op_sel_hi:[1,0]
	v_pk_mul_f32 v[168:169], v[122:123], v[110:111]
	v_pk_fma_f32 v[170:171], v[122:123], v[110:111], v[122:123] neg_lo:[1,0,0] neg_hi:[1,0,0]
	v_pk_fma_f32 v[110:111], v[126:127], s[2:3], v[108:109] op_sel_hi:[1,0,0]
	v_pk_mul_f32 v[98:99], v[102:103], v[102:103]
	v_pk_mul_f32 v[96:97], v[172:173], v[96:97]
	v_pk_fma_f32 v[110:111], v[126:127], v[110:111], s[4:5] op_sel_hi:[1,1,0]
	v_exp_f32_e32 v118, v118
	v_exp_f32_e32 v119, v119
	v_pk_mul_f32 v[172:173], v[100:101], v[96:97]
	v_pk_fma_f32 v[182:183], v[100:101], v[96:97], v[100:101] neg_lo:[1,0,0] neg_hi:[1,0,0]
	v_pk_fma_f32 v[96:97], v[180:181], s[2:3], v[108:109] op_sel_hi:[1,0,0]
	v_pk_mul_f32 v[98:99], v[98:99], s[86:87] op_sel_hi:[1,0]
	v_pk_fma_f32 v[110:111], v[126:127], v[110:111], s[12:13] op_sel_hi:[1,1,0]
	v_pk_fma_f32 v[96:97], v[180:181], v[96:97], s[4:5] op_sel_hi:[1,1,0]
	v_exp_f32_e32 v98, v98
	v_exp_f32_e32 v99, v99
	v_pk_fma_f32 v[110:111], v[126:127], v[110:111], s[88:89] op_sel_hi:[1,1,0]
	v_pk_fma_f32 v[96:97], v[180:181], v[96:97], s[12:13] op_sel_hi:[1,1,0]
	v_pk_mul_f32 v[110:111], v[126:127], v[110:111]
	v_pk_fma_f32 v[96:97], v[180:181], v[96:97], s[88:89] op_sel_hi:[1,1,0]
	v_and_b32_e32 v185, 0x7fffffff, v117
	v_and_b32_e32 v184, 0x7fffffff, v116
	v_pk_mul_f32 v[110:111], v[118:119], v[110:111]
	v_pk_mul_f32 v[96:97], v[180:181], v[96:97]
	v_pk_fma_f32 v[184:185], v[184:185], s[56:57], 1.0 op_sel_hi:[1,0,0]
	v_pk_mul_f32 v[118:119], v[124:125], v[110:111]
	v_pk_fma_f32 v[126:127], v[124:125], v[110:111], v[124:125] neg_lo:[1,0,0] neg_hi:[1,0,0]
	v_cmp_gt_f32_e32 vcc, 0, v125
	v_pk_mul_f32 v[96:97], v[98:99], v[96:97]
	v_rcp_f32_e32 v184, v184
	v_rcp_f32_e32 v185, v185
	v_cndmask_b32_e32 v110, v127, v119, vcc
	v_pk_mul_f32 v[98:99], v[102:103], v[96:97]
	v_pk_fma_f32 v[180:181], v[102:103], v[96:97], v[102:103] neg_lo:[1,0,0] neg_hi:[1,0,0]
	v_cmp_gt_f32_e32 vcc, 0, v102
	v_and_b32_e32 v119, 0x7fffffff, v175
	v_add_u32_e32 v112, 16, v140
	v_cndmask_b32_e32 v97, v180, v98, vcc
	v_cmp_gt_f32_e32 vcc, 0, v100
	v_ashrrev_i32_e32 v113, 31, v112
	s_waitcnt lgkmcnt(0)
; __device__ __forceinline__ u32x4 pack8(const f32x4& a, const f32x4& b) { u32x4 w; w.x = cvt_pk_bf16(a[0], a[1]); w.y = cvt_pk_bf16(a[2], a[3]); w.z = cvt_pk_bf16(b[0], b[1]); w.w = cvt_pk_bf16(b[2], b[3]); return w; }
;     __device__ __forceinline__ void operator()(const f32x4 (&acc)[2][2][4][2], const Unit& u, int ui, int wr, int wc, int fr, int fq) const {
;     ...
;             for (int m = 0; m < 4; ++m) { const float r = rs[ai][m]; const int row = row0 + ai * HALF + m * 16; bf16_t* rowp = Z + (size_t)row * 2048 + col0; float s1 = 0.f, s2 = 0.f;
; #pragma unroll
;                 for (int bj = 0; bj < 2; ++bj) { const f32x4 v0 = acc[ai][bj][m][0] * r, v1 = acc[ai][bj][m][1] * r;
;                     const f32x2 a = gelu_pk((f32x2){v0[0], v0[1]}), b = gelu_pk((f32x2){v0[2], v0[3]}), c = gelu_pk((f32x2){v1[0], v1[1]}), d = gelu_pk((f32x2){v1[2], v1[3]});
;                     const f32x4 z0 = (f32x4){a.x, a.y, b.x, b.y}, z1 = (f32x4){c.x, c.y, d.x, d.y};
;                     *(u32x4*)(rowp + bj * HALF) = pack8(z0, z1);
;                     s1 += (z0[0] + z0[1]) + (z0[2] + z0[3]) + (z1[0] + z1[1]) + (z1[2] + z1[3]);
;                     s2 += (z0[0] * z0[0] + z0[1] * z0[1]) + (z0[2] * z0[2] + z0[3] * z0[3]) + (z1[0] * z1[0] + z1[1] * z1[1]) + (z1[2] * z1[2] + z1[3] * z1[3]); }
;                 if (u.pn >= 4) { s1 += __shfl_xor(s1, 16); s1 += __shfl_xor(s1, 32); s2 += __shfl_xor(s2, 16); s2 += __shfl_xor(s2, 32);
;                     if (fq == 0) vst[(size_t)row * 16 + (u.pn - 4) * 4 + wc] = (f32x2){s1, s2}; } }
	v_lshlrev_b64 v[114:115], 12, v[112:113]
	v_cndmask_b32_e32 v96, v182, v172, vcc
	v_cmp_gt_f32_e32 vcc, 0, v103
	v_pk_mul_f32 v[102:103], v[116:117], v[116:117]
	v_lshl_add_u64 v[114:115], s[20:21], 0, v[114:115]
	v_cndmask_b32_e32 v99, v181, v99, vcc
	v_cmp_gt_f32_e32 vcc, 0, v101
	v_pk_fma_f32 v[100:101], v[184:185], s[2:3], v[108:109] op_sel_hi:[1,0,0]
	v_pk_mul_f32 v[102:103], v[102:103], s[86:87] op_sel_hi:[1,0]
	v_pk_fma_f32 v[100:101], v[184:185], v[100:101], s[4:5] op_sel_hi:[1,1,0]
	v_exp_f32_e32 v102, v102
	v_exp_f32_e32 v103, v103
	v_pk_fma_f32 v[100:101], v[184:185], v[100:101], s[12:13] op_sel_hi:[1,1,0]
	v_cndmask_b32_e32 v98, v183, v173, vcc
	v_pk_fma_f32 v[100:101], v[184:185], v[100:101], s[88:89] op_sel_hi:[1,1,0]
	v_cmp_gt_f32_e32 vcc, 0, v122
	v_pk_mul_f32 v[100:101], v[184:185], v[100:101]
	v_lshl_add_u64 v[114:115], v[162:163], 1, v[114:115]
	v_pk_mul_f32 v[100:101], v[102:103], v[100:101]
	v_cndmask_b32_e32 v102, v170, v168, vcc
	v_pk_mul_f32 v[180:181], v[116:117], v[100:101]
	v_pk_fma_f32 v[182:183], v[116:117], v[100:101], v[116:117] neg_lo:[1,0,0] neg_hi:[1,0,0]
	v_cmp_gt_f32_e32 vcc, 0, v116
	v_cvt_pk_bf16_f32 v120, v104, v106
	v_cvt_pk_bf16_f32 v121, v105, v107
	v_pk_mul_f32 v[172:173], v[174:175], v[174:175]
	v_cndmask_b32_e64 v100, 0, 1, s[0:1]
	v_cndmask_b32_e32 v103, v182, v180, vcc
	v_cmp_gt_f32_e32 vcc, 0, v123
	s_nop 1
	v_cndmask_b32_e32 v116, v171, v169, vcc
	v_cmp_gt_f32_e32 vcc, 0, v124
	v_cvt_pk_bf16_f32 v122, v102, v116
	s_nop 1
	v_cndmask_b32_e32 v101, v126, v118, vcc
	v_and_b32_e32 v118, 0x7fffffff, v174
	v_pk_fma_f32 v[118:119], v[118:119], s[56:57], 1.0 op_sel_hi:[1,0,0]
	v_cvt_pk_bf16_f32 v123, v101, v110
	global_store_dwordx4 v[114:115], v[120:123], off sc1 nt
	v_rcp_f32_e32 v124, v118
	v_rcp_f32_e32 v125, v119
	v_pk_mul_f32 v[120:121], v[172:173], s[86:87] op_sel_hi:[1,0]
	v_cmp_gt_f32_e32 vcc, 0, v117
	v_exp_f32_e32 v120, v120
	v_pk_fma_f32 v[108:109], v[124:125], s[2:3], v[108:109] op_sel_hi:[1,0,0]
	v_exp_f32_e32 v121, v121
	v_pk_fma_f32 v[108:109], v[124:125], v[108:109], s[4:5] op_sel_hi:[1,1,0]
	v_cndmask_b32_e32 v118, v183, v181, vcc
	v_pk_fma_f32 v[108:109], v[124:125], v[108:109], s[12:13] op_sel_hi:[1,1,0]
	v_cmp_gt_f32_e32 vcc, 0, v175
	v_pk_fma_f32 v[108:109], v[124:125], v[108:109], s[88:89] op_sel_hi:[1,1,0]
	v_cmp_ne_u32_e64 s[12:13], 1, v100
	v_pk_mul_f32 v[108:109], v[124:125], v[108:109]
	s_nop 0
	v_pk_mul_f32 v[108:109], v[120:121], v[108:109]
	s_nop 0
	v_pk_mul_f32 v[120:121], v[174:175], v[108:109]
	v_pk_fma_f32 v[108:109], v[174:175], v[108:109], v[174:175] neg_lo:[1,0,0] neg_hi:[1,0,0]
	s_nop 0
	v_cndmask_b32_e32 v109, v109, v121, vcc
	v_cmp_gt_f32_e32 vcc, 0, v174
	s_nop 1
	v_cndmask_b32_e32 v108, v108, v120, vcc
	s_andn2_b64 vcc, exec, s[0:1]
	v_cvt_pk_bf16_f32 v120, v96, v98
	v_cvt_pk_bf16_f32 v121, v97, v99
	v_cvt_pk_bf16_f32 v122, v103, v118
	v_cvt_pk_bf16_f32 v123, v108, v109
	global_store_dwordx4 v[114:115], v[120:123], off offset:256 sc1 nt
	s_cbranch_vccnz .LBB0_760
	v_mov_b32_e32 v100, v103
	v_mov_b32_e32 v119, v101
	v_pk_add_f32 v[114:115], v[100:101], v[118:119]
	v_pk_mul_f32 v[120:121], v[100:101], v[118:119]
	v_mov_b32_e32 v122, v102
	v_mov_b32_e32 v123, v116
	v_mul_f32_e32 v100, v102, v102
	v_mov_b32_e32 v117, v103
	v_pk_fma_f32 v[122:123], v[122:123], v[122:123], v[100:101] op_sel_hi:[1,1,0]
	v_mul_f32_e32 v100, v108, v108
	v_pk_fma_f32 v[124:125], v[108:109], v[108:109], v[100:101] op_sel_hi:[1,1,0]
	v_mov_b32_e32 v126, v96
	v_mov_b32_e32 v127, v98
	v_mul_f32_e32 v100, v96, v96
	v_pk_add_f32 v[170:171], v[102:103], v[116:117]
	v_pk_mul_f32 v[102:103], v[102:103], v[116:117]
	v_mov_b32_e32 v115, v121
	v_pk_mul_f32 v[120:121], v[106:107], v[106:107]
	v_pk_fma_f32 v[126:127], v[126:127], v[126:127], v[100:101] op_sel_hi:[1,1,0]
	v_mov_b32_e32 v168, v97
	v_mov_b32_e32 v169, v99
	v_mul_f32_e32 v100, v97, v97
	v_mov_b32_e32 v171, v103
	v_pk_mul_f32 v[102:103], v[118:119], v[118:119]
	v_pk_add_f32 v[96:97], v[96:97], v[98:99]
	v_and_b32_e32 v99, 64, v192
	v_pk_fma_f32 v[120:121], v[104:105], v[104:105], v[120:121]
	v_pk_add_f32 v[104:105], v[104:105], v[106:107]
	v_xor_b32_e32 v98, 16, v192
	v_add_u32_e32 v103, 64, v99
	v_pk_fma_f32 v[168:169], v[168:169], v[168:169], v[100:101] op_sel_hi:[1,1,0]
	v_pk_add_f32 v[104:105], v[104:105], v[104:105] op_sel:[0,1] op_sel_hi:[1,0]
	v_cmp_lt_i32_e32 vcc, v98, v103
	v_mul_f32_e32 v141, v110, v110
	v_pk_add_f32 v[120:121], v[120:121], v[120:121] op_sel_hi:[0,1]
	v_cndmask_b32_e32 v98, v192, v98, vcc
	v_mov_b32_e32 v126, v101
	v_mov_b32_e32 v111, v169
	v_mov_b32_e32 v105, v102
	v_pk_add_f32 v[96:97], v[96:97], v[96:97] op_sel:[0,1] op_sel_hi:[1,0]
	v_lshlrev_b32_e32 v106, 2, v98
	v_pk_add_f32 v[98:99], v[126:127], v[110:111]
	v_pk_add_f32 v[100:101], v[170:171], v[104:105]
	v_mov_b32_e32 v122, v108
	v_mov_b32_e32 v120, v109
	v_mov_b32_e32 v97, v141
	v_pk_add_f32 v[98:99], v[100:101], v[98:99]
	v_mov_b32_e32 v147, v125
	v_pk_add_f32 v[100:101], v[122:123], v[120:121]
	v_pk_add_f32 v[96:97], v[114:115], v[96:97]
	v_pk_add_f32 v[98:99], v[98:99], v[146:147]
	v_pk_add_f32 v[96:97], v[96:97], v[100:101]
	v_xor_b32_e32 v100, 32, v192
	v_pk_add_f32 v[96:97], v[96:97], v[98:99]
	ds_bpermute_b32 v98, v106, v96
	ds_bpermute_b32 v99, v106, v97
	v_cmp_lt_i32_e32 vcc, v100, v103
	s_waitcnt lgkmcnt(0)
	v_pk_add_f32 v[96:97], v[96:97], v[98:99]
	v_cndmask_b32_e32 v100, v192, v100, vcc
	v_lshlrev_b32_e32 v100, 2, v100
	ds_bpermute_b32 v98, v100, v96
	ds_bpermute_b32 v99, v100, v97
	s_and_saveexec_b64 s[0:1], s[10:11]
	s_cbranch_execz .LBB0_759
	s_waitcnt lgkmcnt(0)
	v_pk_add_f32 v[96:97], v[96:97], v[98:99]
	v_lshlrev_b64 v[98:99], 7, v[112:113]
	v_lshl_add_u64 v[98:99], s[16:17], 0, v[98:99]
	v_lshl_add_u64 v[98:99], s[38:39], 3, v[98:99]
	s_lshl_b32 s88, s44, 3
	v_lshl_add_u64 v[98:99], v[98:99], 0, s[88:89]
	global_store_dwordx2 v[98:99], v[96:97], off

;     __device__ __forceinline__ void operator()(const f32x4 (&acc)[2][2][4][2], const Unit& u, int ui, int wr, int wc, int fr, int fq) const {
;     ...
;             for (int m = 0; m < 4; ++m) { const float r = rs[ai][m]; const int row = row0 + ai * HALF + m * 16; bf16_t* rowp = Z + (size_t)row * 2048 + col0; float s1 = 0.f, s2 = 0.f;
; #pragma unroll
;                 for (int bj = 0; bj < 2; ++bj) { const f32x4 v0 = acc[ai][bj][m][0] * r, v1 = acc[ai][bj][m][1] * r;
;                     const f32x2 a = gelu_pk((f32x2){v0[0], v0[1]}), b = gelu_pk((f32x2){v0[2], v0[3]}), c = gelu_pk((f32x2){v1[0], v1[1]}), d = gelu_pk((f32x2){v1[2], v1[3]});
.LBB0_760:
	v_pk_mul_f32 v[100:101], v[92:93], v[166:167] op_sel_hi:[1,0]
	s_mov_b32 s0, 0xbf3a00e3
	v_and_b32_e32 v93, 0x7fffffff, v101
	v_and_b32_e32 v92, 0x7fffffff, v100
	v_pk_fma_f32 v[92:93], v[92:93], s[56:57], 1.0 op_sel_hi:[1,0,0]
	v_pk_mul_f32 v[106:107], v[88:89], v[166:167] op_sel_hi:[1,0]
	v_rcp_f32_e32 v102, v92
	v_rcp_f32_e32 v103, v93
	v_mov_b64_e32 v[92:93], s[0:1]
	s_mov_b32 s0, 0x3f07dc22
	s_mov_b32 s2, 0x3f35f0e3
	v_pk_fma_f32 v[88:89], v[102:103], s[0:1], v[92:93] op_sel_hi:[1,0,0]
	s_mov_b32 s4, 0xbe11a98e
	v_pk_fma_f32 v[88:89], v[102:103], v[88:89], s[2:3] op_sel_hi:[1,1,0]
	s_mov_b32 s88, 0x3e027906
	v_pk_fma_f32 v[88:89], v[102:103], v[88:89], s[4:5] op_sel_hi:[1,1,0]
	v_pk_mul_f32 v[94:95], v[94:95], v[166:167] op_sel_hi:[1,0]
	v_pk_fma_f32 v[88:89], v[102:103], v[88:89], s[88:89] op_sel_hi:[1,1,0]
	v_and_b32_e32 v105, 0x7fffffff, v95
	v_pk_mul_f32 v[88:89], v[102:103], v[88:89]
	v_pk_mul_f32 v[102:103], v[100:101], v[100:101]
	v_and_b32_e32 v104, 0x7fffffff, v94
	v_pk_mul_f32 v[102:103], v[102:103], s[86:87] op_sel_hi:[1,0]
	v_pk_fma_f32 v[104:105], v[104:105], s[56:57], 1.0 op_sel_hi:[1,0,0]
	v_exp_f32_e32 v102, v102
	v_exp_f32_e32 v103, v103
	v_rcp_f32_e32 v104, v104
	v_rcp_f32_e32 v105, v105
	v_pk_mul_f32 v[108:109], v[90:91], v[166:167] op_sel_hi:[1,0]
	v_pk_mul_f32 v[90:91], v[94:95], v[94:95]
	v_pk_mul_f32 v[88:89], v[102:103], v[88:89]
	v_pk_mul_f32 v[90:91], v[90:91], s[86:87] op_sel_hi:[1,0]
	v_pk_mul_f32 v[102:103], v[100:101], v[88:89]
	v_pk_fma_f32 v[110:111], v[100:101], v[88:89], v[100:101] neg_lo:[1,0,0] neg_hi:[1,0,0]
	v_pk_fma_f32 v[88:89], v[104:105], s[0:1], v[92:93] op_sel_hi:[1,0,0]
	v_exp_f32_e32 v90, v90
	v_pk_fma_f32 v[88:89], v[104:105], v[88:89], s[2:3] op_sel_hi:[1,1,0]
	v_exp_f32_e32 v91, v91
	v_pk_fma_f32 v[88:89], v[104:105], v[88:89], s[4:5] op_sel_hi:[1,1,0]
	v_and_b32_e32 v113, 0x7fffffff, v107
	v_pk_fma_f32 v[88:89], v[104:105], v[88:89], s[88:89] op_sel_hi:[1,1,0]
	v_and_b32_e32 v112, 0x7fffffff, v106
	v_pk_mul_f32 v[88:89], v[104:105], v[88:89]
	v_cmp_gt_f32_e32 vcc, 0, v94
	v_pk_mul_f32 v[88:89], v[90:91], v[88:89]
	v_pk_fma_f32 v[112:113], v[112:113], s[56:57], 1.0 op_sel_hi:[1,0,0]
	v_pk_mul_f32 v[90:91], v[94:95], v[88:89]
	v_pk_fma_f32 v[104:105], v[94:95], v[88:89], v[94:95] neg_lo:[1,0,0] neg_hi:[1,0,0]
	v_rcp_f32_e32 v112, v112
	v_cndmask_b32_e32 v89, v104, v90, vcc
	v_cmp_gt_f32_e32 vcc, 0, v100
	v_rcp_f32_e32 v113, v113
	v_and_b32_e32 v104, 0x7fffffff, v108
	v_cndmask_b32_e32 v88, v110, v102, vcc
	v_cmp_gt_f32_e32 vcc, 0, v95
	v_pk_fma_f32 v[94:95], v[112:113], s[0:1], v[92:93] op_sel_hi:[1,0,0]
	v_pk_mul_f32 v[84:85], v[84:85], v[166:167] op_sel_hi:[1,0]
	v_cndmask_b32_e32 v91, v105, v91, vcc
	v_cmp_gt_f32_e32 vcc, 0, v101
	v_and_b32_e32 v105, 0x7fffffff, v109
	v_pk_fma_f32 v[94:95], v[112:113], v[94:95], s[2:3] op_sel_hi:[1,1,0]
	v_cndmask_b32_e32 v90, v111, v103, vcc
	v_pk_mul_f32 v[102:103], v[106:107], v[106:107]
	v_pk_fma_f32 v[104:105], v[104:105], s[56:57], 1.0 op_sel_hi:[1,0,0]
	v_pk_mul_f32 v[102:103], v[102:103], s[86:87] op_sel_hi:[1,0]
	v_pk_fma_f32 v[94:95], v[112:113], v[94:95], s[4:5] op_sel_hi:[1,1,0]
	v_exp_f32_e32 v102, v102
	v_exp_f32_e32 v103, v103
	v_rcp_f32_e32 v104, v104
	v_rcp_f32_e32 v105, v105
	v_pk_fma_f32 v[94:95], v[112:113], v[94:95], s[88:89] op_sel_hi:[1,1,0]
	v_pk_mul_f32 v[100:101], v[108:109], v[108:109]
	v_pk_mul_f32 v[94:95], v[112:113], v[94:95]
	v_pk_mul_f32 v[100:101], v[100:101], s[86:87] op_sel_hi:[1,0]
	v_pk_mul_f32 v[94:95], v[102:103], v[94:95]
	v_exp_f32_e32 v100, v100
	v_pk_mul_f32 v[102:103], v[106:107], v[94:95]
	v_pk_fma_f32 v[110:111], v[106:107], v[94:95], v[106:107] neg_lo:[1,0,0] neg_hi:[1,0,0]
	v_pk_fma_f32 v[94:95], v[104:105], s[0:1], v[92:93] op_sel_hi:[1,0,0]
	v_exp_f32_e32 v101, v101
	v_pk_fma_f32 v[94:95], v[104:105], v[94:95], s[2:3] op_sel_hi:[1,1,0]
	v_pk_mul_f32 v[118:119], v[80:81], v[166:167] op_sel_hi:[1,0]
	v_pk_fma_f32 v[94:95], v[104:105], v[94:95], s[4:5] op_sel_hi:[1,1,0]
	v_pk_mul_f32 v[86:87], v[86:87], v[166:167] op_sel_hi:[1,0]
	v_pk_fma_f32 v[94:95], v[104:105], v[94:95], s[88:89] op_sel_hi:[1,1,0]
	v_and_b32_e32 v121, 0x7fffffff, v87
	v_pk_mul_f32 v[94:95], v[104:105], v[94:95]
	v_and_b32_e32 v120, 0x7fffffff, v86
	v_pk_mul_f32 v[94:95], v[100:101], v[94:95]
	v_and_b32_e32 v101, 0x7fffffff, v85
	v_and_b32_e32 v100, 0x7fffffff, v84
	v_pk_fma_f32 v[100:101], v[100:101], s[56:57], 1.0 op_sel_hi:[1,0,0]
	v_pk_fma_f32 v[120:121], v[120:121], s[56:57], 1.0 op_sel_hi:[1,0,0]
	v_rcp_f32_e32 v100, v100
	v_rcp_f32_e32 v101, v101
	v_rcp_f32_e32 v120, v120
	v_rcp_f32_e32 v121, v121
	v_pk_mul_f32 v[116:117], v[82:83], v[166:167] op_sel_hi:[1,0]
	v_pk_fma_f32 v[80:81], v[100:101], s[0:1], v[92:93] op_sel_hi:[1,0,0]
	v_pk_mul_f32 v[82:83], v[86:87], v[86:87]
	v_pk_fma_f32 v[80:81], v[100:101], v[80:81], s[2:3] op_sel_hi:[1,1,0]
	v_pk_mul_f32 v[82:83], v[82:83], s[86:87] op_sel_hi:[1,0]
	v_pk_fma_f32 v[80:81], v[100:101], v[80:81], s[4:5] op_sel_hi:[1,1,0]
	v_exp_f32_e32 v82, v82
	v_pk_fma_f32 v[80:81], v[100:101], v[80:81], s[88:89] op_sel_hi:[1,1,0]
	v_exp_f32_e32 v83, v83
	v_pk_mul_f32 v[80:81], v[100:101], v[80:81]
	v_pk_mul_f32 v[100:101], v[84:85], v[84:85]
	v_and_b32_e32 v125, 0x7fffffff, v119
	v_pk_mul_f32 v[100:101], v[100:101], s[86:87] op_sel_hi:[1,0]
	v_and_b32_e32 v124, 0x7fffffff, v118
	v_exp_f32_e32 v100, v100
	v_exp_f32_e32 v101, v101
	v_pk_fma_f32 v[124:125], v[124:125], s[56:57], 1.0 op_sel_hi:[1,0,0]
	v_pk_mul_f32 v[112:113], v[108:109], v[94:95]
	v_pk_fma_f32 v[114:115], v[108:109], v[94:95], v[108:109] neg_lo:[1,0,0] neg_hi:[1,0,0]
	v_pk_mul_f32 v[80:81], v[100:101], v[80:81]
	v_cmp_gt_f32_e32 vcc, 0, v109
	v_pk_mul_f32 v[100:101], v[84:85], v[80:81]
	v_pk_fma_f32 v[122:123], v[84:85], v[80:81], v[84:85] neg_lo:[1,0,0] neg_hi:[1,0,0]
	v_pk_fma_f32 v[80:81], v[120:121], s[0:1], v[92:93] op_sel_hi:[1,0,0]
	v_rcp_f32_e32 v124, v124
	v_pk_fma_f32 v[80:81], v[120:121], v[80:81], s[2:3] op_sel_hi:[1,1,0]
	v_rcp_f32_e32 v125, v125
	v_pk_fma_f32 v[80:81], v[120:121], v[80:81], s[4:5] op_sel_hi:[1,1,0]
	v_cndmask_b32_e32 v94, v115, v113, vcc
	v_pk_fma_f32 v[80:81], v[120:121], v[80:81], s[88:89] op_sel_hi:[1,1,0]
	v_cmp_gt_f32_e32 vcc, 0, v86
	v_pk_mul_f32 v[80:81], v[120:121], v[80:81]
	v_add_u32_e32 v96, 32, v140
	v_pk_mul_f32 v[80:81], v[82:83], v[80:81]
	v_ashrrev_i32_e32 v97, 31, v96
	v_pk_mul_f32 v[82:83], v[86:87], v[80:81]
	v_pk_fma_f32 v[120:121], v[86:87], v[80:81], v[86:87] neg_lo:[1,0,0] neg_hi:[1,0,0]
	s_waitcnt lgkmcnt(0)
; __device__ __forceinline__ u32x4 pack8(const f32x4& a, const f32x4& b) { u32x4 w; w.x = cvt_pk_bf16(a[0], a[1]); w.y = cvt_pk_bf16(a[2], a[3]); w.z = cvt_pk_bf16(b[0], b[1]); w.w = cvt_pk_bf16(b[2], b[3]); return w; }
;     __device__ __forceinline__ void operator()(const f32x4 (&acc)[2][2][4][2], const Unit& u, int ui, int wr, int wc, int fr, int fq) const {
;     ...
;             for (int m = 0; m < 4; ++m) { const float r = rs[ai][m]; const int row = row0 + ai * HALF + m * 16; bf16_t* rowp = Z + (size_t)row * 2048 + col0; float s1 = 0.f, s2 = 0.f;
; #pragma unroll
;                 for (int bj = 0; bj < 2; ++bj) { const f32x4 v0 = acc[ai][bj][m][0] * r, v1 = acc[ai][bj][m][1] * r;
;                     const f32x2 a = gelu_pk((f32x2){v0[0], v0[1]}), b = gelu_pk((f32x2){v0[2], v0[3]}), c = gelu_pk((f32x2){v1[0], v1[1]}), d = gelu_pk((f32x2){v1[2], v1[3]});
;                     const f32x4 z0 = (f32x4){a.x, a.y, b.x, b.y}, z1 = (f32x4){c.x, c.y, d.x, d.y};
;                     *(u32x4*)(rowp + bj * HALF) = pack8(z0, z1);
;                     s1 += (z0[0] + z0[1]) + (z0[2] + z0[3]) + (z1[0] + z1[1]) + (z1[2] + z1[3]);
;                     s2 += (z0[0] * z0[0] + z0[1] * z0[1]) + (z0[2] * z0[2] + z0[3] * z0[3]) + (z1[0] * z1[0] + z1[1] * z1[1]) + (z1[2] * z1[2] + z1[3] * z1[3]); }
;                 if (u.pn >= 4) { s1 += __shfl_xor(s1, 16); s1 += __shfl_xor(s1, 32); s2 += __shfl_xor(s2, 16); s2 += __shfl_xor(s2, 32);
;                     if (fq == 0) vst[(size_t)row * 16 + (u.pn - 4) * 4 + wc] = (f32x2){s1, s2}; } }
	v_lshlrev_b64 v[98:99], 12, v[96:97]
	v_cndmask_b32_e32 v81, v120, v82, vcc
	v_cmp_gt_f32_e32 vcc, 0, v84
	v_lshl_add_u64 v[98:99], s[20:21], 0, v[98:99]
	v_lshl_add_u64 v[98:99], v[162:163], 1, v[98:99]
	v_cndmask_b32_e32 v80, v122, v100, vcc
	v_cmp_gt_f32_e32 vcc, 0, v87
	v_pk_mul_f32 v[86:87], v[118:119], v[118:119]
	v_cvt_pk_bf16_f32 v104, v88, v90
	v_cvt_pk_bf16_f32 v105, v89, v91
	s_nop 0
	v_cndmask_b32_e32 v83, v121, v83, vcc
	v_cmp_gt_f32_e32 vcc, 0, v85
	v_pk_fma_f32 v[84:85], v[124:125], s[0:1], v[92:93] op_sel_hi:[1,0,0]
	v_pk_mul_f32 v[86:87], v[86:87], s[86:87] op_sel_hi:[1,0]
	v_pk_fma_f32 v[84:85], v[124:125], v[84:85], s[2:3] op_sel_hi:[1,1,0]
	v_exp_f32_e32 v86, v86
	v_exp_f32_e32 v87, v87
	v_pk_fma_f32 v[84:85], v[124:125], v[84:85], s[4:5] op_sel_hi:[1,1,0]
	v_cndmask_b32_e32 v82, v123, v101, vcc
	v_pk_fma_f32 v[84:85], v[124:125], v[84:85], s[88:89] op_sel_hi:[1,1,0]
	v_cmp_gt_f32_e32 vcc, 0, v106
	v_pk_mul_f32 v[84:85], v[124:125], v[84:85]
	v_pk_mul_f32 v[120:121], v[116:117], v[116:117]
	v_pk_mul_f32 v[84:85], v[86:87], v[84:85]
	v_cndmask_b32_e32 v86, v110, v102, vcc
	v_pk_mul_f32 v[100:101], v[118:119], v[84:85]
	v_pk_fma_f32 v[122:123], v[118:119], v[84:85], v[118:119] neg_lo:[1,0,0] neg_hi:[1,0,0]
	v_cmp_gt_f32_e32 vcc, 0, v118
	v_and_b32_e32 v102, 0x7fffffff, v116
	s_nop 0
	v_cndmask_b32_e32 v87, v122, v100, vcc
	v_cmp_gt_f32_e32 vcc, 0, v107
	s_nop 1
	v_cndmask_b32_e32 v100, v111, v103, vcc
	v_and_b32_e32 v103, 0x7fffffff, v117
	v_pk_fma_f32 v[102:103], v[102:103], s[56:57], 1.0 op_sel_hi:[1,0,0]
	v_cmp_gt_f32_e32 vcc, 0, v108
	v_rcp_f32_e32 v108, v102
	v_rcp_f32_e32 v109, v103
	v_cvt_pk_bf16_f32 v106, v86, v100
	v_cndmask_b32_e32 v85, v114, v112, vcc
	v_cvt_pk_bf16_f32 v107, v85, v94
	global_store_dwordx4 v[98:99], v[104:107], off sc1 nt
	v_pk_fma_f32 v[92:93], v[108:109], s[0:1], v[92:93] op_sel_hi:[1,0,0]
	v_cmp_gt_f32_e32 vcc, 0, v119
	v_pk_mul_f32 v[104:105], v[120:121], s[86:87] op_sel_hi:[1,0]
	v_pk_fma_f32 v[92:93], v[108:109], v[92:93], s[2:3] op_sel_hi:[1,1,0]
	v_exp_f32_e32 v104, v104
	v_exp_f32_e32 v105, v105
	v_pk_fma_f32 v[92:93], v[108:109], v[92:93], s[4:5] op_sel_hi:[1,1,0]
	v_cndmask_b32_e32 v102, v123, v101, vcc
	v_pk_fma_f32 v[92:93], v[108:109], v[92:93], s[88:89] op_sel_hi:[1,1,0]
	v_cmp_gt_f32_e32 vcc, 0, v117
	v_pk_mul_f32 v[92:93], v[108:109], v[92:93]
	s_nop 0
	v_pk_mul_f32 v[92:93], v[104:105], v[92:93]
	s_nop 0
	v_pk_mul_f32 v[104:105], v[116:117], v[92:93]
	v_pk_fma_f32 v[92:93], v[116:117], v[92:93], v[116:117] neg_lo:[1,0,0] neg_hi:[1,0,0]
	s_nop 0
	v_cndmask_b32_e32 v93, v93, v105, vcc
	v_cmp_gt_f32_e32 vcc, 0, v116
	s_nop 1
	v_cndmask_b32_e32 v92, v92, v104, vcc
	s_and_b64 vcc, exec, s[12:13]
	v_cvt_pk_bf16_f32 v104, v80, v82
	v_cvt_pk_bf16_f32 v105, v81, v83
	v_cvt_pk_bf16_f32 v106, v87, v102
	v_cvt_pk_bf16_f32 v107, v92, v93
	global_store_dwordx4 v[98:99], v[104:107], off offset:256 sc1 nt
	s_cbranch_vccnz .LBB0_764
	v_mov_b32_e32 v84, v87
	v_mov_b32_e32 v103, v85
	v_pk_add_f32 v[98:99], v[84:85], v[102:103]
	v_pk_mul_f32 v[104:105], v[84:85], v[102:103]
	v_mov_b32_e32 v106, v86
	v_mov_b32_e32 v107, v100
	v_mul_f32_e32 v84, v86, v86
	v_mov_b32_e32 v101, v87
	v_pk_fma_f32 v[106:107], v[106:107], v[106:107], v[84:85] op_sel_hi:[1,1,0]
	v_mul_f32_e32 v84, v92, v92
	v_pk_fma_f32 v[108:109], v[92:93], v[92:93], v[84:85] op_sel_hi:[1,1,0]
	v_mov_b32_e32 v110, v80
	v_mov_b32_e32 v111, v82
	v_mul_f32_e32 v84, v80, v80
	v_pk_add_f32 v[114:115], v[86:87], v[100:101]
	v_pk_mul_f32 v[86:87], v[86:87], v[100:101]
	v_mov_b32_e32 v99, v105
	v_pk_mul_f32 v[104:105], v[90:91], v[90:91]
	v_pk_fma_f32 v[110:111], v[110:111], v[110:111], v[84:85] op_sel_hi:[1,1,0]
	v_mov_b32_e32 v112, v81
	v_mov_b32_e32 v113, v83
	v_mul_f32_e32 v84, v81, v81
	v_mov_b32_e32 v115, v87
	v_pk_mul_f32 v[86:87], v[102:103], v[102:103]
	v_pk_add_f32 v[80:81], v[80:81], v[82:83]
	v_and_b32_e32 v83, 64, v192
	v_pk_fma_f32 v[104:105], v[88:89], v[88:89], v[104:105]
	v_pk_add_f32 v[88:89], v[88:89], v[90:91]
	v_xor_b32_e32 v82, 16, v192
	v_add_u32_e32 v87, 64, v83
	v_pk_fma_f32 v[112:113], v[112:113], v[112:113], v[84:85] op_sel_hi:[1,1,0]
	v_pk_add_f32 v[88:89], v[88:89], v[88:89] op_sel:[0,1] op_sel_hi:[1,0]
	v_cmp_lt_i32_e32 vcc, v82, v87
	v_mul_f32_e32 v116, v94, v94
	v_pk_add_f32 v[104:105], v[104:105], v[104:105] op_sel_hi:[0,1]
	v_cndmask_b32_e32 v82, v192, v82, vcc
	v_mov_b32_e32 v110, v85
	v_mov_b32_e32 v95, v113
	v_mov_b32_e32 v89, v86
	v_pk_add_f32 v[80:81], v[80:81], v[80:81] op_sel:[0,1] op_sel_hi:[1,0]
	v_lshlrev_b32_e32 v90, 2, v82
	v_pk_add_f32 v[82:83], v[110:111], v[94:95]
	v_pk_add_f32 v[84:85], v[114:115], v[88:89]
	v_mov_b32_e32 v106, v92
	v_mov_b32_e32 v104, v93
	v_mov_b32_e32 v81, v116
	v_pk_add_f32 v[82:83], v[84:85], v[82:83]
	v_mov_b32_e32 v147, v109
	v_pk_add_f32 v[84:85], v[106:107], v[104:105]
	v_pk_add_f32 v[80:81], v[98:99], v[80:81]
	v_pk_add_f32 v[82:83], v[82:83], v[146:147]
	v_pk_add_f32 v[80:81], v[80:81], v[84:85]
	v_xor_b32_e32 v84, 32, v192
	v_pk_add_f32 v[80:81], v[80:81], v[82:83]
	ds_bpermute_b32 v82, v90, v80
	ds_bpermute_b32 v83, v90, v81
	v_cmp_lt_i32_e32 vcc, v84, v87
	s_waitcnt lgkmcnt(0)
	v_pk_add_f32 v[80:81], v[80:81], v[82:83]
	v_cndmask_b32_e32 v84, v192, v84, vcc
	v_lshlrev_b32_e32 v84, 2, v84
	ds_bpermute_b32 v82, v84, v80
	ds_bpermute_b32 v83, v84, v81
	s_and_saveexec_b64 s[0:1], s[10:11]
	s_cbranch_execz .LBB0_763
	s_waitcnt lgkmcnt(0)
	v_pk_add_f32 v[80:81], v[80:81], v[82:83]
	v_lshlrev_b64 v[82:83], 7, v[96:97]
	v_lshl_add_u64 v[82:83], s[16:17], 0, v[82:83]
	v_lshl_add_u64 v[82:83], s[38:39], 3, v[82:83]
	s_lshl_b32 s88, s44, 3
	v_lshl_add_u64 v[82:83], v[82:83], 0, s[88:89]
	global_store_dwordx2 v[82:83], v[80:81], off

;     __device__ __forceinline__ void operator()(const f32x4 (&acc)[2][2][4][2], const Unit& u, int ui, int wr, int wc, int fr, int fq) const {
;     ...
;             for (int m = 0; m < 4; ++m) { const float r = rs[ai][m]; const int row = row0 + ai * HALF + m * 16; bf16_t* rowp = Z + (size_t)row * 2048 + col0; float s1 = 0.f, s2 = 0.f;
; #pragma unroll
;                 for (int bj = 0; bj < 2; ++bj) { const f32x4 v0 = acc[ai][bj][m][0] * r, v1 = acc[ai][bj][m][1] * r;
;                     const f32x2 a = gelu_pk((f32x2){v0[0], v0[1]}), b = gelu_pk((f32x2){v0[2], v0[3]}), c = gelu_pk((f32x2){v1[0], v1[1]}), d = gelu_pk((f32x2){v1[2], v1[3]});
.LBB0_764:
	v_mov_b32_e32 v84, v167
	v_pk_mul_f32 v[86:87], v[76:77], v[84:85] op_sel_hi:[1,0]
	s_mov_b32 s0, 0xbf3a00e3
	v_and_b32_e32 v77, 0x7fffffff, v87
	v_and_b32_e32 v76, 0x7fffffff, v86
	v_pk_fma_f32 v[76:77], v[76:77], s[56:57], 1.0 op_sel_hi:[1,0,0]
	v_pk_mul_f32 v[90:91], v[72:73], v[84:85] op_sel_hi:[1,0]
	v_rcp_f32_e32 v88, v76
	v_rcp_f32_e32 v89, v77
	v_mov_b64_e32 v[76:77], s[0:1]
	s_mov_b32 s0, 0x3f07dc22
	s_mov_b32 s88, 0x3e027906
	v_pk_fma_f32 v[72:73], v[88:89], s[0:1], v[76:77] op_sel_hi:[1,0,0]
	v_pk_mul_f32 v[78:79], v[78:79], v[84:85] op_sel_hi:[1,0]
	v_pk_fma_f32 v[72:73], v[88:89], v[72:73], s[2:3] op_sel_hi:[1,1,0]
	v_and_b32_e32 v95, 0x7fffffff, v79
	v_pk_fma_f32 v[72:73], v[88:89], v[72:73], s[4:5] op_sel_hi:[1,1,0]
	v_and_b32_e32 v94, 0x7fffffff, v78
	v_pk_fma_f32 v[72:73], v[88:89], v[72:73], s[88:89] op_sel_hi:[1,1,0]
	v_pk_fma_f32 v[94:95], v[94:95], s[56:57], 1.0 op_sel_hi:[1,0,0]
	v_pk_mul_f32 v[72:73], v[88:89], v[72:73]
	v_pk_mul_f32 v[88:89], v[86:87], v[86:87]
	v_rcp_f32_e32 v94, v94
	v_pk_mul_f32 v[88:89], v[88:89], s[86:87] op_sel_hi:[1,0]
	v_rcp_f32_e32 v95, v95
	v_exp_f32_e32 v88, v88
	v_exp_f32_e32 v89, v89
	v_pk_mul_f32 v[92:93], v[74:75], v[84:85] op_sel_hi:[1,0]
	v_pk_mul_f32 v[74:75], v[78:79], v[78:79]
	v_pk_mul_f32 v[68:69], v[68:69], v[84:85] op_sel_hi:[1,0]
	v_pk_mul_f32 v[72:73], v[88:89], v[72:73]
	v_pk_mul_f32 v[74:75], v[74:75], s[86:87] op_sel_hi:[1,0]
	v_pk_mul_f32 v[88:89], v[86:87], v[72:73]
	v_pk_fma_f32 v[96:97], v[86:87], v[72:73], v[86:87] neg_lo:[1,0,0] neg_hi:[1,0,0]
	v_pk_fma_f32 v[72:73], v[94:95], s[0:1], v[76:77] op_sel_hi:[1,0,0]
	v_exp_f32_e32 v74, v74
	v_pk_fma_f32 v[72:73], v[94:95], v[72:73], s[2:3] op_sel_hi:[1,1,0]
	v_exp_f32_e32 v75, v75
	v_and_b32_e32 v101, 0x7fffffff, v69
	v_and_b32_e32 v100, 0x7fffffff, v68
	v_pk_fma_f32 v[72:73], v[94:95], v[72:73], s[4:5] op_sel_hi:[1,1,0]
	v_pk_fma_f32 v[100:101], v[100:101], s[56:57], 1.0 op_sel_hi:[1,0,0]
	v_pk_fma_f32 v[72:73], v[94:95], v[72:73], s[88:89] op_sel_hi:[1,1,0]
	v_rcp_f32_e32 v100, v100
	v_rcp_f32_e32 v101, v101
	v_pk_mul_f32 v[72:73], v[94:95], v[72:73]
	v_and_b32_e32 v99, 0x7fffffff, v91
	v_pk_mul_f32 v[72:73], v[74:75], v[72:73]
	v_and_b32_e32 v98, 0x7fffffff, v90
	v_pk_mul_f32 v[74:75], v[78:79], v[72:73]
	v_pk_fma_f32 v[94:95], v[78:79], v[72:73], v[78:79] neg_lo:[1,0,0] neg_hi:[1,0,0]
	v_cmp_gt_f32_e32 vcc, 0, v78
	v_pk_fma_f32 v[98:99], v[98:99], s[56:57], 1.0 op_sel_hi:[1,0,0]
	v_pk_mul_f32 v[70:71], v[70:71], v[84:85] op_sel_hi:[1,0]
	v_cndmask_b32_e32 v73, v94, v74, vcc
	v_cmp_gt_f32_e32 vcc, 0, v86
	v_rcp_f32_e32 v98, v98
	v_rcp_f32_e32 v99, v99
	v_pk_mul_f32 v[102:103], v[66:67], v[84:85] op_sel_hi:[1,0]
	v_pk_mul_f32 v[84:85], v[64:65], v[84:85] op_sel_hi:[1,0]
	v_pk_fma_f32 v[64:65], v[100:101], s[0:1], v[76:77] op_sel_hi:[1,0,0]
	v_cndmask_b32_e32 v72, v96, v88, vcc
	v_cmp_gt_f32_e32 vcc, 0, v79
	v_pk_fma_f32 v[64:65], v[100:101], v[64:65], s[2:3] op_sel_hi:[1,1,0]
	v_pk_fma_f32 v[78:79], v[98:99], s[0:1], v[76:77] op_sel_hi:[1,0,0]
	v_cndmask_b32_e32 v75, v95, v75, vcc
	v_cmp_gt_f32_e32 vcc, 0, v87
	v_pk_fma_f32 v[64:65], v[100:101], v[64:65], s[4:5] op_sel_hi:[1,1,0]
	v_and_b32_e32 v95, 0x7fffffff, v93
	v_cndmask_b32_e32 v74, v97, v89, vcc
	v_pk_mul_f32 v[88:89], v[90:91], v[90:91]
	v_pk_fma_f32 v[64:65], v[100:101], v[64:65], s[88:89] op_sel_hi:[1,1,0]
	v_pk_mul_f32 v[88:89], v[88:89], s[86:87] op_sel_hi:[1,0]
	v_and_b32_e32 v94, 0x7fffffff, v92
	v_pk_mul_f32 v[64:65], v[100:101], v[64:65]
	v_pk_mul_f32 v[100:101], v[68:69], v[68:69]
	v_pk_fma_f32 v[78:79], v[98:99], v[78:79], s[2:3] op_sel_hi:[1,1,0]
	v_exp_f32_e32 v88, v88
	v_exp_f32_e32 v89, v89
	v_pk_fma_f32 v[94:95], v[94:95], s[56:57], 1.0 op_sel_hi:[1,0,0]
	v_pk_mul_f32 v[100:101], v[100:101], s[86:87] op_sel_hi:[1,0]
	v_and_b32_e32 v105, 0x7fffffff, v71
	v_and_b32_e32 v104, 0x7fffffff, v70
	v_pk_fma_f32 v[78:79], v[98:99], v[78:79], s[4:5] op_sel_hi:[1,1,0]
	v_rcp_f32_e32 v94, v94
	v_rcp_f32_e32 v95, v95
	v_exp_f32_e32 v100, v100
	v_exp_f32_e32 v101, v101
	v_pk_fma_f32 v[104:105], v[104:105], s[56:57], 1.0 op_sel_hi:[1,0,0]
	v_pk_fma_f32 v[78:79], v[98:99], v[78:79], s[88:89] op_sel_hi:[1,1,0]
	v_rcp_f32_e32 v104, v104
	v_rcp_f32_e32 v105, v105
	v_pk_mul_f32 v[78:79], v[98:99], v[78:79]
	v_pk_mul_f32 v[86:87], v[92:93], v[92:93]
	v_pk_mul_f32 v[78:79], v[88:89], v[78:79]
	v_pk_mul_f32 v[86:87], v[86:87], s[86:87] op_sel_hi:[1,0]
	v_pk_mul_f32 v[96:97], v[90:91], v[78:79]
	v_pk_fma_f32 v[98:99], v[90:91], v[78:79], v[90:91] neg_lo:[1,0,0] neg_hi:[1,0,0]
	v_pk_fma_f32 v[78:79], v[94:95], s[0:1], v[76:77] op_sel_hi:[1,0,0]
	v_pk_mul_f32 v[66:67], v[70:71], v[70:71]
	v_pk_mul_f32 v[64:65], v[100:101], v[64:65]
	v_pk_fma_f32 v[78:79], v[94:95], v[78:79], s[2:3] op_sel_hi:[1,1,0]
	v_exp_f32_e32 v86, v86
	v_exp_f32_e32 v87, v87
	v_pk_mul_f32 v[100:101], v[68:69], v[64:65]
	v_pk_fma_f32 v[106:107], v[68:69], v[64:65], v[68:69] neg_lo:[1,0,0] neg_hi:[1,0,0]
	v_pk_fma_f32 v[64:65], v[104:105], s[0:1], v[76:77] op_sel_hi:[1,0,0]
	v_pk_mul_f32 v[66:67], v[66:67], s[86:87] op_sel_hi:[1,0]
	v_pk_fma_f32 v[78:79], v[94:95], v[78:79], s[4:5] op_sel_hi:[1,1,0]
	v_pk_fma_f32 v[64:65], v[104:105], v[64:65], s[2:3] op_sel_hi:[1,1,0]
	v_exp_f32_e32 v66, v66
	v_exp_f32_e32 v67, v67
	v_pk_fma_f32 v[78:79], v[94:95], v[78:79], s[88:89] op_sel_hi:[1,1,0]
	v_pk_fma_f32 v[64:65], v[104:105], v[64:65], s[4:5] op_sel_hi:[1,1,0]
	v_pk_mul_f32 v[78:79], v[94:95], v[78:79]
	v_pk_fma_f32 v[64:65], v[104:105], v[64:65], s[88:89] op_sel_hi:[1,1,0]
	v_and_b32_e32 v109, 0x7fffffff, v85
	v_and_b32_e32 v108, 0x7fffffff, v84
	v_pk_mul_f32 v[78:79], v[86:87], v[78:79]
	v_pk_mul_f32 v[64:65], v[104:105], v[64:65]
	v_pk_fma_f32 v[108:109], v[108:109], s[56:57], 1.0 op_sel_hi:[1,0,0]
	v_pk_mul_f32 v[86:87], v[92:93], v[78:79]
	v_pk_fma_f32 v[94:95], v[92:93], v[78:79], v[92:93] neg_lo:[1,0,0] neg_hi:[1,0,0]
	v_cmp_gt_f32_e32 vcc, 0, v93
	v_pk_mul_f32 v[64:65], v[66:67], v[64:65]
	v_rcp_f32_e32 v108, v108
	v_rcp_f32_e32 v109, v109
	v_cndmask_b32_e32 v78, v95, v87, vcc
	v_pk_mul_f32 v[66:67], v[70:71], v[64:65]
	v_pk_fma_f32 v[104:105], v[70:71], v[64:65], v[70:71] neg_lo:[1,0,0] neg_hi:[1,0,0]
	v_cmp_gt_f32_e32 vcc, 0, v70
	v_and_b32_e32 v87, 0x7fffffff, v103
	v_add_u32_e32 v80, 48, v140
	v_cndmask_b32_e32 v65, v104, v66, vcc
	v_cmp_gt_f32_e32 vcc, 0, v68
	v_ashrrev_i32_e32 v81, 31, v80
	s_waitcnt lgkmcnt(0)
; __device__ __forceinline__ u32x4 pack8(const f32x4& a, const f32x4& b) { u32x4 w; w.x = cvt_pk_bf16(a[0], a[1]); w.y = cvt_pk_bf16(a[2], a[3]); w.z = cvt_pk_bf16(b[0], b[1]); w.w = cvt_pk_bf16(b[2], b[3]); return w; }
;     __device__ __forceinline__ void operator()(const f32x4 (&acc)[2][2][4][2], const Unit& u, int ui, int wr, int wc, int fr, int fq) const {
;     ...
;             for (int m = 0; m < 4; ++m) { const float r = rs[ai][m]; const int row = row0 + ai * HALF + m * 16; bf16_t* rowp = Z + (size_t)row * 2048 + col0; float s1 = 0.f, s2 = 0.f;
; #pragma unroll
;                 for (int bj = 0; bj < 2; ++bj) { const f32x4 v0 = acc[ai][bj][m][0] * r, v1 = acc[ai][bj][m][1] * r;
;                     const f32x2 a = gelu_pk((f32x2){v0[0], v0[1]}), b = gelu_pk((f32x2){v0[2], v0[3]}), c = gelu_pk((f32x2){v1[0], v1[1]}), d = gelu_pk((f32x2){v1[2], v1[3]});
;                     const f32x4 z0 = (f32x4){a.x, a.y, b.x, b.y}, z1 = (f32x4){c.x, c.y, d.x, d.y};
;                     *(u32x4*)(rowp + bj * HALF) = pack8(z0, z1);
;                     s1 += (z0[0] + z0[1]) + (z0[2] + z0[3]) + (z1[0] + z1[1]) + (z1[2] + z1[3]);
;                     s2 += (z0[0] * z0[0] + z0[1] * z0[1]) + (z0[2] * z0[2] + z0[3] * z0[3]) + (z1[0] * z1[0] + z1[1] * z1[1]) + (z1[2] * z1[2] + z1[3] * z1[3]); }
;                 if (u.pn >= 4) { s1 += __shfl_xor(s1, 16); s1 += __shfl_xor(s1, 32); s2 += __shfl_xor(s2, 16); s2 += __shfl_xor(s2, 32);
;                     if (fq == 0) vst[(size_t)row * 16 + (u.pn - 4) * 4 + wc] = (f32x2){s1, s2}; } }
	v_lshlrev_b64 v[82:83], 12, v[80:81]
	v_cndmask_b32_e32 v64, v106, v100, vcc
	v_cmp_gt_f32_e32 vcc, 0, v71
	v_pk_mul_f32 v[70:71], v[84:85], v[84:85]
	v_lshl_add_u64 v[82:83], s[20:21], 0, v[82:83]
	v_cndmask_b32_e32 v67, v105, v67, vcc
	v_cmp_gt_f32_e32 vcc, 0, v69
	v_pk_fma_f32 v[68:69], v[108:109], s[0:1], v[76:77] op_sel_hi:[1,0,0]
	v_pk_mul_f32 v[70:71], v[70:71], s[86:87] op_sel_hi:[1,0]
	v_pk_fma_f32 v[68:69], v[108:109], v[68:69], s[2:3] op_sel_hi:[1,1,0]
	v_exp_f32_e32 v70, v70
	v_exp_f32_e32 v71, v71
	v_pk_fma_f32 v[68:69], v[108:109], v[68:69], s[4:5] op_sel_hi:[1,1,0]
	v_cndmask_b32_e32 v66, v107, v101, vcc
	v_pk_fma_f32 v[68:69], v[108:109], v[68:69], s[88:89] op_sel_hi:[1,1,0]
	v_cmp_gt_f32_e32 vcc, 0, v90
	v_pk_mul_f32 v[68:69], v[108:109], v[68:69]
	v_lshl_add_u64 v[82:83], v[162:163], 1, v[82:83]
	v_pk_mul_f32 v[68:69], v[70:71], v[68:69]
	v_cndmask_b32_e32 v70, v98, v96, vcc
	v_pk_mul_f32 v[104:105], v[84:85], v[68:69]
	v_pk_fma_f32 v[106:107], v[84:85], v[68:69], v[84:85] neg_lo:[1,0,0] neg_hi:[1,0,0]
	v_cmp_gt_f32_e32 vcc, 0, v84
	v_cvt_pk_bf16_f32 v88, v72, v74
	v_cvt_pk_bf16_f32 v89, v73, v75
	v_pk_mul_f32 v[100:101], v[102:103], v[102:103]
	s_nop 0
	v_cndmask_b32_e32 v71, v106, v104, vcc
	v_cmp_gt_f32_e32 vcc, 0, v91
	s_nop 1
	v_cndmask_b32_e32 v84, v99, v97, vcc
	v_cmp_gt_f32_e32 vcc, 0, v92
	v_cvt_pk_bf16_f32 v90, v70, v84
	s_nop 1
	v_cndmask_b32_e32 v69, v94, v86, vcc
	v_and_b32_e32 v86, 0x7fffffff, v102
	v_pk_fma_f32 v[86:87], v[86:87], s[56:57], 1.0 op_sel_hi:[1,0,0]
	v_cvt_pk_bf16_f32 v91, v69, v78
	global_store_dwordx4 v[82:83], v[88:91], off sc1 nt
	v_rcp_f32_e32 v92, v86
	v_rcp_f32_e32 v93, v87
	v_pk_mul_f32 v[88:89], v[100:101], s[86:87] op_sel_hi:[1,0]
	v_cmp_gt_f32_e32 vcc, 0, v85
	v_exp_f32_e32 v88, v88
	v_pk_fma_f32 v[76:77], v[92:93], s[0:1], v[76:77] op_sel_hi:[1,0,0]
	v_exp_f32_e32 v89, v89
	v_pk_fma_f32 v[76:77], v[92:93], v[76:77], s[2:3] op_sel_hi:[1,1,0]
	v_cndmask_b32_e32 v86, v107, v105, vcc
	v_pk_fma_f32 v[76:77], v[92:93], v[76:77], s[4:5] op_sel_hi:[1,1,0]
	v_cmp_gt_f32_e32 vcc, 0, v103
	v_pk_fma_f32 v[76:77], v[92:93], v[76:77], s[88:89] op_sel_hi:[1,1,0]
	s_nop 0
	v_pk_mul_f32 v[76:77], v[92:93], v[76:77]
	s_nop 0
	v_pk_mul_f32 v[76:77], v[88:89], v[76:77]
	s_nop 0
	v_pk_mul_f32 v[88:89], v[102:103], v[76:77]
	v_pk_fma_f32 v[76:77], v[102:103], v[76:77], v[102:103] neg_lo:[1,0,0] neg_hi:[1,0,0]
	s_nop 0
	v_cndmask_b32_e32 v77, v77, v89, vcc
	v_cmp_gt_f32_e32 vcc, 0, v102
	s_nop 1
	v_cndmask_b32_e32 v76, v76, v88, vcc
	s_and_b64 vcc, exec, s[12:13]
	v_cvt_pk_bf16_f32 v88, v64, v66
	v_cvt_pk_bf16_f32 v89, v65, v67
	v_cvt_pk_bf16_f32 v90, v71, v86
	v_cvt_pk_bf16_f32 v91, v76, v77
	global_store_dwordx4 v[82:83], v[88:91], off offset:256 sc1 nt
	s_cbranch_vccnz .LBB0_768
	v_mov_b32_e32 v68, v71
	v_mov_b32_e32 v87, v69
	v_pk_add_f32 v[82:83], v[68:69], v[86:87]
	v_pk_mul_f32 v[88:89], v[68:69], v[86:87]
	v_mov_b32_e32 v90, v70
	v_mov_b32_e32 v91, v84
	v_mul_f32_e32 v68, v70, v70
	v_mov_b32_e32 v85, v71
	v_pk_fma_f32 v[90:91], v[90:91], v[90:91], v[68:69] op_sel_hi:[1,1,0]
	v_mul_f32_e32 v68, v76, v76
	v_pk_fma_f32 v[92:93], v[76:77], v[76:77], v[68:69] op_sel_hi:[1,1,0]
	v_mov_b32_e32 v94, v64
	v_mov_b32_e32 v95, v66
	v_mul_f32_e32 v68, v64, v64
	v_pk_add_f32 v[98:99], v[70:71], v[84:85]
	v_pk_mul_f32 v[70:71], v[70:71], v[84:85]
	v_mov_b32_e32 v83, v89
	v_pk_mul_f32 v[88:89], v[74:75], v[74:75]
	v_pk_fma_f32 v[94:95], v[94:95], v[94:95], v[68:69] op_sel_hi:[1,1,0]
	v_mov_b32_e32 v96, v65
	v_mov_b32_e32 v97, v67
	v_mul_f32_e32 v68, v65, v65
	v_mov_b32_e32 v99, v71
	v_pk_mul_f32 v[70:71], v[86:87], v[86:87]
	v_pk_add_f32 v[64:65], v[64:65], v[66:67]
	v_and_b32_e32 v67, 64, v192
	v_pk_fma_f32 v[88:89], v[72:73], v[72:73], v[88:89]
	v_pk_add_f32 v[72:73], v[72:73], v[74:75]
	v_xor_b32_e32 v66, 16, v192
	v_add_u32_e32 v71, 64, v67
	v_pk_fma_f32 v[96:97], v[96:97], v[96:97], v[68:69] op_sel_hi:[1,1,0]
	v_pk_add_f32 v[72:73], v[72:73], v[72:73] op_sel:[0,1] op_sel_hi:[1,0]
	v_cmp_lt_i32_e32 vcc, v66, v71
	v_mul_f32_e32 v100, v78, v78
	v_pk_add_f32 v[88:89], v[88:89], v[88:89] op_sel_hi:[0,1]
	v_cndmask_b32_e32 v66, v192, v66, vcc
	v_mov_b32_e32 v94, v69
	v_mov_b32_e32 v79, v97
	v_mov_b32_e32 v73, v70
	v_pk_add_f32 v[64:65], v[64:65], v[64:65] op_sel:[0,1] op_sel_hi:[1,0]
	v_lshlrev_b32_e32 v74, 2, v66
	v_pk_add_f32 v[66:67], v[94:95], v[78:79]
	v_pk_add_f32 v[68:69], v[98:99], v[72:73]
	v_mov_b32_e32 v90, v76
	v_mov_b32_e32 v88, v77
	v_mov_b32_e32 v65, v100
	v_pk_add_f32 v[66:67], v[68:69], v[66:67]
	v_mov_b32_e32 v147, v93
	v_pk_add_f32 v[68:69], v[90:91], v[88:89]
	v_pk_add_f32 v[64:65], v[82:83], v[64:65]
	v_pk_add_f32 v[66:67], v[66:67], v[146:147]
	v_pk_add_f32 v[64:65], v[64:65], v[68:69]
	v_xor_b32_e32 v68, 32, v192
	v_pk_add_f32 v[64:65], v[64:65], v[66:67]
	ds_bpermute_b32 v66, v74, v64
	ds_bpermute_b32 v67, v74, v65
	v_cmp_lt_i32_e32 vcc, v68, v71
	s_waitcnt lgkmcnt(0)
	v_pk_add_f32 v[64:65], v[64:65], v[66:67]
	v_cndmask_b32_e32 v68, v192, v68, vcc
	v_lshlrev_b32_e32 v68, 2, v68
	ds_bpermute_b32 v66, v68, v64
	ds_bpermute_b32 v67, v68, v65
	s_and_saveexec_b64 s[0:1], s[10:11]
	s_cbranch_execz .LBB0_767
	s_waitcnt lgkmcnt(0)
	v_pk_add_f32 v[64:65], v[64:65], v[66:67]
	v_lshlrev_b64 v[66:67], 7, v[80:81]
	v_lshl_add_u64 v[66:67], s[16:17], 0, v[66:67]
	v_lshl_add_u64 v[66:67], s[38:39], 3, v[66:67]
	s_lshl_b32 s88, s44, 3
	v_lshl_add_u64 v[66:67], v[66:67], 0, s[88:89]
	global_store_dwordx2 v[66:67], v[64:65], off

;     __device__ __forceinline__ void operator()(const f32x4 (&acc)[2][2][4][2], const Unit& u, int ui, int wr, int wc, int fr, int fq) const {
;     ...
;             for (int m = 0; m < 4; ++m) { const float r = rs[ai][m]; const int row = row0 + ai * HALF + m * 16; bf16_t* rowp = Z + (size_t)row * 2048 + col0; float s1 = 0.f, s2 = 0.f;
; #pragma unroll
;                 for (int bj = 0; bj < 2; ++bj) { const f32x4 v0 = acc[ai][bj][m][0] * r, v1 = acc[ai][bj][m][1] * r;
;                     const f32x2 a = gelu_pk((f32x2){v0[0], v0[1]}), b = gelu_pk((f32x2){v0[2], v0[3]}), c = gelu_pk((f32x2){v1[0], v1[1]}), d = gelu_pk((f32x2){v1[2], v1[3]});
.LBB0_768:
	v_pk_mul_f32 v[68:69], v[60:61], v[164:165] op_sel_hi:[1,0]
	s_mov_b32 s0, 0xbf3a00e3
	v_and_b32_e32 v61, 0x7fffffff, v69
	v_and_b32_e32 v60, 0x7fffffff, v68
	v_pk_fma_f32 v[60:61], v[60:61], s[56:57], 1.0 op_sel_hi:[1,0,0]
	v_pk_mul_f32 v[74:75], v[56:57], v[164:165] op_sel_hi:[1,0]
	v_rcp_f32_e32 v70, v60
	v_rcp_f32_e32 v71, v61
	v_mov_b64_e32 v[60:61], s[0:1]
	s_mov_b32 s0, 0x3f07dc22
	s_mov_b32 s88, 0x3e027906
	v_pk_fma_f32 v[56:57], v[70:71], s[0:1], v[60:61] op_sel_hi:[1,0,0]
	v_pk_mul_f32 v[62:63], v[62:63], v[164:165] op_sel_hi:[1,0]
	v_pk_fma_f32 v[56:57], v[70:71], v[56:57], s[2:3] op_sel_hi:[1,1,0]
	v_and_b32_e32 v73, 0x7fffffff, v63
	v_pk_fma_f32 v[56:57], v[70:71], v[56:57], s[4:5] op_sel_hi:[1,1,0]
	v_and_b32_e32 v72, 0x7fffffff, v62
	v_pk_fma_f32 v[56:57], v[70:71], v[56:57], s[88:89] op_sel_hi:[1,1,0]
	v_pk_fma_f32 v[72:73], v[72:73], s[56:57], 1.0 op_sel_hi:[1,0,0]
	v_pk_mul_f32 v[56:57], v[70:71], v[56:57]
	v_pk_mul_f32 v[70:71], v[68:69], v[68:69]
	v_rcp_f32_e32 v72, v72
	v_pk_mul_f32 v[70:71], v[70:71], s[86:87] op_sel_hi:[1,0]
	v_rcp_f32_e32 v73, v73
	v_exp_f32_e32 v70, v70
	v_exp_f32_e32 v71, v71
	v_pk_mul_f32 v[76:77], v[58:59], v[164:165] op_sel_hi:[1,0]
	v_pk_mul_f32 v[58:59], v[62:63], v[62:63]
	v_and_b32_e32 v81, 0x7fffffff, v75
	v_pk_mul_f32 v[56:57], v[70:71], v[56:57]
	v_pk_mul_f32 v[58:59], v[58:59], s[86:87] op_sel_hi:[1,0]
	v_pk_mul_f32 v[70:71], v[68:69], v[56:57]
	v_pk_fma_f32 v[78:79], v[68:69], v[56:57], v[68:69] neg_lo:[1,0,0] neg_hi:[1,0,0]
	v_pk_fma_f32 v[56:57], v[72:73], s[0:1], v[60:61] op_sel_hi:[1,0,0]
	v_exp_f32_e32 v58, v58
	v_pk_fma_f32 v[56:57], v[72:73], v[56:57], s[2:3] op_sel_hi:[1,1,0]
	v_exp_f32_e32 v59, v59
	v_pk_fma_f32 v[56:57], v[72:73], v[56:57], s[4:5] op_sel_hi:[1,1,0]
	v_and_b32_e32 v80, 0x7fffffff, v74
	v_pk_fma_f32 v[56:57], v[72:73], v[56:57], s[88:89] op_sel_hi:[1,1,0]
	v_cmp_gt_f32_e32 vcc, 0, v62
	v_pk_mul_f32 v[56:57], v[72:73], v[56:57]
	v_pk_fma_f32 v[80:81], v[80:81], s[56:57], 1.0 op_sel_hi:[1,0,0]
	v_pk_mul_f32 v[56:57], v[58:59], v[56:57]
	v_rcp_f32_e32 v80, v80
	v_pk_mul_f32 v[58:59], v[62:63], v[56:57]
	v_pk_fma_f32 v[72:73], v[62:63], v[56:57], v[62:63] neg_lo:[1,0,0] neg_hi:[1,0,0]
	v_rcp_f32_e32 v81, v81
	v_cndmask_b32_e32 v57, v72, v58, vcc
	v_cmp_gt_f32_e32 vcc, 0, v68
	v_and_b32_e32 v72, 0x7fffffff, v76
	v_pk_mul_f32 v[52:53], v[52:53], v[164:165] op_sel_hi:[1,0]
	v_cndmask_b32_e32 v56, v78, v70, vcc
	v_cmp_gt_f32_e32 vcc, 0, v63
	v_pk_fma_f32 v[62:63], v[80:81], s[0:1], v[60:61] op_sel_hi:[1,0,0]
	v_pk_mul_f32 v[86:87], v[48:49], v[164:165] op_sel_hi:[1,0]
	v_cndmask_b32_e32 v59, v73, v59, vcc
	v_cmp_gt_f32_e32 vcc, 0, v69
	v_and_b32_e32 v73, 0x7fffffff, v77
	v_pk_fma_f32 v[62:63], v[80:81], v[62:63], s[2:3] op_sel_hi:[1,1,0]
	v_cndmask_b32_e32 v58, v79, v71, vcc
	v_pk_mul_f32 v[70:71], v[74:75], v[74:75]
	v_pk_fma_f32 v[72:73], v[72:73], s[56:57], 1.0 op_sel_hi:[1,0,0]
	v_pk_mul_f32 v[70:71], v[70:71], s[86:87] op_sel_hi:[1,0]
	v_pk_fma_f32 v[62:63], v[80:81], v[62:63], s[4:5] op_sel_hi:[1,1,0]
	v_exp_f32_e32 v70, v70
	v_exp_f32_e32 v71, v71
	v_rcp_f32_e32 v72, v72
	v_rcp_f32_e32 v73, v73
	v_pk_fma_f32 v[62:63], v[80:81], v[62:63], s[88:89] op_sel_hi:[1,1,0]
	v_pk_mul_f32 v[68:69], v[76:77], v[76:77]
	v_pk_mul_f32 v[62:63], v[80:81], v[62:63]
	v_pk_mul_f32 v[68:69], v[68:69], s[86:87] op_sel_hi:[1,0]
	v_pk_mul_f32 v[62:63], v[70:71], v[62:63]
	v_exp_f32_e32 v68, v68
	v_pk_mul_f32 v[70:71], v[74:75], v[62:63]
	v_pk_fma_f32 v[78:79], v[74:75], v[62:63], v[74:75] neg_lo:[1,0,0] neg_hi:[1,0,0]
	v_pk_fma_f32 v[62:63], v[72:73], s[0:1], v[60:61] op_sel_hi:[1,0,0]
	v_exp_f32_e32 v69, v69
	v_pk_fma_f32 v[62:63], v[72:73], v[62:63], s[2:3] op_sel_hi:[1,1,0]
	v_pk_mul_f32 v[54:55], v[54:55], v[164:165] op_sel_hi:[1,0]
	v_pk_fma_f32 v[62:63], v[72:73], v[62:63], s[4:5] op_sel_hi:[1,1,0]
	v_and_b32_e32 v89, 0x7fffffff, v55
	v_pk_fma_f32 v[62:63], v[72:73], v[62:63], s[88:89] op_sel_hi:[1,1,0]
	v_and_b32_e32 v88, 0x7fffffff, v54
	v_pk_mul_f32 v[62:63], v[72:73], v[62:63]
	v_pk_fma_f32 v[88:89], v[88:89], s[56:57], 1.0 op_sel_hi:[1,0,0]
	v_pk_mul_f32 v[62:63], v[68:69], v[62:63]
	v_and_b32_e32 v69, 0x7fffffff, v53
	v_and_b32_e32 v68, 0x7fffffff, v52
	v_pk_fma_f32 v[68:69], v[68:69], s[56:57], 1.0 op_sel_hi:[1,0,0]
	v_rcp_f32_e32 v88, v88
	v_rcp_f32_e32 v68, v68
	v_rcp_f32_e32 v69, v69
	v_rcp_f32_e32 v89, v89
	v_pk_mul_f32 v[84:85], v[50:51], v[164:165] op_sel_hi:[1,0]
	v_pk_mul_f32 v[50:51], v[54:55], v[54:55]
	v_pk_fma_f32 v[48:49], v[68:69], s[0:1], v[60:61] op_sel_hi:[1,0,0]
	v_pk_mul_f32 v[50:51], v[50:51], s[86:87] op_sel_hi:[1,0]
	v_pk_fma_f32 v[48:49], v[68:69], v[48:49], s[2:3] op_sel_hi:[1,1,0]
	v_exp_f32_e32 v50, v50
	v_pk_fma_f32 v[48:49], v[68:69], v[48:49], s[4:5] op_sel_hi:[1,1,0]
	v_exp_f32_e32 v51, v51
	v_pk_fma_f32 v[48:49], v[68:69], v[48:49], s[88:89] op_sel_hi:[1,1,0]
	v_and_b32_e32 v93, 0x7fffffff, v87
	v_pk_mul_f32 v[48:49], v[68:69], v[48:49]
	v_pk_mul_f32 v[68:69], v[52:53], v[52:53]
	v_and_b32_e32 v92, 0x7fffffff, v86
	v_pk_mul_f32 v[68:69], v[68:69], s[86:87] op_sel_hi:[1,0]
	v_pk_fma_f32 v[92:93], v[92:93], s[56:57], 1.0 op_sel_hi:[1,0,0]
	v_exp_f32_e32 v68, v68
	v_exp_f32_e32 v69, v69
	v_pk_mul_f32 v[80:81], v[76:77], v[62:63]
	v_pk_fma_f32 v[82:83], v[76:77], v[62:63], v[76:77] neg_lo:[1,0,0] neg_hi:[1,0,0]
	v_cmp_gt_f32_e32 vcc, 0, v77
	v_pk_mul_f32 v[48:49], v[68:69], v[48:49]
	v_rcp_f32_e32 v92, v92
	v_pk_mul_f32 v[68:69], v[52:53], v[48:49]
	v_pk_fma_f32 v[90:91], v[52:53], v[48:49], v[52:53] neg_lo:[1,0,0] neg_hi:[1,0,0]
	v_pk_fma_f32 v[48:49], v[88:89], s[0:1], v[60:61] op_sel_hi:[1,0,0]
	v_rcp_f32_e32 v93, v93
	v_pk_fma_f32 v[48:49], v[88:89], v[48:49], s[2:3] op_sel_hi:[1,1,0]
	v_cndmask_b32_e32 v62, v83, v81, vcc
	v_pk_fma_f32 v[48:49], v[88:89], v[48:49], s[4:5] op_sel_hi:[1,1,0]
	v_cmp_gt_f32_e32 vcc, 0, v54
	v_pk_fma_f32 v[48:49], v[88:89], v[48:49], s[88:89] op_sel_hi:[1,1,0]
	v_add_u32_e32 v64, 0x80, v140
	v_pk_mul_f32 v[48:49], v[88:89], v[48:49]
	v_ashrrev_i32_e32 v65, 31, v64
	v_pk_mul_f32 v[48:49], v[50:51], v[48:49]
	s_waitcnt lgkmcnt(0)
; __device__ __forceinline__ u32x4 pack8(const f32x4& a, const f32x4& b) { u32x4 w; w.x = cvt_pk_bf16(a[0], a[1]); w.y = cvt_pk_bf16(a[2], a[3]); w.z = cvt_pk_bf16(b[0], b[1]); w.w = cvt_pk_bf16(b[2], b[3]); return w; }
;     __device__ __forceinline__ void operator()(const f32x4 (&acc)[2][2][4][2], const Unit& u, int ui, int wr, int wc, int fr, int fq) const {
;     ...
;             for (int m = 0; m < 4; ++m) { const float r = rs[ai][m]; const int row = row0 + ai * HALF + m * 16; bf16_t* rowp = Z + (size_t)row * 2048 + col0; float s1 = 0.f, s2 = 0.f;
; #pragma unroll
;                 for (int bj = 0; bj < 2; ++bj) { const f32x4 v0 = acc[ai][bj][m][0] * r, v1 = acc[ai][bj][m][1] * r;
;                     const f32x2 a = gelu_pk((f32x2){v0[0], v0[1]}), b = gelu_pk((f32x2){v0[2], v0[3]}), c = gelu_pk((f32x2){v1[0], v1[1]}), d = gelu_pk((f32x2){v1[2], v1[3]});
;                     const f32x4 z0 = (f32x4){a.x, a.y, b.x, b.y}, z1 = (f32x4){c.x, c.y, d.x, d.y};
;                     *(u32x4*)(rowp + bj * HALF) = pack8(z0, z1);
;                     s1 += (z0[0] + z0[1]) + (z0[2] + z0[3]) + (z1[0] + z1[1]) + (z1[2] + z1[3]);
;                     s2 += (z0[0] * z0[0] + z0[1] * z0[1]) + (z0[2] * z0[2] + z0[3] * z0[3]) + (z1[0] * z1[0] + z1[1] * z1[1]) + (z1[2] * z1[2] + z1[3] * z1[3]); }
;                 if (u.pn >= 4) { s1 += __shfl_xor(s1, 16); s1 += __shfl_xor(s1, 32); s2 += __shfl_xor(s2, 16); s2 += __shfl_xor(s2, 32);
;                     if (fq == 0) vst[(size_t)row * 16 + (u.pn - 4) * 4 + wc] = (f32x2){s1, s2}; } }
	v_lshlrev_b64 v[66:67], 12, v[64:65]
	v_pk_mul_f32 v[50:51], v[54:55], v[48:49]
	v_pk_fma_f32 v[88:89], v[54:55], v[48:49], v[54:55] neg_lo:[1,0,0] neg_hi:[1,0,0]
	v_lshl_add_u64 v[66:67], s[20:21], 0, v[66:67]
	v_cndmask_b32_e32 v49, v88, v50, vcc
	v_cmp_gt_f32_e32 vcc, 0, v52
	v_lshl_add_u64 v[66:67], v[162:163], 1, v[66:67]
	v_cvt_pk_bf16_f32 v72, v56, v58
	v_cvt_pk_bf16_f32 v73, v57, v59
	s_nop 0
	v_cndmask_b32_e32 v48, v90, v68, vcc
	v_cmp_gt_f32_e32 vcc, 0, v55
	v_pk_mul_f32 v[54:55], v[86:87], v[86:87]
	s_nop 0
	v_cndmask_b32_e32 v51, v89, v51, vcc
	v_cmp_gt_f32_e32 vcc, 0, v53
	v_pk_fma_f32 v[52:53], v[92:93], s[0:1], v[60:61] op_sel_hi:[1,0,0]
	v_pk_mul_f32 v[54:55], v[54:55], s[86:87] op_sel_hi:[1,0]
	v_pk_fma_f32 v[52:53], v[92:93], v[52:53], s[2:3] op_sel_hi:[1,1,0]
	v_exp_f32_e32 v54, v54
	v_exp_f32_e32 v55, v55
	v_pk_fma_f32 v[52:53], v[92:93], v[52:53], s[4:5] op_sel_hi:[1,1,0]
	v_cndmask_b32_e32 v50, v91, v69, vcc
	v_pk_fma_f32 v[52:53], v[92:93], v[52:53], s[88:89] op_sel_hi:[1,1,0]
	v_cmp_gt_f32_e32 vcc, 0, v74
	v_pk_mul_f32 v[52:53], v[92:93], v[52:53]
	v_pk_mul_f32 v[88:89], v[84:85], v[84:85]
	v_pk_mul_f32 v[52:53], v[54:55], v[52:53]
	v_cndmask_b32_e32 v54, v78, v70, vcc
	v_pk_mul_f32 v[68:69], v[86:87], v[52:53]
	v_pk_fma_f32 v[90:91], v[86:87], v[52:53], v[86:87] neg_lo:[1,0,0] neg_hi:[1,0,0]
	v_cmp_gt_f32_e32 vcc, 0, v86
	v_and_b32_e32 v70, 0x7fffffff, v84
	s_nop 0
	v_cndmask_b32_e32 v55, v90, v68, vcc
	v_cmp_gt_f32_e32 vcc, 0, v75
	s_nop 1
	v_cndmask_b32_e32 v68, v79, v71, vcc
	v_and_b32_e32 v71, 0x7fffffff, v85
	v_pk_fma_f32 v[70:71], v[70:71], s[56:57], 1.0 op_sel_hi:[1,0,0]
	v_cmp_gt_f32_e32 vcc, 0, v76
	v_rcp_f32_e32 v76, v70
	v_rcp_f32_e32 v77, v71
	v_cvt_pk_bf16_f32 v74, v54, v68
	v_cndmask_b32_e32 v53, v82, v80, vcc
	v_cvt_pk_bf16_f32 v75, v53, v62
	global_store_dwordx4 v[66:67], v[72:75], off sc1 nt
	v_pk_fma_f32 v[60:61], v[76:77], s[0:1], v[60:61] op_sel_hi:[1,0,0]
	v_cmp_gt_f32_e32 vcc, 0, v87
	v_pk_mul_f32 v[72:73], v[88:89], s[86:87] op_sel_hi:[1,0]
	v_pk_fma_f32 v[60:61], v[76:77], v[60:61], s[2:3] op_sel_hi:[1,1,0]
	v_exp_f32_e32 v72, v72
	v_exp_f32_e32 v73, v73
	v_pk_fma_f32 v[60:61], v[76:77], v[60:61], s[4:5] op_sel_hi:[1,1,0]
	v_cndmask_b32_e32 v70, v91, v69, vcc
	v_pk_fma_f32 v[60:61], v[76:77], v[60:61], s[88:89] op_sel_hi:[1,1,0]
	v_cmp_gt_f32_e32 vcc, 0, v85
	v_pk_mul_f32 v[60:61], v[76:77], v[60:61]
	s_nop 0
	v_pk_mul_f32 v[60:61], v[72:73], v[60:61]
	s_nop 0
	v_pk_mul_f32 v[72:73], v[84:85], v[60:61]
	v_pk_fma_f32 v[60:61], v[84:85], v[60:61], v[84:85] neg_lo:[1,0,0] neg_hi:[1,0,0]
	s_nop 0
	v_cndmask_b32_e32 v61, v61, v73, vcc
	v_cmp_gt_f32_e32 vcc, 0, v84
	s_nop 1
	v_cndmask_b32_e32 v60, v60, v72, vcc
	s_and_b64 vcc, exec, s[12:13]
	v_cvt_pk_bf16_f32 v72, v48, v50
	v_cvt_pk_bf16_f32 v73, v49, v51
	v_cvt_pk_bf16_f32 v74, v55, v70
	v_cvt_pk_bf16_f32 v75, v60, v61
	global_store_dwordx4 v[66:67], v[72:75], off offset:256 sc1 nt
	s_cbranch_vccnz .LBB0_772
	v_mov_b32_e32 v52, v55
	v_mov_b32_e32 v71, v53
	v_pk_add_f32 v[66:67], v[52:53], v[70:71]
	v_pk_mul_f32 v[72:73], v[52:53], v[70:71]
	v_mov_b32_e32 v74, v54
	v_mov_b32_e32 v75, v68
	v_mul_f32_e32 v52, v54, v54
	v_mov_b32_e32 v69, v55
	v_pk_fma_f32 v[74:75], v[74:75], v[74:75], v[52:53] op_sel_hi:[1,1,0]
	v_mul_f32_e32 v52, v60, v60
	v_pk_fma_f32 v[76:77], v[60:61], v[60:61], v[52:53] op_sel_hi:[1,1,0]
	v_mov_b32_e32 v78, v48
	v_mov_b32_e32 v79, v50
	v_mul_f32_e32 v52, v48, v48
	v_pk_add_f32 v[82:83], v[54:55], v[68:69]
	v_pk_mul_f32 v[54:55], v[54:55], v[68:69]
	v_mov_b32_e32 v67, v73
	v_pk_mul_f32 v[72:73], v[58:59], v[58:59]
	v_pk_fma_f32 v[78:79], v[78:79], v[78:79], v[52:53] op_sel_hi:[1,1,0]
	v_mov_b32_e32 v80, v49
	v_mov_b32_e32 v81, v51
	v_mul_f32_e32 v52, v49, v49
	v_mov_b32_e32 v83, v55
	v_pk_mul_f32 v[54:55], v[70:71], v[70:71]
	v_pk_add_f32 v[48:49], v[48:49], v[50:51]
	v_and_b32_e32 v51, 64, v192
	v_pk_fma_f32 v[72:73], v[56:57], v[56:57], v[72:73]
	v_pk_add_f32 v[56:57], v[56:57], v[58:59]
	v_xor_b32_e32 v50, 16, v192
	v_add_u32_e32 v55, 64, v51
	v_pk_fma_f32 v[80:81], v[80:81], v[80:81], v[52:53] op_sel_hi:[1,1,0]
	v_pk_add_f32 v[56:57], v[56:57], v[56:57] op_sel:[0,1] op_sel_hi:[1,0]
	v_cmp_lt_i32_e32 vcc, v50, v55
	v_mul_f32_e32 v84, v62, v62
	v_pk_add_f32 v[72:73], v[72:73], v[72:73] op_sel_hi:[0,1]
	v_cndmask_b32_e32 v50, v192, v50, vcc
	v_mov_b32_e32 v78, v53
	v_mov_b32_e32 v63, v81
	v_mov_b32_e32 v57, v54
	v_pk_add_f32 v[48:49], v[48:49], v[48:49] op_sel:[0,1] op_sel_hi:[1,0]
	v_lshlrev_b32_e32 v58, 2, v50
	v_pk_add_f32 v[50:51], v[78:79], v[62:63]
	v_pk_add_f32 v[52:53], v[82:83], v[56:57]
	v_mov_b32_e32 v74, v60
	v_mov_b32_e32 v72, v61
	v_mov_b32_e32 v49, v84
	v_pk_add_f32 v[50:51], v[52:53], v[50:51]
	v_mov_b32_e32 v147, v77
	v_pk_add_f32 v[52:53], v[74:75], v[72:73]
	v_pk_add_f32 v[48:49], v[66:67], v[48:49]
	v_pk_add_f32 v[50:51], v[50:51], v[146:147]
	v_pk_add_f32 v[48:49], v[48:49], v[52:53]
	v_xor_b32_e32 v52, 32, v192
	v_pk_add_f32 v[48:49], v[48:49], v[50:51]
	ds_bpermute_b32 v50, v58, v48
	ds_bpermute_b32 v51, v58, v49
	v_cmp_lt_i32_e32 vcc, v52, v55
	s_waitcnt lgkmcnt(0)
	v_pk_add_f32 v[48:49], v[48:49], v[50:51]
	v_cndmask_b32_e32 v52, v192, v52, vcc
	v_lshlrev_b32_e32 v52, 2, v52
	ds_bpermute_b32 v50, v52, v48
	ds_bpermute_b32 v51, v52, v49
	s_and_saveexec_b64 s[0:1], s[10:11]
	s_cbranch_execz .LBB0_771
	s_waitcnt lgkmcnt(0)
	v_pk_add_f32 v[48:49], v[48:49], v[50:51]
	v_lshlrev_b64 v[50:51], 7, v[64:65]
	v_lshl_add_u64 v[50:51], s[16:17], 0, v[50:51]
	v_lshl_add_u64 v[50:51], s[38:39], 3, v[50:51]
	s_lshl_b32 s88, s44, 3
	v_lshl_add_u64 v[50:51], v[50:51], 0, s[88:89]
	global_store_dwordx2 v[50:51], v[48:49], off

;     __device__ __forceinline__ void operator()(const f32x4 (&acc)[2][2][4][2], const Unit& u, int ui, int wr, int wc, int fr, int fq) const {
;     ...
;             for (int m = 0; m < 4; ++m) { const float r = rs[ai][m]; const int row = row0 + ai * HALF + m * 16; bf16_t* rowp = Z + (size_t)row * 2048 + col0; float s1 = 0.f, s2 = 0.f;
; #pragma unroll
;                 for (int bj = 0; bj < 2; ++bj) { const f32x4 v0 = acc[ai][bj][m][0] * r, v1 = acc[ai][bj][m][1] * r;
;                     const f32x2 a = gelu_pk((f32x2){v0[0], v0[1]}), b = gelu_pk((f32x2){v0[2], v0[3]}), c = gelu_pk((f32x2){v1[0], v1[1]}), d = gelu_pk((f32x2){v1[2], v1[3]});
.LBB0_772:
	v_mov_b32_e32 v52, v165
	v_pk_mul_f32 v[54:55], v[44:45], v[52:53] op_sel_hi:[1,0]
	s_mov_b32 s0, 0xbf3a00e3
	v_and_b32_e32 v45, 0x7fffffff, v55
	v_and_b32_e32 v44, 0x7fffffff, v54
	v_pk_fma_f32 v[44:45], v[44:45], s[56:57], 1.0 op_sel_hi:[1,0,0]
	v_pk_mul_f32 v[58:59], v[40:41], v[52:53] op_sel_hi:[1,0]
	v_rcp_f32_e32 v56, v44
	v_rcp_f32_e32 v57, v45
	v_mov_b64_e32 v[44:45], s[0:1]
	s_mov_b32 s0, 0x3f07dc22
	s_mov_b32 s88, 0x3e027906
	v_pk_fma_f32 v[40:41], v[56:57], s[0:1], v[44:45] op_sel_hi:[1,0,0]
	v_pk_mul_f32 v[46:47], v[46:47], v[52:53] op_sel_hi:[1,0]
	v_pk_fma_f32 v[40:41], v[56:57], v[40:41], s[2:3] op_sel_hi:[1,1,0]
	v_and_b32_e32 v63, 0x7fffffff, v47
	v_pk_fma_f32 v[40:41], v[56:57], v[40:41], s[4:5] op_sel_hi:[1,1,0]
	v_and_b32_e32 v62, 0x7fffffff, v46
	v_pk_fma_f32 v[40:41], v[56:57], v[40:41], s[88:89] op_sel_hi:[1,1,0]
	v_pk_fma_f32 v[62:63], v[62:63], s[56:57], 1.0 op_sel_hi:[1,0,0]
	v_pk_mul_f32 v[40:41], v[56:57], v[40:41]
	v_pk_mul_f32 v[56:57], v[54:55], v[54:55]
	v_rcp_f32_e32 v62, v62
	v_pk_mul_f32 v[56:57], v[56:57], s[86:87] op_sel_hi:[1,0]
	v_rcp_f32_e32 v63, v63
	v_exp_f32_e32 v56, v56
	v_exp_f32_e32 v57, v57
	v_pk_mul_f32 v[60:61], v[42:43], v[52:53] op_sel_hi:[1,0]
	v_pk_mul_f32 v[42:43], v[46:47], v[46:47]
	v_pk_mul_f32 v[36:37], v[36:37], v[52:53] op_sel_hi:[1,0]
	v_pk_mul_f32 v[40:41], v[56:57], v[40:41]
	v_pk_mul_f32 v[42:43], v[42:43], s[86:87] op_sel_hi:[1,0]
	v_pk_mul_f32 v[56:57], v[54:55], v[40:41]
	v_pk_fma_f32 v[64:65], v[54:55], v[40:41], v[54:55] neg_lo:[1,0,0] neg_hi:[1,0,0]
	v_pk_fma_f32 v[40:41], v[62:63], s[0:1], v[44:45] op_sel_hi:[1,0,0]
	v_exp_f32_e32 v42, v42
	v_pk_fma_f32 v[40:41], v[62:63], v[40:41], s[2:3] op_sel_hi:[1,1,0]
	v_exp_f32_e32 v43, v43
	v_and_b32_e32 v69, 0x7fffffff, v37
	v_and_b32_e32 v68, 0x7fffffff, v36
	v_pk_fma_f32 v[40:41], v[62:63], v[40:41], s[4:5] op_sel_hi:[1,1,0]
	v_pk_fma_f32 v[68:69], v[68:69], s[56:57], 1.0 op_sel_hi:[1,0,0]
	v_pk_fma_f32 v[40:41], v[62:63], v[40:41], s[88:89] op_sel_hi:[1,1,0]
	v_rcp_f32_e32 v68, v68
	v_rcp_f32_e32 v69, v69
	v_pk_mul_f32 v[40:41], v[62:63], v[40:41]
	v_and_b32_e32 v67, 0x7fffffff, v59
	v_pk_mul_f32 v[40:41], v[42:43], v[40:41]
	v_and_b32_e32 v66, 0x7fffffff, v58
	v_pk_mul_f32 v[42:43], v[46:47], v[40:41]
	v_pk_fma_f32 v[62:63], v[46:47], v[40:41], v[46:47] neg_lo:[1,0,0] neg_hi:[1,0,0]
	v_cmp_gt_f32_e32 vcc, 0, v46
	v_pk_fma_f32 v[66:67], v[66:67], s[56:57], 1.0 op_sel_hi:[1,0,0]
	v_pk_mul_f32 v[38:39], v[38:39], v[52:53] op_sel_hi:[1,0]
	v_cndmask_b32_e32 v41, v62, v42, vcc
	v_cmp_gt_f32_e32 vcc, 0, v54
	v_rcp_f32_e32 v66, v66
	v_rcp_f32_e32 v67, v67
	v_pk_mul_f32 v[70:71], v[34:35], v[52:53] op_sel_hi:[1,0]
	v_pk_mul_f32 v[52:53], v[32:33], v[52:53] op_sel_hi:[1,0]
	v_pk_fma_f32 v[32:33], v[68:69], s[0:1], v[44:45] op_sel_hi:[1,0,0]
	v_cndmask_b32_e32 v40, v64, v56, vcc
	v_cmp_gt_f32_e32 vcc, 0, v47
	v_pk_fma_f32 v[32:33], v[68:69], v[32:33], s[2:3] op_sel_hi:[1,1,0]
	v_pk_fma_f32 v[46:47], v[66:67], s[0:1], v[44:45] op_sel_hi:[1,0,0]
	v_cndmask_b32_e32 v43, v63, v43, vcc
	v_cmp_gt_f32_e32 vcc, 0, v55
	v_pk_fma_f32 v[32:33], v[68:69], v[32:33], s[4:5] op_sel_hi:[1,1,0]
	v_and_b32_e32 v63, 0x7fffffff, v61
	v_cndmask_b32_e32 v42, v65, v57, vcc
	v_pk_mul_f32 v[56:57], v[58:59], v[58:59]
	v_pk_fma_f32 v[32:33], v[68:69], v[32:33], s[88:89] op_sel_hi:[1,1,0]
	v_pk_mul_f32 v[56:57], v[56:57], s[86:87] op_sel_hi:[1,0]
	v_and_b32_e32 v62, 0x7fffffff, v60
	v_pk_mul_f32 v[32:33], v[68:69], v[32:33]
	v_pk_mul_f32 v[68:69], v[36:37], v[36:37]
	v_pk_fma_f32 v[46:47], v[66:67], v[46:47], s[2:3] op_sel_hi:[1,1,0]
	v_exp_f32_e32 v56, v56
	v_exp_f32_e32 v57, v57
	v_pk_fma_f32 v[62:63], v[62:63], s[56:57], 1.0 op_sel_hi:[1,0,0]
	v_pk_mul_f32 v[68:69], v[68:69], s[86:87] op_sel_hi:[1,0]
	v_and_b32_e32 v73, 0x7fffffff, v39
	v_and_b32_e32 v72, 0x7fffffff, v38
	v_pk_fma_f32 v[46:47], v[66:67], v[46:47], s[4:5] op_sel_hi:[1,1,0]
	v_rcp_f32_e32 v62, v62
	v_rcp_f32_e32 v63, v63
	v_exp_f32_e32 v68, v68
	v_exp_f32_e32 v69, v69
	v_pk_fma_f32 v[72:73], v[72:73], s[56:57], 1.0 op_sel_hi:[1,0,0]
	v_pk_fma_f32 v[46:47], v[66:67], v[46:47], s[88:89] op_sel_hi:[1,1,0]
	v_rcp_f32_e32 v72, v72
	v_rcp_f32_e32 v73, v73
	v_pk_mul_f32 v[46:47], v[66:67], v[46:47]
	v_pk_mul_f32 v[54:55], v[60:61], v[60:61]
	v_pk_mul_f32 v[46:47], v[56:57], v[46:47]
	v_pk_mul_f32 v[54:55], v[54:55], s[86:87] op_sel_hi:[1,0]
	v_pk_mul_f32 v[64:65], v[58:59], v[46:47]
	v_pk_fma_f32 v[66:67], v[58:59], v[46:47], v[58:59] neg_lo:[1,0,0] neg_hi:[1,0,0]
	v_pk_fma_f32 v[46:47], v[62:63], s[0:1], v[44:45] op_sel_hi:[1,0,0]
	v_pk_mul_f32 v[34:35], v[38:39], v[38:39]
	v_pk_mul_f32 v[32:33], v[68:69], v[32:33]
	v_pk_fma_f32 v[46:47], v[62:63], v[46:47], s[2:3] op_sel_hi:[1,1,0]
	v_exp_f32_e32 v54, v54
	v_exp_f32_e32 v55, v55
	v_pk_mul_f32 v[68:69], v[36:37], v[32:33]
	v_pk_fma_f32 v[74:75], v[36:37], v[32:33], v[36:37] neg_lo:[1,0,0] neg_hi:[1,0,0]
	v_pk_fma_f32 v[32:33], v[72:73], s[0:1], v[44:45] op_sel_hi:[1,0,0]
	v_pk_mul_f32 v[34:35], v[34:35], s[86:87] op_sel_hi:[1,0]
	v_pk_fma_f32 v[46:47], v[62:63], v[46:47], s[4:5] op_sel_hi:[1,1,0]
	v_pk_fma_f32 v[32:33], v[72:73], v[32:33], s[2:3] op_sel_hi:[1,1,0]
	v_exp_f32_e32 v34, v34
	v_exp_f32_e32 v35, v35
	v_pk_fma_f32 v[46:47], v[62:63], v[46:47], s[88:89] op_sel_hi:[1,1,0]
	v_pk_fma_f32 v[32:33], v[72:73], v[32:33], s[4:5] op_sel_hi:[1,1,0]
	v_pk_mul_f32 v[46:47], v[62:63], v[46:47]
	v_pk_fma_f32 v[32:33], v[72:73], v[32:33], s[88:89] op_sel_hi:[1,1,0]
	v_and_b32_e32 v77, 0x7fffffff, v53
	v_and_b32_e32 v76, 0x7fffffff, v52
	v_pk_mul_f32 v[46:47], v[54:55], v[46:47]
	v_pk_mul_f32 v[32:33], v[72:73], v[32:33]
	v_pk_fma_f32 v[76:77], v[76:77], s[56:57], 1.0 op_sel_hi:[1,0,0]
	v_pk_mul_f32 v[54:55], v[60:61], v[46:47]
	v_pk_fma_f32 v[62:63], v[60:61], v[46:47], v[60:61] neg_lo:[1,0,0] neg_hi:[1,0,0]
	v_cmp_gt_f32_e32 vcc, 0, v61
	v_pk_mul_f32 v[32:33], v[34:35], v[32:33]
	v_rcp_f32_e32 v76, v76
	v_rcp_f32_e32 v77, v77
	v_cndmask_b32_e32 v46, v63, v55, vcc
	v_pk_mul_f32 v[34:35], v[38:39], v[32:33]
	v_pk_fma_f32 v[72:73], v[38:39], v[32:33], v[38:39] neg_lo:[1,0,0] neg_hi:[1,0,0]
	v_cmp_gt_f32_e32 vcc, 0, v38
	v_and_b32_e32 v55, 0x7fffffff, v71
	v_add_u32_e32 v48, 0x90, v140
	v_cndmask_b32_e32 v33, v72, v34, vcc
	v_cmp_gt_f32_e32 vcc, 0, v36
	v_ashrrev_i32_e32 v49, 31, v48
	s_waitcnt lgkmcnt(0)
; __device__ __forceinline__ u32x4 pack8(const f32x4& a, const f32x4& b) { u32x4 w; w.x = cvt_pk_bf16(a[0], a[1]); w.y = cvt_pk_bf16(a[2], a[3]); w.z = cvt_pk_bf16(b[0], b[1]); w.w = cvt_pk_bf16(b[2], b[3]); return w; }
;     __device__ __forceinline__ void operator()(const f32x4 (&acc)[2][2][4][2], const Unit& u, int ui, int wr, int wc, int fr, int fq) const {
;     ...
;             for (int m = 0; m < 4; ++m) { const float r = rs[ai][m]; const int row = row0 + ai * HALF + m * 16; bf16_t* rowp = Z + (size_t)row * 2048 + col0; float s1 = 0.f, s2 = 0.f;
; #pragma unroll
;                 for (int bj = 0; bj < 2; ++bj) { const f32x4 v0 = acc[ai][bj][m][0] * r, v1 = acc[ai][bj][m][1] * r;
;                     const f32x2 a = gelu_pk((f32x2){v0[0], v0[1]}), b = gelu_pk((f32x2){v0[2], v0[3]}), c = gelu_pk((f32x2){v1[0], v1[1]}), d = gelu_pk((f32x2){v1[2], v1[3]});
;                     const f32x4 z0 = (f32x4){a.x, a.y, b.x, b.y}, z1 = (f32x4){c.x, c.y, d.x, d.y};
;                     *(u32x4*)(rowp + bj * HALF) = pack8(z0, z1);
;                     s1 += (z0[0] + z0[1]) + (z0[2] + z0[3]) + (z1[0] + z1[1]) + (z1[2] + z1[3]);
;                     s2 += (z0[0] * z0[0] + z0[1] * z0[1]) + (z0[2] * z0[2] + z0[3] * z0[3]) + (z1[0] * z1[0] + z1[1] * z1[1]) + (z1[2] * z1[2] + z1[3] * z1[3]); }
;                 if (u.pn >= 4) { s1 += __shfl_xor(s1, 16); s1 += __shfl_xor(s1, 32); s2 += __shfl_xor(s2, 16); s2 += __shfl_xor(s2, 32);
;                     if (fq == 0) vst[(size_t)row * 16 + (u.pn - 4) * 4 + wc] = (f32x2){s1, s2}; } }
	v_lshlrev_b64 v[50:51], 12, v[48:49]
	v_cndmask_b32_e32 v32, v74, v68, vcc
	v_cmp_gt_f32_e32 vcc, 0, v39
	v_pk_mul_f32 v[38:39], v[52:53], v[52:53]
	v_lshl_add_u64 v[50:51], s[20:21], 0, v[50:51]
	v_cndmask_b32_e32 v35, v73, v35, vcc
	v_cmp_gt_f32_e32 vcc, 0, v37
	v_pk_fma_f32 v[36:37], v[76:77], s[0:1], v[44:45] op_sel_hi:[1,0,0]
	v_pk_mul_f32 v[38:39], v[38:39], s[86:87] op_sel_hi:[1,0]
	v_pk_fma_f32 v[36:37], v[76:77], v[36:37], s[2:3] op_sel_hi:[1,1,0]
	v_exp_f32_e32 v38, v38
	v_exp_f32_e32 v39, v39
	v_pk_fma_f32 v[36:37], v[76:77], v[36:37], s[4:5] op_sel_hi:[1,1,0]
	v_cndmask_b32_e32 v34, v75, v69, vcc
	v_pk_fma_f32 v[36:37], v[76:77], v[36:37], s[88:89] op_sel_hi:[1,1,0]
	v_cmp_gt_f32_e32 vcc, 0, v58
	v_pk_mul_f32 v[36:37], v[76:77], v[36:37]
	v_lshl_add_u64 v[50:51], v[162:163], 1, v[50:51]
	v_pk_mul_f32 v[36:37], v[38:39], v[36:37]
	v_cndmask_b32_e32 v38, v66, v64, vcc
	v_pk_mul_f32 v[72:73], v[52:53], v[36:37]
	v_pk_fma_f32 v[74:75], v[52:53], v[36:37], v[52:53] neg_lo:[1,0,0] neg_hi:[1,0,0]
	v_cmp_gt_f32_e32 vcc, 0, v52
	v_cvt_pk_bf16_f32 v56, v40, v42
	v_cvt_pk_bf16_f32 v57, v41, v43
	v_pk_mul_f32 v[68:69], v[70:71], v[70:71]
	s_nop 0
	v_cndmask_b32_e32 v39, v74, v72, vcc
	v_cmp_gt_f32_e32 vcc, 0, v59
	s_nop 1
	v_cndmask_b32_e32 v52, v67, v65, vcc
	v_cmp_gt_f32_e32 vcc, 0, v60
	v_cvt_pk_bf16_f32 v58, v38, v52
	s_nop 1
	v_cndmask_b32_e32 v37, v62, v54, vcc
	v_and_b32_e32 v54, 0x7fffffff, v70
	v_pk_fma_f32 v[54:55], v[54:55], s[56:57], 1.0 op_sel_hi:[1,0,0]
	v_cvt_pk_bf16_f32 v59, v37, v46
	global_store_dwordx4 v[50:51], v[56:59], off sc1 nt
	v_rcp_f32_e32 v60, v54
	v_rcp_f32_e32 v61, v55
	v_pk_mul_f32 v[56:57], v[68:69], s[86:87] op_sel_hi:[1,0]
	v_cmp_gt_f32_e32 vcc, 0, v53
	v_exp_f32_e32 v56, v56
	v_pk_fma_f32 v[44:45], v[60:61], s[0:1], v[44:45] op_sel_hi:[1,0,0]
	v_exp_f32_e32 v57, v57
	v_pk_fma_f32 v[44:45], v[60:61], v[44:45], s[2:3] op_sel_hi:[1,1,0]
	v_cndmask_b32_e32 v54, v75, v73, vcc
	v_pk_fma_f32 v[44:45], v[60:61], v[44:45], s[4:5] op_sel_hi:[1,1,0]
	v_cmp_gt_f32_e32 vcc, 0, v71
	v_pk_fma_f32 v[44:45], v[60:61], v[44:45], s[88:89] op_sel_hi:[1,1,0]
	s_nop 0
	v_pk_mul_f32 v[44:45], v[60:61], v[44:45]
	s_nop 0
	v_pk_mul_f32 v[44:45], v[56:57], v[44:45]
	s_nop 0
	v_pk_mul_f32 v[56:57], v[70:71], v[44:45]
	v_pk_fma_f32 v[44:45], v[70:71], v[44:45], v[70:71] neg_lo:[1,0,0] neg_hi:[1,0,0]
	s_nop 0
	v_cndmask_b32_e32 v45, v45, v57, vcc
	v_cmp_gt_f32_e32 vcc, 0, v70
	s_nop 1
	v_cndmask_b32_e32 v44, v44, v56, vcc
	s_and_b64 vcc, exec, s[12:13]
	v_cvt_pk_bf16_f32 v56, v32, v34
	v_cvt_pk_bf16_f32 v57, v33, v35
	v_cvt_pk_bf16_f32 v58, v39, v54
	v_cvt_pk_bf16_f32 v59, v44, v45
	global_store_dwordx4 v[50:51], v[56:59], off offset:256 sc1 nt
	s_cbranch_vccnz .LBB0_776
	v_mov_b32_e32 v36, v39
	v_mov_b32_e32 v55, v37
	v_pk_add_f32 v[50:51], v[36:37], v[54:55]
	v_pk_mul_f32 v[56:57], v[36:37], v[54:55]
	v_mov_b32_e32 v58, v38
	v_mov_b32_e32 v59, v52
	v_mul_f32_e32 v36, v38, v38
	v_mov_b32_e32 v53, v39
	v_pk_fma_f32 v[58:59], v[58:59], v[58:59], v[36:37] op_sel_hi:[1,1,0]
	v_mul_f32_e32 v36, v44, v44
	v_pk_fma_f32 v[60:61], v[44:45], v[44:45], v[36:37] op_sel_hi:[1,1,0]
	v_mov_b32_e32 v62, v32
	v_mov_b32_e32 v63, v34
	v_mul_f32_e32 v36, v32, v32
	v_pk_add_f32 v[66:67], v[38:39], v[52:53]
	v_pk_mul_f32 v[38:39], v[38:39], v[52:53]
	v_mov_b32_e32 v51, v57
	v_pk_mul_f32 v[56:57], v[42:43], v[42:43]
	v_pk_fma_f32 v[62:63], v[62:63], v[62:63], v[36:37] op_sel_hi:[1,1,0]
	v_mov_b32_e32 v64, v33
	v_mov_b32_e32 v65, v35
	v_mul_f32_e32 v36, v33, v33
	v_mov_b32_e32 v67, v39
	v_pk_mul_f32 v[38:39], v[54:55], v[54:55]
	v_pk_add_f32 v[32:33], v[32:33], v[34:35]
	v_and_b32_e32 v35, 64, v192
	v_pk_fma_f32 v[56:57], v[40:41], v[40:41], v[56:57]
	v_pk_add_f32 v[40:41], v[40:41], v[42:43]
	v_xor_b32_e32 v34, 16, v192
	v_add_u32_e32 v39, 64, v35
	v_pk_fma_f32 v[64:65], v[64:65], v[64:65], v[36:37] op_sel_hi:[1,1,0]
	v_pk_add_f32 v[40:41], v[40:41], v[40:41] op_sel:[0,1] op_sel_hi:[1,0]
	v_cmp_lt_i32_e32 vcc, v34, v39
	v_mul_f32_e32 v68, v46, v46
	v_pk_add_f32 v[56:57], v[56:57], v[56:57] op_sel_hi:[0,1]
	v_cndmask_b32_e32 v34, v192, v34, vcc
	v_mov_b32_e32 v62, v37
	v_mov_b32_e32 v47, v65
	v_mov_b32_e32 v41, v38
	v_pk_add_f32 v[32:33], v[32:33], v[32:33] op_sel:[0,1] op_sel_hi:[1,0]
	v_lshlrev_b32_e32 v42, 2, v34
	v_pk_add_f32 v[34:35], v[62:63], v[46:47]
	v_pk_add_f32 v[36:37], v[66:67], v[40:41]
	v_mov_b32_e32 v58, v44
	v_mov_b32_e32 v56, v45
	v_mov_b32_e32 v33, v68
	v_pk_add_f32 v[34:35], v[36:37], v[34:35]
	v_mov_b32_e32 v147, v61
	v_pk_add_f32 v[36:37], v[58:59], v[56:57]
	v_pk_add_f32 v[32:33], v[50:51], v[32:33]
	v_pk_add_f32 v[34:35], v[34:35], v[146:147]
	v_pk_add_f32 v[32:33], v[32:33], v[36:37]
	v_xor_b32_e32 v36, 32, v192
	v_pk_add_f32 v[32:33], v[32:33], v[34:35]
	ds_bpermute_b32 v34, v42, v32
	ds_bpermute_b32 v35, v42, v33
	v_cmp_lt_i32_e32 vcc, v36, v39
	s_waitcnt lgkmcnt(0)
	v_pk_add_f32 v[32:33], v[32:33], v[34:35]
	v_cndmask_b32_e32 v36, v192, v36, vcc
	v_lshlrev_b32_e32 v36, 2, v36
	ds_bpermute_b32 v34, v36, v32
	ds_bpermute_b32 v35, v36, v33
	s_and_saveexec_b64 s[0:1], s[10:11]
	s_cbranch_execz .LBB0_775
	s_waitcnt lgkmcnt(0)
	v_pk_add_f32 v[32:33], v[32:33], v[34:35]
	v_lshlrev_b64 v[34:35], 7, v[48:49]
	v_lshl_add_u64 v[34:35], s[16:17], 0, v[34:35]
	v_lshl_add_u64 v[34:35], s[38:39], 3, v[34:35]
	s_lshl_b32 s88, s44, 3
	v_lshl_add_u64 v[34:35], v[34:35], 0, s[88:89]
	global_store_dwordx2 v[34:35], v[32:33], off

;     __device__ __forceinline__ void operator()(const f32x4 (&acc)[2][2][4][2], const Unit& u, int ui, int wr, int wc, int fr, int fq) const {
;     ...
;             for (int m = 0; m < 4; ++m) { const float r = rs[ai][m]; const int row = row0 + ai * HALF + m * 16; bf16_t* rowp = Z + (size_t)row * 2048 + col0; float s1 = 0.f, s2 = 0.f;
; #pragma unroll
;                 for (int bj = 0; bj < 2; ++bj) { const f32x4 v0 = acc[ai][bj][m][0] * r, v1 = acc[ai][bj][m][1] * r;
;                     const f32x2 a = gelu_pk((f32x2){v0[0], v0[1]}), b = gelu_pk((f32x2){v0[2], v0[3]}), c = gelu_pk((f32x2){v1[0], v1[1]}), d = gelu_pk((f32x2){v1[2], v1[3]});
.LBB0_776:
	v_pk_mul_f32 v[36:37], v[28:29], v[142:143] op_sel_hi:[1,0]
	s_mov_b32 s0, 0xbf3a00e3
	v_and_b32_e32 v29, 0x7fffffff, v37
	v_and_b32_e32 v28, 0x7fffffff, v36
	v_pk_fma_f32 v[28:29], v[28:29], s[56:57], 1.0 op_sel_hi:[1,0,0]
	v_pk_mul_f32 v[42:43], v[24:25], v[142:143] op_sel_hi:[1,0]
	v_rcp_f32_e32 v38, v28
	v_rcp_f32_e32 v39, v29
	v_mov_b64_e32 v[28:29], s[0:1]
	s_mov_b32 s0, 0x3f07dc22
	s_mov_b32 s88, 0x3e027906
	v_pk_fma_f32 v[24:25], v[38:39], s[0:1], v[28:29] op_sel_hi:[1,0,0]
	v_pk_mul_f32 v[30:31], v[30:31], v[142:143] op_sel_hi:[1,0]
	v_pk_fma_f32 v[24:25], v[38:39], v[24:25], s[2:3] op_sel_hi:[1,1,0]
	v_and_b32_e32 v41, 0x7fffffff, v31
	v_pk_fma_f32 v[24:25], v[38:39], v[24:25], s[4:5] op_sel_hi:[1,1,0]
	v_and_b32_e32 v40, 0x7fffffff, v30
	v_pk_fma_f32 v[24:25], v[38:39], v[24:25], s[88:89] op_sel_hi:[1,1,0]
	v_pk_fma_f32 v[40:41], v[40:41], s[56:57], 1.0 op_sel_hi:[1,0,0]
	v_pk_mul_f32 v[24:25], v[38:39], v[24:25]
	v_pk_mul_f32 v[38:39], v[36:37], v[36:37]
	v_rcp_f32_e32 v40, v40
	v_pk_mul_f32 v[38:39], v[38:39], s[86:87] op_sel_hi:[1,0]
	v_rcp_f32_e32 v41, v41
	v_exp_f32_e32 v38, v38
	v_exp_f32_e32 v39, v39
	v_pk_mul_f32 v[44:45], v[26:27], v[142:143] op_sel_hi:[1,0]
	v_pk_mul_f32 v[26:27], v[30:31], v[30:31]
	v_and_b32_e32 v49, 0x7fffffff, v43
	v_pk_mul_f32 v[24:25], v[38:39], v[24:25]
	v_pk_mul_f32 v[26:27], v[26:27], s[86:87] op_sel_hi:[1,0]
	v_pk_mul_f32 v[38:39], v[36:37], v[24:25]
	v_pk_fma_f32 v[46:47], v[36:37], v[24:25], v[36:37] neg_lo:[1,0,0] neg_hi:[1,0,0]
	v_pk_fma_f32 v[24:25], v[40:41], s[0:1], v[28:29] op_sel_hi:[1,0,0]
	v_exp_f32_e32 v26, v26
	v_pk_fma_f32 v[24:25], v[40:41], v[24:25], s[2:3] op_sel_hi:[1,1,0]
	v_exp_f32_e32 v27, v27
	v_pk_fma_f32 v[24:25], v[40:41], v[24:25], s[4:5] op_sel_hi:[1,1,0]
	v_and_b32_e32 v48, 0x7fffffff, v42
	v_pk_fma_f32 v[24:25], v[40:41], v[24:25], s[88:89] op_sel_hi:[1,1,0]
	v_cmp_gt_f32_e32 vcc, 0, v30
	v_pk_mul_f32 v[24:25], v[40:41], v[24:25]
	v_pk_fma_f32 v[48:49], v[48:49], s[56:57], 1.0 op_sel_hi:[1,0,0]
	v_pk_mul_f32 v[24:25], v[26:27], v[24:25]
	v_rcp_f32_e32 v48, v48
	v_pk_mul_f32 v[26:27], v[30:31], v[24:25]
	v_pk_fma_f32 v[40:41], v[30:31], v[24:25], v[30:31] neg_lo:[1,0,0] neg_hi:[1,0,0]
	v_rcp_f32_e32 v49, v49
	v_cndmask_b32_e32 v25, v40, v26, vcc
	v_cmp_gt_f32_e32 vcc, 0, v36
	v_and_b32_e32 v40, 0x7fffffff, v44
	v_pk_mul_f32 v[20:21], v[20:21], v[142:143] op_sel_hi:[1,0]
	v_cndmask_b32_e32 v24, v46, v38, vcc
	v_cmp_gt_f32_e32 vcc, 0, v31
	v_pk_fma_f32 v[30:31], v[48:49], s[0:1], v[28:29] op_sel_hi:[1,0,0]
	v_pk_mul_f32 v[54:55], v[16:17], v[142:143] op_sel_hi:[1,0]
	v_cndmask_b32_e32 v27, v41, v27, vcc
	v_cmp_gt_f32_e32 vcc, 0, v37
	v_and_b32_e32 v41, 0x7fffffff, v45
	v_pk_fma_f32 v[30:31], v[48:49], v[30:31], s[2:3] op_sel_hi:[1,1,0]
	v_cndmask_b32_e32 v26, v47, v39, vcc
	v_pk_mul_f32 v[38:39], v[42:43], v[42:43]
	v_pk_fma_f32 v[40:41], v[40:41], s[56:57], 1.0 op_sel_hi:[1,0,0]
	v_pk_mul_f32 v[38:39], v[38:39], s[86:87] op_sel_hi:[1,0]
	v_pk_fma_f32 v[30:31], v[48:49], v[30:31], s[4:5] op_sel_hi:[1,1,0]
	v_exp_f32_e32 v38, v38
	v_exp_f32_e32 v39, v39
	v_rcp_f32_e32 v40, v40
	v_rcp_f32_e32 v41, v41
	v_pk_fma_f32 v[30:31], v[48:49], v[30:31], s[88:89] op_sel_hi:[1,1,0]
	v_pk_mul_f32 v[36:37], v[44:45], v[44:45]
	v_pk_mul_f32 v[30:31], v[48:49], v[30:31]
	v_pk_mul_f32 v[36:37], v[36:37], s[86:87] op_sel_hi:[1,0]
	v_pk_mul_f32 v[30:31], v[38:39], v[30:31]
	v_exp_f32_e32 v36, v36
	v_pk_mul_f32 v[38:39], v[42:43], v[30:31]
	v_pk_fma_f32 v[46:47], v[42:43], v[30:31], v[42:43] neg_lo:[1,0,0] neg_hi:[1,0,0]
	v_pk_fma_f32 v[30:31], v[40:41], s[0:1], v[28:29] op_sel_hi:[1,0,0]
	v_exp_f32_e32 v37, v37
	v_pk_fma_f32 v[30:31], v[40:41], v[30:31], s[2:3] op_sel_hi:[1,1,0]
	v_pk_mul_f32 v[22:23], v[22:23], v[142:143] op_sel_hi:[1,0]
	v_pk_fma_f32 v[30:31], v[40:41], v[30:31], s[4:5] op_sel_hi:[1,1,0]
	v_and_b32_e32 v57, 0x7fffffff, v23
	v_pk_fma_f32 v[30:31], v[40:41], v[30:31], s[88:89] op_sel_hi:[1,1,0]
	v_and_b32_e32 v56, 0x7fffffff, v22
	v_pk_mul_f32 v[30:31], v[40:41], v[30:31]
	v_pk_fma_f32 v[56:57], v[56:57], s[56:57], 1.0 op_sel_hi:[1,0,0]
	v_pk_mul_f32 v[30:31], v[36:37], v[30:31]
	v_and_b32_e32 v37, 0x7fffffff, v21
	v_and_b32_e32 v36, 0x7fffffff, v20
	v_pk_fma_f32 v[36:37], v[36:37], s[56:57], 1.0 op_sel_hi:[1,0,0]
	v_rcp_f32_e32 v56, v56
	v_rcp_f32_e32 v36, v36
	v_rcp_f32_e32 v37, v37
	v_rcp_f32_e32 v57, v57
	v_pk_mul_f32 v[52:53], v[18:19], v[142:143] op_sel_hi:[1,0]
	v_pk_mul_f32 v[18:19], v[22:23], v[22:23]
	v_pk_fma_f32 v[16:17], v[36:37], s[0:1], v[28:29] op_sel_hi:[1,0,0]
	v_pk_mul_f32 v[18:19], v[18:19], s[86:87] op_sel_hi:[1,0]
	v_pk_fma_f32 v[16:17], v[36:37], v[16:17], s[2:3] op_sel_hi:[1,1,0]
	v_exp_f32_e32 v18, v18
	v_pk_fma_f32 v[16:17], v[36:37], v[16:17], s[4:5] op_sel_hi:[1,1,0]
	v_exp_f32_e32 v19, v19
	v_pk_fma_f32 v[16:17], v[36:37], v[16:17], s[88:89] op_sel_hi:[1,1,0]
	v_and_b32_e32 v61, 0x7fffffff, v55
	v_pk_mul_f32 v[16:17], v[36:37], v[16:17]
	v_pk_mul_f32 v[36:37], v[20:21], v[20:21]
	v_and_b32_e32 v60, 0x7fffffff, v54
	v_pk_mul_f32 v[36:37], v[36:37], s[86:87] op_sel_hi:[1,0]
	v_pk_fma_f32 v[60:61], v[60:61], s[56:57], 1.0 op_sel_hi:[1,0,0]
	v_exp_f32_e32 v36, v36
	v_exp_f32_e32 v37, v37
	v_pk_mul_f32 v[48:49], v[44:45], v[30:31]
	v_pk_fma_f32 v[50:51], v[44:45], v[30:31], v[44:45] neg_lo:[1,0,0] neg_hi:[1,0,0]
	v_cmp_gt_f32_e32 vcc, 0, v45
	v_pk_mul_f32 v[16:17], v[36:37], v[16:17]
	v_rcp_f32_e32 v60, v60
	v_pk_mul_f32 v[36:37], v[20:21], v[16:17]
	v_pk_fma_f32 v[58:59], v[20:21], v[16:17], v[20:21] neg_lo:[1,0,0] neg_hi:[1,0,0]
	v_pk_fma_f32 v[16:17], v[56:57], s[0:1], v[28:29] op_sel_hi:[1,0,0]
	v_rcp_f32_e32 v61, v61
	v_pk_fma_f32 v[16:17], v[56:57], v[16:17], s[2:3] op_sel_hi:[1,1,0]
	v_cndmask_b32_e32 v30, v51, v49, vcc
	v_pk_fma_f32 v[16:17], v[56:57], v[16:17], s[4:5] op_sel_hi:[1,1,0]
	v_cmp_gt_f32_e32 vcc, 0, v22
	v_pk_fma_f32 v[16:17], v[56:57], v[16:17], s[88:89] op_sel_hi:[1,1,0]
	v_add_u32_e32 v32, 0xa0, v140
	v_pk_mul_f32 v[16:17], v[56:57], v[16:17]
	v_ashrrev_i32_e32 v33, 31, v32
	v_pk_mul_f32 v[16:17], v[18:19], v[16:17]
	s_waitcnt lgkmcnt(0)
; __device__ __forceinline__ u32x4 pack8(const f32x4& a, const f32x4& b) { u32x4 w; w.x = cvt_pk_bf16(a[0], a[1]); w.y = cvt_pk_bf16(a[2], a[3]); w.z = cvt_pk_bf16(b[0], b[1]); w.w = cvt_pk_bf16(b[2], b[3]); return w; }
;     __device__ __forceinline__ void operator()(const f32x4 (&acc)[2][2][4][2], const Unit& u, int ui, int wr, int wc, int fr, int fq) const {
;     ...
;             for (int m = 0; m < 4; ++m) { const float r = rs[ai][m]; const int row = row0 + ai * HALF + m * 16; bf16_t* rowp = Z + (size_t)row * 2048 + col0; float s1 = 0.f, s2 = 0.f;
; #pragma unroll
;                 for (int bj = 0; bj < 2; ++bj) { const f32x4 v0 = acc[ai][bj][m][0] * r, v1 = acc[ai][bj][m][1] * r;
;                     const f32x2 a = gelu_pk((f32x2){v0[0], v0[1]}), b = gelu_pk((f32x2){v0[2], v0[3]}), c = gelu_pk((f32x2){v1[0], v1[1]}), d = gelu_pk((f32x2){v1[2], v1[3]});
;                     const f32x4 z0 = (f32x4){a.x, a.y, b.x, b.y}, z1 = (f32x4){c.x, c.y, d.x, d.y};
;                     *(u32x4*)(rowp + bj * HALF) = pack8(z0, z1);
;                     s1 += (z0[0] + z0[1]) + (z0[2] + z0[3]) + (z1[0] + z1[1]) + (z1[2] + z1[3]);
;                     s2 += (z0[0] * z0[0] + z0[1] * z0[1]) + (z0[2] * z0[2] + z0[3] * z0[3]) + (z1[0] * z1[0] + z1[1] * z1[1]) + (z1[2] * z1[2] + z1[3] * z1[3]); }
;                 if (u.pn >= 4) { s1 += __shfl_xor(s1, 16); s1 += __shfl_xor(s1, 32); s2 += __shfl_xor(s2, 16); s2 += __shfl_xor(s2, 32);
;                     if (fq == 0) vst[(size_t)row * 16 + (u.pn - 4) * 4 + wc] = (f32x2){s1, s2}; } }
	v_lshlrev_b64 v[34:35], 12, v[32:33]
	v_pk_mul_f32 v[18:19], v[22:23], v[16:17]
	v_pk_fma_f32 v[56:57], v[22:23], v[16:17], v[22:23] neg_lo:[1,0,0] neg_hi:[1,0,0]
	v_lshl_add_u64 v[34:35], s[20:21], 0, v[34:35]
	v_cndmask_b32_e32 v17, v56, v18, vcc
	v_cmp_gt_f32_e32 vcc, 0, v20
	v_lshl_add_u64 v[34:35], v[162:163], 1, v[34:35]
	v_cvt_pk_bf16_f32 v40, v24, v26
	v_cvt_pk_bf16_f32 v41, v25, v27
	s_nop 0
	v_cndmask_b32_e32 v16, v58, v36, vcc
	v_cmp_gt_f32_e32 vcc, 0, v23
	v_pk_mul_f32 v[22:23], v[54:55], v[54:55]
	s_nop 0
	v_cndmask_b32_e32 v19, v57, v19, vcc
	v_cmp_gt_f32_e32 vcc, 0, v21
	v_pk_fma_f32 v[20:21], v[60:61], s[0:1], v[28:29] op_sel_hi:[1,0,0]
	v_pk_mul_f32 v[22:23], v[22:23], s[86:87] op_sel_hi:[1,0]
	v_pk_fma_f32 v[20:21], v[60:61], v[20:21], s[2:3] op_sel_hi:[1,1,0]
	v_exp_f32_e32 v22, v22
	v_exp_f32_e32 v23, v23
	v_pk_fma_f32 v[20:21], v[60:61], v[20:21], s[4:5] op_sel_hi:[1,1,0]
	v_cndmask_b32_e32 v18, v59, v37, vcc
	v_pk_fma_f32 v[20:21], v[60:61], v[20:21], s[88:89] op_sel_hi:[1,1,0]
	v_cmp_gt_f32_e32 vcc, 0, v42
	v_pk_mul_f32 v[20:21], v[60:61], v[20:21]
	v_pk_mul_f32 v[56:57], v[52:53], v[52:53]
	v_pk_mul_f32 v[20:21], v[22:23], v[20:21]
	v_cndmask_b32_e32 v22, v46, v38, vcc
	v_pk_mul_f32 v[36:37], v[54:55], v[20:21]
	v_pk_fma_f32 v[58:59], v[54:55], v[20:21], v[54:55] neg_lo:[1,0,0] neg_hi:[1,0,0]
	v_cmp_gt_f32_e32 vcc, 0, v54
	v_and_b32_e32 v38, 0x7fffffff, v52
	s_nop 0
	v_cndmask_b32_e32 v23, v58, v36, vcc
	v_cmp_gt_f32_e32 vcc, 0, v43
	s_nop 1
	v_cndmask_b32_e32 v36, v47, v39, vcc
	v_and_b32_e32 v39, 0x7fffffff, v53
	v_pk_fma_f32 v[38:39], v[38:39], s[56:57], 1.0 op_sel_hi:[1,0,0]
	v_cmp_gt_f32_e32 vcc, 0, v44
	v_rcp_f32_e32 v44, v38
	v_rcp_f32_e32 v45, v39
	v_cvt_pk_bf16_f32 v42, v22, v36
	v_cndmask_b32_e32 v21, v50, v48, vcc
	v_cvt_pk_bf16_f32 v43, v21, v30
	global_store_dwordx4 v[34:35], v[40:43], off sc1 nt
	v_pk_fma_f32 v[28:29], v[44:45], s[0:1], v[28:29] op_sel_hi:[1,0,0]
	v_cmp_gt_f32_e32 vcc, 0, v55
	v_pk_mul_f32 v[40:41], v[56:57], s[86:87] op_sel_hi:[1,0]
	v_pk_fma_f32 v[28:29], v[44:45], v[28:29], s[2:3] op_sel_hi:[1,1,0]
	v_exp_f32_e32 v40, v40
	v_exp_f32_e32 v41, v41
	v_pk_fma_f32 v[28:29], v[44:45], v[28:29], s[4:5] op_sel_hi:[1,1,0]
	v_cndmask_b32_e32 v38, v59, v37, vcc
	v_pk_fma_f32 v[28:29], v[44:45], v[28:29], s[88:89] op_sel_hi:[1,1,0]
	v_cmp_gt_f32_e32 vcc, 0, v53
	v_pk_mul_f32 v[28:29], v[44:45], v[28:29]
	s_nop 0
	v_pk_mul_f32 v[28:29], v[40:41], v[28:29]
	s_nop 0
	v_pk_mul_f32 v[40:41], v[52:53], v[28:29]
	v_pk_fma_f32 v[28:29], v[52:53], v[28:29], v[52:53] neg_lo:[1,0,0] neg_hi:[1,0,0]
	s_nop 0
	v_cndmask_b32_e32 v29, v29, v41, vcc
	v_cmp_gt_f32_e32 vcc, 0, v52
	s_nop 1
	v_cndmask_b32_e32 v28, v28, v40, vcc
	s_and_b64 vcc, exec, s[12:13]
	v_cvt_pk_bf16_f32 v40, v16, v18
	v_cvt_pk_bf16_f32 v41, v17, v19
	v_cvt_pk_bf16_f32 v42, v23, v38
	v_cvt_pk_bf16_f32 v43, v28, v29
	global_store_dwordx4 v[34:35], v[40:43], off offset:256 sc1 nt
	s_cbranch_vccnz .LBB0_780
	v_mov_b32_e32 v20, v23
	v_mov_b32_e32 v39, v21
	v_pk_add_f32 v[34:35], v[20:21], v[38:39]
	v_pk_mul_f32 v[40:41], v[20:21], v[38:39]
	v_mov_b32_e32 v42, v22
	v_mov_b32_e32 v43, v36
	v_mul_f32_e32 v20, v22, v22
	v_mov_b32_e32 v37, v23
	v_pk_fma_f32 v[42:43], v[42:43], v[42:43], v[20:21] op_sel_hi:[1,1,0]
	v_mul_f32_e32 v20, v28, v28
	v_pk_fma_f32 v[44:45], v[28:29], v[28:29], v[20:21] op_sel_hi:[1,1,0]
	v_mov_b32_e32 v46, v16
	v_mov_b32_e32 v47, v18
	v_mul_f32_e32 v20, v16, v16
	v_pk_add_f32 v[50:51], v[22:23], v[36:37]
	v_pk_mul_f32 v[22:23], v[22:23], v[36:37]
	v_mov_b32_e32 v35, v41
	v_pk_mul_f32 v[40:41], v[26:27], v[26:27]
	v_pk_fma_f32 v[46:47], v[46:47], v[46:47], v[20:21] op_sel_hi:[1,1,0]
	v_mov_b32_e32 v48, v17
	v_mov_b32_e32 v49, v19
	v_mul_f32_e32 v20, v17, v17
	v_mov_b32_e32 v51, v23
	v_pk_mul_f32 v[22:23], v[38:39], v[38:39]
	v_pk_add_f32 v[16:17], v[16:17], v[18:19]
	v_and_b32_e32 v19, 64, v192
	v_pk_fma_f32 v[40:41], v[24:25], v[24:25], v[40:41]
	v_pk_add_f32 v[24:25], v[24:25], v[26:27]
	v_xor_b32_e32 v18, 16, v192
	v_add_u32_e32 v23, 64, v19
	v_pk_fma_f32 v[48:49], v[48:49], v[48:49], v[20:21] op_sel_hi:[1,1,0]
	v_pk_add_f32 v[24:25], v[24:25], v[24:25] op_sel:[0,1] op_sel_hi:[1,0]
	v_cmp_lt_i32_e32 vcc, v18, v23
	v_mul_f32_e32 v52, v30, v30
	v_pk_add_f32 v[40:41], v[40:41], v[40:41] op_sel_hi:[0,1]
	v_cndmask_b32_e32 v18, v192, v18, vcc
	v_mov_b32_e32 v46, v21
	v_mov_b32_e32 v31, v49
	v_mov_b32_e32 v25, v22
	v_pk_add_f32 v[16:17], v[16:17], v[16:17] op_sel:[0,1] op_sel_hi:[1,0]
	v_lshlrev_b32_e32 v26, 2, v18
	v_pk_add_f32 v[18:19], v[46:47], v[30:31]
	v_pk_add_f32 v[20:21], v[50:51], v[24:25]
	v_mov_b32_e32 v42, v28
	v_mov_b32_e32 v40, v29
	v_mov_b32_e32 v17, v52
	v_pk_add_f32 v[18:19], v[20:21], v[18:19]
	v_mov_b32_e32 v147, v45
	v_pk_add_f32 v[20:21], v[42:43], v[40:41]
	v_pk_add_f32 v[16:17], v[34:35], v[16:17]
	v_pk_add_f32 v[18:19], v[18:19], v[146:147]
	v_pk_add_f32 v[16:17], v[16:17], v[20:21]
	v_xor_b32_e32 v20, 32, v192
	v_pk_add_f32 v[16:17], v[16:17], v[18:19]
	ds_bpermute_b32 v18, v26, v16
	ds_bpermute_b32 v19, v26, v17
	v_cmp_lt_i32_e32 vcc, v20, v23
	s_waitcnt lgkmcnt(0)
	v_pk_add_f32 v[16:17], v[16:17], v[18:19]
	v_cndmask_b32_e32 v20, v192, v20, vcc
	v_lshlrev_b32_e32 v20, 2, v20
	ds_bpermute_b32 v18, v20, v16
	ds_bpermute_b32 v19, v20, v17
	s_and_saveexec_b64 s[0:1], s[10:11]
	s_cbranch_execz .LBB0_779
	s_waitcnt lgkmcnt(0)
	v_pk_add_f32 v[16:17], v[16:17], v[18:19]
	v_lshlrev_b64 v[18:19], 7, v[32:33]
	v_lshl_add_u64 v[18:19], s[16:17], 0, v[18:19]
	v_lshl_add_u64 v[18:19], s[38:39], 3, v[18:19]
	s_lshl_b32 s88, s44, 3
	v_lshl_add_u64 v[18:19], v[18:19], 0, s[88:89]
	global_store_dwordx2 v[18:19], v[16:17], off

;     __device__ __forceinline__ void operator()(const f32x4 (&acc)[2][2][4][2], const Unit& u, int ui, int wr, int wc, int fr, int fq) const {
;     ...
;             for (int m = 0; m < 4; ++m) { const float r = rs[ai][m]; const int row = row0 + ai * HALF + m * 16; bf16_t* rowp = Z + (size_t)row * 2048 + col0; float s1 = 0.f, s2 = 0.f;
; #pragma unroll
;                 for (int bj = 0; bj < 2; ++bj) { const f32x4 v0 = acc[ai][bj][m][0] * r, v1 = acc[ai][bj][m][1] * r;
;                     const f32x2 a = gelu_pk((f32x2){v0[0], v0[1]}), b = gelu_pk((f32x2){v0[2], v0[3]}), c = gelu_pk((f32x2){v1[0], v1[1]}), d = gelu_pk((f32x2){v1[2], v1[3]});
.LBB0_780:
	v_mov_b32_e32 v20, v143
	v_pk_mul_f32 v[22:23], v[12:13], v[20:21] op_sel_hi:[1,0]
	s_mov_b32 s0, 0xbf3a00e3
	v_and_b32_e32 v13, 0x7fffffff, v23
	v_and_b32_e32 v12, 0x7fffffff, v22
	v_pk_fma_f32 v[12:13], v[12:13], s[56:57], 1.0 op_sel_hi:[1,0,0]
	v_pk_mul_f32 v[26:27], v[8:9], v[20:21] op_sel_hi:[1,0]
	v_rcp_f32_e32 v24, v12
	v_rcp_f32_e32 v25, v13
	v_mov_b64_e32 v[12:13], s[0:1]
	s_mov_b32 s0, 0x3f07dc22
	s_mov_b32 s88, 0x3e027906
	v_pk_fma_f32 v[8:9], v[24:25], s[0:1], v[12:13] op_sel_hi:[1,0,0]
	v_pk_mul_f32 v[14:15], v[14:15], v[20:21] op_sel_hi:[1,0]
	v_pk_fma_f32 v[8:9], v[24:25], v[8:9], s[2:3] op_sel_hi:[1,1,0]
	v_and_b32_e32 v31, 0x7fffffff, v15
	v_pk_fma_f32 v[8:9], v[24:25], v[8:9], s[4:5] op_sel_hi:[1,1,0]
	v_and_b32_e32 v30, 0x7fffffff, v14
	v_pk_fma_f32 v[8:9], v[24:25], v[8:9], s[88:89] op_sel_hi:[1,1,0]
	v_pk_fma_f32 v[30:31], v[30:31], s[56:57], 1.0 op_sel_hi:[1,0,0]
	v_pk_mul_f32 v[8:9], v[24:25], v[8:9]
	v_pk_mul_f32 v[24:25], v[22:23], v[22:23]
	v_rcp_f32_e32 v30, v30
	v_pk_mul_f32 v[24:25], v[24:25], s[86:87] op_sel_hi:[1,0]
	v_rcp_f32_e32 v31, v31
	v_exp_f32_e32 v24, v24
	v_exp_f32_e32 v25, v25
	v_pk_mul_f32 v[28:29], v[10:11], v[20:21] op_sel_hi:[1,0]
	v_pk_mul_f32 v[10:11], v[14:15], v[14:15]
	v_pk_mul_f32 v[4:5], v[4:5], v[20:21] op_sel_hi:[1,0]
	v_pk_mul_f32 v[8:9], v[24:25], v[8:9]
	v_pk_mul_f32 v[10:11], v[10:11], s[86:87] op_sel_hi:[1,0]
	v_pk_mul_f32 v[24:25], v[22:23], v[8:9]
	v_pk_fma_f32 v[32:33], v[22:23], v[8:9], v[22:23] neg_lo:[1,0,0] neg_hi:[1,0,0]
	v_pk_fma_f32 v[8:9], v[30:31], s[0:1], v[12:13] op_sel_hi:[1,0,0]
	v_exp_f32_e32 v10, v10
	v_pk_fma_f32 v[8:9], v[30:31], v[8:9], s[2:3] op_sel_hi:[1,1,0]
	v_exp_f32_e32 v11, v11
	v_and_b32_e32 v37, 0x7fffffff, v5
	v_and_b32_e32 v36, 0x7fffffff, v4
	v_pk_fma_f32 v[8:9], v[30:31], v[8:9], s[4:5] op_sel_hi:[1,1,0]
	v_pk_fma_f32 v[36:37], v[36:37], s[56:57], 1.0 op_sel_hi:[1,0,0]
	v_pk_fma_f32 v[8:9], v[30:31], v[8:9], s[88:89] op_sel_hi:[1,1,0]
	v_rcp_f32_e32 v36, v36
	v_rcp_f32_e32 v37, v37
	v_pk_mul_f32 v[8:9], v[30:31], v[8:9]
	v_and_b32_e32 v35, 0x7fffffff, v27
	v_pk_mul_f32 v[8:9], v[10:11], v[8:9]
	v_and_b32_e32 v34, 0x7fffffff, v26
	v_pk_mul_f32 v[10:11], v[14:15], v[8:9]
	v_pk_fma_f32 v[30:31], v[14:15], v[8:9], v[14:15] neg_lo:[1,0,0] neg_hi:[1,0,0]
	v_cmp_gt_f32_e32 vcc, 0, v14
	v_pk_fma_f32 v[34:35], v[34:35], s[56:57], 1.0 op_sel_hi:[1,0,0]
	v_pk_mul_f32 v[6:7], v[6:7], v[20:21] op_sel_hi:[1,0]
	v_cndmask_b32_e32 v9, v30, v10, vcc
	v_cmp_gt_f32_e32 vcc, 0, v22
	v_rcp_f32_e32 v34, v34
	v_rcp_f32_e32 v35, v35
	v_pk_mul_f32 v[38:39], v[2:3], v[20:21] op_sel_hi:[1,0]
	v_pk_mul_f32 v[20:21], v[0:1], v[20:21] op_sel_hi:[1,0]
	v_pk_fma_f32 v[0:1], v[36:37], s[0:1], v[12:13] op_sel_hi:[1,0,0]
	v_cndmask_b32_e32 v8, v32, v24, vcc
	v_cmp_gt_f32_e32 vcc, 0, v15
	v_pk_fma_f32 v[0:1], v[36:37], v[0:1], s[2:3] op_sel_hi:[1,1,0]
	v_pk_fma_f32 v[14:15], v[34:35], s[0:1], v[12:13] op_sel_hi:[1,0,0]
	v_cndmask_b32_e32 v11, v31, v11, vcc
	v_cmp_gt_f32_e32 vcc, 0, v23
	v_pk_fma_f32 v[0:1], v[36:37], v[0:1], s[4:5] op_sel_hi:[1,1,0]
	v_and_b32_e32 v31, 0x7fffffff, v29
	v_cndmask_b32_e32 v10, v33, v25, vcc
	v_pk_mul_f32 v[24:25], v[26:27], v[26:27]
	v_pk_fma_f32 v[0:1], v[36:37], v[0:1], s[88:89] op_sel_hi:[1,1,0]
	v_pk_mul_f32 v[24:25], v[24:25], s[86:87] op_sel_hi:[1,0]
	v_and_b32_e32 v30, 0x7fffffff, v28
	v_pk_mul_f32 v[0:1], v[36:37], v[0:1]
	v_pk_mul_f32 v[36:37], v[4:5], v[4:5]
	v_pk_fma_f32 v[14:15], v[34:35], v[14:15], s[2:3] op_sel_hi:[1,1,0]
	v_exp_f32_e32 v24, v24
	v_exp_f32_e32 v25, v25
	v_pk_fma_f32 v[30:31], v[30:31], s[56:57], 1.0 op_sel_hi:[1,0,0]
	v_pk_mul_f32 v[36:37], v[36:37], s[86:87] op_sel_hi:[1,0]
	v_and_b32_e32 v41, 0x7fffffff, v7
	v_and_b32_e32 v40, 0x7fffffff, v6
	v_pk_fma_f32 v[14:15], v[34:35], v[14:15], s[4:5] op_sel_hi:[1,1,0]
	v_rcp_f32_e32 v30, v30
	v_rcp_f32_e32 v31, v31
	v_exp_f32_e32 v36, v36
	v_exp_f32_e32 v37, v37
	v_pk_fma_f32 v[40:41], v[40:41], s[56:57], 1.0 op_sel_hi:[1,0,0]
	v_pk_fma_f32 v[14:15], v[34:35], v[14:15], s[88:89] op_sel_hi:[1,1,0]
	v_rcp_f32_e32 v40, v40
	v_rcp_f32_e32 v41, v41
	v_pk_mul_f32 v[14:15], v[34:35], v[14:15]
	v_pk_mul_f32 v[22:23], v[28:29], v[28:29]
	v_pk_mul_f32 v[14:15], v[24:25], v[14:15]
	v_pk_mul_f32 v[22:23], v[22:23], s[86:87] op_sel_hi:[1,0]
	v_pk_mul_f32 v[32:33], v[26:27], v[14:15]
	v_pk_fma_f32 v[34:35], v[26:27], v[14:15], v[26:27] neg_lo:[1,0,0] neg_hi:[1,0,0]
	v_pk_fma_f32 v[14:15], v[30:31], s[0:1], v[12:13] op_sel_hi:[1,0,0]
	v_pk_mul_f32 v[2:3], v[6:7], v[6:7]
	v_pk_mul_f32 v[0:1], v[36:37], v[0:1]
	v_pk_fma_f32 v[14:15], v[30:31], v[14:15], s[2:3] op_sel_hi:[1,1,0]
	v_exp_f32_e32 v22, v22
	v_exp_f32_e32 v23, v23
	v_pk_mul_f32 v[36:37], v[4:5], v[0:1]
	v_pk_fma_f32 v[42:43], v[4:5], v[0:1], v[4:5] neg_lo:[1,0,0] neg_hi:[1,0,0]
	v_pk_fma_f32 v[0:1], v[40:41], s[0:1], v[12:13] op_sel_hi:[1,0,0]
	v_pk_mul_f32 v[2:3], v[2:3], s[86:87] op_sel_hi:[1,0]
	v_pk_fma_f32 v[14:15], v[30:31], v[14:15], s[4:5] op_sel_hi:[1,1,0]
	v_pk_fma_f32 v[0:1], v[40:41], v[0:1], s[2:3] op_sel_hi:[1,1,0]
	v_exp_f32_e32 v2, v2
	v_exp_f32_e32 v3, v3
	v_pk_fma_f32 v[14:15], v[30:31], v[14:15], s[88:89] op_sel_hi:[1,1,0]
	v_pk_fma_f32 v[0:1], v[40:41], v[0:1], s[4:5] op_sel_hi:[1,1,0]
	v_pk_mul_f32 v[14:15], v[30:31], v[14:15]
	v_pk_fma_f32 v[0:1], v[40:41], v[0:1], s[88:89] op_sel_hi:[1,1,0]
	v_and_b32_e32 v45, 0x7fffffff, v21
	v_and_b32_e32 v44, 0x7fffffff, v20
	v_pk_mul_f32 v[14:15], v[22:23], v[14:15]
	v_pk_mul_f32 v[0:1], v[40:41], v[0:1]
	v_pk_fma_f32 v[44:45], v[44:45], s[56:57], 1.0 op_sel_hi:[1,0,0]
	v_pk_mul_f32 v[22:23], v[28:29], v[14:15]
	v_pk_fma_f32 v[30:31], v[28:29], v[14:15], v[28:29] neg_lo:[1,0,0] neg_hi:[1,0,0]
	v_cmp_gt_f32_e32 vcc, 0, v29
	v_pk_mul_f32 v[0:1], v[2:3], v[0:1]
	v_rcp_f32_e32 v44, v44
	v_rcp_f32_e32 v45, v45
	v_cndmask_b32_e32 v14, v31, v23, vcc
	v_pk_mul_f32 v[2:3], v[6:7], v[0:1]
	v_pk_fma_f32 v[40:41], v[6:7], v[0:1], v[6:7] neg_lo:[1,0,0] neg_hi:[1,0,0]
	v_cmp_gt_f32_e32 vcc, 0, v6
	v_and_b32_e32 v23, 0x7fffffff, v39
	v_add_u32_e32 v16, 0xb0, v140
	v_cndmask_b32_e32 v1, v40, v2, vcc
	v_cmp_gt_f32_e32 vcc, 0, v4
	v_ashrrev_i32_e32 v17, 31, v16
	s_waitcnt lgkmcnt(0)
; __device__ __forceinline__ u32x4 pack8(const f32x4& a, const f32x4& b) { u32x4 w; w.x = cvt_pk_bf16(a[0], a[1]); w.y = cvt_pk_bf16(a[2], a[3]); w.z = cvt_pk_bf16(b[0], b[1]); w.w = cvt_pk_bf16(b[2], b[3]); return w; }
; __device__ __forceinline__ f32x2 gelu_pk(f32x2 v) {
;     ...
;     const f32x2 s = (v * v) * (-0.72134752044f);
;     f32x2 e; e.x = __builtin_amdgcn_exp2f(s.x); e.y = __builtin_amdgcn_exp2f(s.y);
;     const f32x2 m = v * (q * e), r = v - m;
;     f32x2 o; o.x = v.x < 0.f ? m.x : r.x; o.y = v.y < 0.f ? m.y : r.y; return o;
;     __device__ __forceinline__ void operator()(const f32x4 (&acc)[2][2][4][2], const Unit& u, int ui, int wr, int wc, int fr, int fq) const {
;     ...
;                 for (int bj = 0; bj < 2; ++bj) { const f32x4 v0 = acc[ai][bj][m][0] * r, v1 = acc[ai][bj][m][1] * r;
;                     const f32x2 a = gelu_pk((f32x2){v0[0], v0[1]}), b = gelu_pk((f32x2){v0[2], v0[3]}), c = gelu_pk((f32x2){v1[0], v1[1]}), d = gelu_pk((f32x2){v1[2], v1[3]});
;                     const f32x4 z0 = (f32x4){a.x, a.y, b.x, b.y}, z1 = (f32x4){c.x, c.y, d.x, d.y};
;                     *(u32x4*)(rowp + bj * HALF) = pack8(z0, z1);
;                     s1 += (z0[0] + z0[1]) + (z0[2] + z0[3]) + (z1[0] + z1[1]) + (z1[2] + z1[3]);
;                     s2 += (z0[0] * z0[0] + z0[1] * z0[1]) + (z0[2] * z0[2] + z0[3] * z0[3]) + (z1[0] * z1[0] + z1[1] * z1[1]) + (z1[2] * z1[2] + z1[3] * z1[3]); }
;                 if (u.pn >= 4) { s1 += __shfl_xor(s1, 16); s1 += __shfl_xor(s1, 32); s2 += __shfl_xor(s2, 16); s2 += __shfl_xor(s2, 32);
;                     if (fq == 0) vst[(size_t)row * 16 + (u.pn - 4) * 4 + wc] = (f32x2){s1, s2}; } }
	v_lshlrev_b64 v[18:19], 12, v[16:17]
	v_cndmask_b32_e32 v0, v42, v36, vcc
	v_cmp_gt_f32_e32 vcc, 0, v7
	v_pk_mul_f32 v[6:7], v[20:21], v[20:21]
	v_lshl_add_u64 v[18:19], s[20:21], 0, v[18:19]
	v_cndmask_b32_e32 v3, v41, v3, vcc
	v_cmp_gt_f32_e32 vcc, 0, v5
	v_pk_fma_f32 v[4:5], v[44:45], s[0:1], v[12:13] op_sel_hi:[1,0,0]
	v_pk_mul_f32 v[6:7], v[6:7], s[86:87] op_sel_hi:[1,0]
	v_pk_fma_f32 v[4:5], v[44:45], v[4:5], s[2:3] op_sel_hi:[1,1,0]
	v_exp_f32_e32 v6, v6
	v_exp_f32_e32 v7, v7
	v_pk_fma_f32 v[4:5], v[44:45], v[4:5], s[4:5] op_sel_hi:[1,1,0]
	v_cndmask_b32_e32 v2, v43, v37, vcc
	v_pk_fma_f32 v[4:5], v[44:45], v[4:5], s[88:89] op_sel_hi:[1,1,0]
	v_cmp_gt_f32_e32 vcc, 0, v26
	v_pk_mul_f32 v[4:5], v[44:45], v[4:5]
	v_lshl_add_u64 v[18:19], v[162:163], 1, v[18:19]
	v_pk_mul_f32 v[4:5], v[6:7], v[4:5]
	v_cndmask_b32_e32 v6, v34, v32, vcc
	v_pk_mul_f32 v[40:41], v[20:21], v[4:5]
	v_pk_fma_f32 v[42:43], v[20:21], v[4:5], v[20:21] neg_lo:[1,0,0] neg_hi:[1,0,0]
	v_cmp_gt_f32_e32 vcc, 0, v20
	v_cvt_pk_bf16_f32 v24, v8, v10
	v_cvt_pk_bf16_f32 v25, v9, v11
	v_pk_mul_f32 v[36:37], v[38:39], v[38:39]
	s_nop 0
	v_cndmask_b32_e32 v7, v42, v40, vcc
	v_cmp_gt_f32_e32 vcc, 0, v27
	s_nop 1
	v_cndmask_b32_e32 v20, v35, v33, vcc
	v_cmp_gt_f32_e32 vcc, 0, v28
	v_cvt_pk_bf16_f32 v26, v6, v20
	s_nop 1
	v_cndmask_b32_e32 v5, v30, v22, vcc
	v_and_b32_e32 v22, 0x7fffffff, v38
	v_pk_fma_f32 v[22:23], v[22:23], s[56:57], 1.0 op_sel_hi:[1,0,0]
	v_cvt_pk_bf16_f32 v27, v5, v14
	global_store_dwordx4 v[18:19], v[24:27], off sc1 nt
	v_rcp_f32_e32 v28, v22
	v_rcp_f32_e32 v29, v23
	v_pk_mul_f32 v[24:25], v[36:37], s[86:87] op_sel_hi:[1,0]
	v_cmp_gt_f32_e32 vcc, 0, v21
	v_exp_f32_e32 v24, v24
	v_pk_fma_f32 v[12:13], v[28:29], s[0:1], v[12:13] op_sel_hi:[1,0,0]
	v_exp_f32_e32 v25, v25
	v_pk_fma_f32 v[12:13], v[28:29], v[12:13], s[2:3] op_sel_hi:[1,1,0]
	v_cndmask_b32_e32 v22, v43, v41, vcc
	v_pk_fma_f32 v[12:13], v[28:29], v[12:13], s[4:5] op_sel_hi:[1,1,0]
	v_cmp_gt_f32_e32 vcc, 0, v39
	v_pk_fma_f32 v[12:13], v[28:29], v[12:13], s[88:89] op_sel_hi:[1,1,0]
	s_nop 0
	v_pk_mul_f32 v[12:13], v[28:29], v[12:13]
	s_nop 0
	v_pk_mul_f32 v[12:13], v[24:25], v[12:13]
	s_nop 0
	v_pk_mul_f32 v[24:25], v[38:39], v[12:13]
	v_pk_fma_f32 v[12:13], v[38:39], v[12:13], v[38:39] neg_lo:[1,0,0] neg_hi:[1,0,0]
	s_nop 0
	v_cndmask_b32_e32 v13, v13, v25, vcc
	v_cmp_gt_f32_e32 vcc, 0, v38
	s_nop 1
	v_cndmask_b32_e32 v12, v12, v24, vcc
	s_and_b64 vcc, exec, s[12:13]
	v_cvt_pk_bf16_f32 v24, v0, v2
	v_cvt_pk_bf16_f32 v25, v1, v3
	v_cvt_pk_bf16_f32 v26, v7, v22
	v_cvt_pk_bf16_f32 v27, v12, v13
	global_store_dwordx4 v[18:19], v[24:27], off offset:256 sc1 nt
	s_cbranch_vccnz .LBB0_784
	v_mov_b32_e32 v4, v7
	v_mov_b32_e32 v23, v5
	v_pk_add_f32 v[18:19], v[4:5], v[22:23]
	v_pk_mul_f32 v[24:25], v[4:5], v[22:23]
	v_mov_b32_e32 v26, v6
	v_mov_b32_e32 v27, v20
	v_mul_f32_e32 v4, v6, v6
	v_mov_b32_e32 v21, v7
	v_pk_fma_f32 v[26:27], v[26:27], v[26:27], v[4:5] op_sel_hi:[1,1,0]
	v_mul_f32_e32 v4, v12, v12
	v_pk_fma_f32 v[28:29], v[12:13], v[12:13], v[4:5] op_sel_hi:[1,1,0]
	v_mov_b32_e32 v30, v0
	v_mov_b32_e32 v31, v2
	v_mul_f32_e32 v4, v0, v0
	v_pk_add_f32 v[34:35], v[6:7], v[20:21]
	v_pk_mul_f32 v[6:7], v[6:7], v[20:21]
	v_mov_b32_e32 v19, v25
	v_pk_mul_f32 v[24:25], v[10:11], v[10:11]
	v_pk_fma_f32 v[30:31], v[30:31], v[30:31], v[4:5] op_sel_hi:[1,1,0]
	v_mov_b32_e32 v32, v1
	v_mov_b32_e32 v33, v3
	v_mul_f32_e32 v4, v1, v1
	v_mov_b32_e32 v35, v7
	v_pk_mul_f32 v[6:7], v[22:23], v[22:23]
	v_pk_add_f32 v[0:1], v[0:1], v[2:3]
	v_and_b32_e32 v3, 64, v192
	v_pk_fma_f32 v[24:25], v[8:9], v[8:9], v[24:25]
	v_pk_add_f32 v[8:9], v[8:9], v[10:11]
	v_xor_b32_e32 v2, 16, v192
	v_add_u32_e32 v7, 64, v3
	v_pk_fma_f32 v[32:33], v[32:33], v[32:33], v[4:5] op_sel_hi:[1,1,0]
	v_pk_add_f32 v[8:9], v[8:9], v[8:9] op_sel:[0,1] op_sel_hi:[1,0]
	v_cmp_lt_i32_e32 vcc, v2, v7
	v_mul_f32_e32 v36, v14, v14
	v_pk_add_f32 v[24:25], v[24:25], v[24:25] op_sel_hi:[0,1]
	v_cndmask_b32_e32 v2, v192, v2, vcc
	v_mov_b32_e32 v30, v5
	v_mov_b32_e32 v15, v33
	v_mov_b32_e32 v9, v6
	v_pk_add_f32 v[0:1], v[0:1], v[0:1] op_sel:[0,1] op_sel_hi:[1,0]
	v_lshlrev_b32_e32 v10, 2, v2
	v_pk_add_f32 v[2:3], v[30:31], v[14:15]
	v_pk_add_f32 v[4:5], v[34:35], v[8:9]
	v_mov_b32_e32 v26, v12
	v_mov_b32_e32 v24, v13
	v_mov_b32_e32 v1, v36
	v_pk_add_f32 v[2:3], v[4:5], v[2:3]
	v_mov_b32_e32 v147, v29
	v_pk_add_f32 v[4:5], v[26:27], v[24:25]
	v_pk_add_f32 v[0:1], v[18:19], v[0:1]
	v_pk_add_f32 v[2:3], v[2:3], v[146:147]
	v_pk_add_f32 v[0:1], v[0:1], v[4:5]
	v_xor_b32_e32 v4, 32, v192
	v_pk_add_f32 v[0:1], v[0:1], v[2:3]
	ds_bpermute_b32 v2, v10, v0
	ds_bpermute_b32 v3, v10, v1
	v_cmp_lt_i32_e32 vcc, v4, v7
	s_waitcnt lgkmcnt(0)
	v_pk_add_f32 v[0:1], v[0:1], v[2:3]
	v_cndmask_b32_e32 v4, v192, v4, vcc
	v_lshlrev_b32_e32 v4, 2, v4
	ds_bpermute_b32 v2, v4, v0
	ds_bpermute_b32 v3, v4, v1
	s_and_saveexec_b64 s[0:1], s[10:11]
	s_cbranch_execz .LBB0_783
	s_waitcnt lgkmcnt(0)
	v_pk_add_f32 v[0:1], v[0:1], v[2:3]
	v_lshlrev_b64 v[2:3], 7, v[16:17]
	v_lshl_add_u64 v[2:3], s[16:17], 0, v[2:3]
	v_lshl_add_u64 v[2:3], s[38:39], 3, v[2:3]
	s_lshl_b32 s88, s44, 3
	v_lshl_add_u64 v[2:3], v[2:3], 0, s[88:89]
	global_store_dwordx2 v[2:3], v[0:1], off

; __device__ __forceinline__ unsigned cvt_pk_bf16(float lo, float hi) { unsigned r; asm volatile("v_cvt_pk_bf16_f32 %0, %1, %2" : "=v"(r) : "v"(lo), "v"(hi)); return r; }
; __device__ __forceinline__ u32x4 pack8(const f32x4& a, const f32x4& b) { u32x4 w; w.x = cvt_pk_bf16(a[0], a[1]); w.y = cvt_pk_bf16(a[2], a[3]); w.z = cvt_pk_bf16(b[0], b[1]); w.w = cvt_pk_bf16(b[2], b[3]); return w; }
;     __device__ __forceinline__ void operator()(const f32x4 (&acc)[2][2][4][2], const Unit& u, int ui, int wr, int wc, int fr, int fq) const {
;     ...
;             for (int m = 0; m < 4; ++m) rs[ai][m] = row_rstd(lds, ui, ai * HALF + wr * 64 + m * 16 + fr);
;         if (u.pn < 2) {
; #pragma unroll
;             for (int ai = 0; ai < 2; ++ai)
; #pragma unroll
;                 for (int m = 0; m < 4; ++m) { const float r = rs[ai][m]; bf16_t* rowp = UG + (size_t)(row0 + ai * HALF + m * 16) * 1024 + u.pn * BM + cw;
; #pragma unroll
;                     for (int bj = 0; bj < 2; ++bj) *(u32x4*)(rowp + bj * HALF) = pack8(acc[ai][bj][m][0] * r, acc[ai][bj][m][1] * r); }
;         } else {
; #pragma unroll
;             for (int ai = 0; ai < 2; ++ai)
; #pragma unroll
;                 for (int m = 0; m < 4; ++m) { const float r = rs[ai][m]; bf16_t* rowp = UG + (size_t)(row0 + ai * HALF + m * 16) * 1024 + 512 + (u.pn - 2) * HALF + cw;
;                     const float c1 = r * -1.44269504089f; u32x4 w;
; #pragma unroll
;                     for (int n = 0; n < 2; ++n)
; #pragma unroll
;                         for (int p = 0; p < 2; ++p) { const f32x2 av = (f32x2){acc[ai][0][m][n][2 * p], acc[ai][0][m][n][2 * p + 1]}, gt = (f32x2){acc[ai][1][m][n][2 * p], acc[ai][1][m][n][2 * p + 1]};
;                             const f32x2 t = gt * c1; f32x2 d; d.x = __builtin_amdgcn_exp2f(t.x); d.y = __builtin_amdgcn_exp2f(t.y); d = d + 1.0f;
;                             f32x2 q; q.x = __builtin_amdgcn_rcpf(d.x); q.y = __builtin_amdgcn_rcpf(d.y);
;                             const f32x2 hh = av * (q * r); w[2 * n + p] = cvt_pk_bf16(hh.x, hh.y); }
;                     *(u32x4*)rowp = w; }
.LBB0_795:
	v_mov_b32_e32 v140, v147
	v_mov_b32_e32 v167, v172
	s_mov_b64 s[0:1], -1
	v_add_u32_e32 v140, s35, v140
	v_lshl_add_u32 v166, s45, 8, v140
	v_lshlrev_b32_e32 v140, 2, v140
	v_lshl_add_u32 v140, s47, 10, v140
	v_add_u32_e32 v140, 0x20400, v140
	ds_read2_b32 v[164:165], v140 offset1:16
	ds_read2_b32 v[162:163], v140 offset0:32 offset1:48
	ds_read2_b32 v[142:143], v140 offset0:128 offset1:144
	ds_read2_b32 v[140:141], v140 offset0:160 offset1:176
	v_lshl_add_u32 v168, v167, 3, s36
	s_cmp_lt_i32 s44, 2
	v_ashrrev_i32_e32 v169, 31, v168
	v_ashrrev_i32_e32 v167, 31, v166
	s_cbranch_scc1 .LBB0_798
	s_waitcnt lgkmcnt(0)
	v_mul_f32_e32 v180, 0xbfb8aa3b, v164
	v_pk_mul_f32 v[176:177], v[116:117], v[180:181] op_sel_hi:[1,0]
	v_pk_mul_f32 v[178:179], v[118:119], v[180:181] op_sel_hi:[1,0]
	v_exp_f32_e32 v176, v176
	v_exp_f32_e32 v177, v177
	v_exp_f32_e32 v178, v178
	v_exp_f32_e32 v179, v179
	s_lshl_b32 s0, s44, 7
	v_pk_add_f32 v[176:177], v[176:177], 1.0 op_sel_hi:[1,0]
	v_lshlrev_b64 v[170:171], 11, v[166:167]
	v_pk_add_f32 v[178:179], v[178:179], 1.0 op_sel_hi:[1,0]
	v_rcp_f32_e32 v176, v176
	v_rcp_f32_e32 v177, v177
	v_rcp_f32_e32 v178, v178
	v_rcp_f32_e32 v179, v179
	s_add_i32 s88, s0, 0xffffff00
	v_pk_mul_f32 v[176:177], v[164:165], v[176:177] op_sel_hi:[0,1]
	v_pk_mul_f32 v[176:177], v[124:125], v[176:177]
	v_pk_mul_f32 v[178:179], v[164:165], v[178:179] op_sel_hi:[0,1]
	v_pk_mul_f32 v[178:179], v[126:127], v[178:179]
	v_cvt_pk_bf16_f32 v176, v176, v177
	v_lshl_add_u64 v[170:171], s[20:21], 0, v[170:171]
	v_cvt_pk_bf16_f32 v177, v178, v179
	v_pk_mul_f32 v[178:179], v[108:109], v[180:181] op_sel_hi:[1,0]
	v_pk_mul_f32 v[180:181], v[110:111], v[180:181] op_sel_hi:[1,0]
	v_exp_f32_e32 v178, v178
	v_exp_f32_e32 v179, v179
	v_exp_f32_e32 v180, v180
	v_exp_f32_e32 v181, v181
	v_lshl_add_u64 v[170:171], s[88:89], 1, v[170:171]
	v_pk_add_f32 v[178:179], v[178:179], 1.0 op_sel_hi:[1,0]
	v_lshl_add_u64 v[170:171], v[168:169], 1, v[170:171]
	v_pk_add_f32 v[180:181], v[180:181], 1.0 op_sel_hi:[1,0]
	v_rcp_f32_e32 v178, v178
	v_rcp_f32_e32 v179, v179
	v_rcp_f32_e32 v180, v180
	v_rcp_f32_e32 v181, v181
	v_mov_b32_e32 v182, v165
	v_pk_mul_f32 v[178:179], v[164:165], v[178:179] op_sel_hi:[0,1]
	v_pk_mul_f32 v[178:179], v[120:121], v[178:179]
	v_pk_mul_f32 v[180:181], v[164:165], v[180:181] op_sel_hi:[0,1]
	v_pk_mul_f32 v[180:181], v[122:123], v[180:181]
	v_cvt_pk_bf16_f32 v178, v178, v179
	s_mov_b32 s0, 0x8000
	v_cvt_pk_bf16_f32 v179, v180, v181
	v_mul_f32_e32 v180, 0xbfb8aa3b, v165
	global_store_dwordx4 v[170:171], v[176:179], off offset:1024 sc1 nt
	s_nop 1
	v_pk_mul_f32 v[176:177], v[100:101], v[180:181] op_sel_hi:[1,0]
	v_pk_mul_f32 v[178:179], v[102:103], v[180:181] op_sel_hi:[1,0]
	v_exp_f32_e32 v176, v176
	v_exp_f32_e32 v177, v177
	v_exp_f32_e32 v178, v178
	v_exp_f32_e32 v179, v179
	v_pk_add_f32 v[176:177], v[176:177], 1.0 op_sel_hi:[1,0]
	s_nop 0
	v_rcp_f32_e32 v176, v176
	v_pk_add_f32 v[178:179], v[178:179], 1.0 op_sel_hi:[1,0]
	v_rcp_f32_e32 v177, v177
	v_rcp_f32_e32 v178, v178
	v_rcp_f32_e32 v179, v179
	v_pk_mul_f32 v[176:177], v[182:183], v[176:177] op_sel_hi:[0,1]
	v_pk_mul_f32 v[176:177], v[112:113], v[176:177]
	v_pk_mul_f32 v[178:179], v[182:183], v[178:179] op_sel_hi:[0,1]
	v_pk_mul_f32 v[178:179], v[114:115], v[178:179]
	v_cvt_pk_bf16_f32 v176, v176, v177
	s_nop 0
	v_cvt_pk_bf16_f32 v177, v178, v179
	v_pk_mul_f32 v[178:179], v[92:93], v[180:181] op_sel_hi:[1,0]
	v_pk_mul_f32 v[180:181], v[94:95], v[180:181] op_sel_hi:[1,0]
	v_exp_f32_e32 v178, v178
	v_exp_f32_e32 v179, v179
	v_exp_f32_e32 v180, v180
	v_exp_f32_e32 v181, v181
	v_pk_add_f32 v[178:179], v[178:179], 1.0 op_sel_hi:[1,0]
	s_nop 0
	v_rcp_f32_e32 v178, v178
	v_pk_add_f32 v[180:181], v[180:181], 1.0 op_sel_hi:[1,0]
	v_rcp_f32_e32 v179, v179
	v_rcp_f32_e32 v180, v180
	v_rcp_f32_e32 v181, v181
	v_pk_mul_f32 v[178:179], v[182:183], v[178:179] op_sel_hi:[0,1]
	v_pk_mul_f32 v[178:179], v[104:105], v[178:179]
	v_pk_mul_f32 v[180:181], v[182:183], v[180:181] op_sel_hi:[0,1]
	v_pk_mul_f32 v[180:181], v[106:107], v[180:181]
	v_cvt_pk_bf16_f32 v178, v178, v179
	v_mov_b32_e32 v182, v163
	v_cvt_pk_bf16_f32 v179, v180, v181
	v_add_co_u32_e32 v180, vcc, s0, v170
	s_mov_b32 s0, 0x10000
	s_nop 0
	v_addc_co_u32_e32 v181, vcc, 0, v171, vcc
	global_store_dwordx4 v[180:181], v[176:179], off offset:1024 sc1 nt
	v_mul_f32_e32 v180, 0xbfb8aa3b, v162
	s_nop 0
	v_pk_mul_f32 v[176:177], v[84:85], v[180:181] op_sel_hi:[1,0]
	v_pk_mul_f32 v[178:179], v[86:87], v[180:181] op_sel_hi:[1,0]
	v_exp_f32_e32 v176, v176
	v_exp_f32_e32 v177, v177
	v_exp_f32_e32 v178, v178
	v_exp_f32_e32 v179, v179
	v_pk_add_f32 v[176:177], v[176:177], 1.0 op_sel_hi:[1,0]
	s_nop 0
	v_rcp_f32_e32 v176, v176
	v_pk_add_f32 v[178:179], v[178:179], 1.0 op_sel_hi:[1,0]
	v_rcp_f32_e32 v177, v177
	v_rcp_f32_e32 v178, v178
	v_rcp_f32_e32 v179, v179
	v_pk_mul_f32 v[176:177], v[162:163], v[176:177] op_sel_hi:[0,1]
	v_pk_mul_f32 v[176:177], v[96:97], v[176:177]
	v_pk_mul_f32 v[178:179], v[162:163], v[178:179] op_sel_hi:[0,1]
	v_pk_mul_f32 v[178:179], v[98:99], v[178:179]
	v_cvt_pk_bf16_f32 v176, v176, v177
	s_nop 0
	v_cvt_pk_bf16_f32 v177, v178, v179
	v_pk_mul_f32 v[178:179], v[76:77], v[180:181] op_sel_hi:[1,0]
	v_pk_mul_f32 v[180:181], v[78:79], v[180:181] op_sel_hi:[1,0]
	v_exp_f32_e32 v178, v178
	v_exp_f32_e32 v179, v179
	v_exp_f32_e32 v180, v180
	v_exp_f32_e32 v181, v181
	v_pk_add_f32 v[178:179], v[178:179], 1.0 op_sel_hi:[1,0]
	s_nop 0
	v_rcp_f32_e32 v178, v178
	v_pk_add_f32 v[180:181], v[180:181], 1.0 op_sel_hi:[1,0]
	v_rcp_f32_e32 v179, v179
	v_rcp_f32_e32 v180, v180
	v_rcp_f32_e32 v181, v181
	v_pk_mul_f32 v[178:179], v[162:163], v[178:179] op_sel_hi:[0,1]
; __device__ __forceinline__ unsigned cvt_pk_bf16(float lo, float hi) { unsigned r; asm volatile("v_cvt_pk_bf16_f32 %0, %1, %2" : "=v"(r) : "v"(lo), "v"(hi)); return r; }
;     __device__ __forceinline__ void operator()(const f32x4 (&acc)[2][2][4][2], const Unit& u, int ui, int wr, int wc, int fr, int fq) const {
;     ...
;                 for (int m = 0; m < 4; ++m) { const float r = rs[ai][m]; bf16_t* rowp = UG + (size_t)(row0 + ai * HALF + m * 16) * 1024 + 512 + (u.pn - 2) * HALF + cw;
;                     const float c1 = r * -1.44269504089f; u32x4 w;
; #pragma unroll
;                     for (int n = 0; n < 2; ++n)
; #pragma unroll
;                         for (int p = 0; p < 2; ++p) { const f32x2 av = (f32x2){acc[ai][0][m][n][2 * p], acc[ai][0][m][n][2 * p + 1]}, gt = (f32x2){acc[ai][1][m][n][2 * p], acc[ai][1][m][n][2 * p + 1]};
;                             const f32x2 t = gt * c1; f32x2 d; d.x = __builtin_amdgcn_exp2f(t.x); d.y = __builtin_amdgcn_exp2f(t.y); d = d + 1.0f;
;                             f32x2 q; q.x = __builtin_amdgcn_rcpf(d.x); q.y = __builtin_amdgcn_rcpf(d.y);
;                             const f32x2 hh = av * (q * r); w[2 * n + p] = cvt_pk_bf16(hh.x, hh.y); }
;                     *(u32x4*)rowp = w; }
	v_pk_mul_f32 v[178:179], v[88:89], v[178:179]
	v_pk_mul_f32 v[180:181], v[162:163], v[180:181] op_sel_hi:[0,1]
	v_pk_mul_f32 v[180:181], v[90:91], v[180:181]
	v_cvt_pk_bf16_f32 v178, v178, v179
	s_nop 0
	v_cvt_pk_bf16_f32 v179, v180, v181
	v_add_co_u32_e32 v180, vcc, s0, v170
	s_mov_b32 s0, 0x18000
	s_nop 0
	v_addc_co_u32_e32 v181, vcc, 0, v171, vcc
	global_store_dwordx4 v[180:181], v[176:179], off offset:1024 sc1 nt
	v_mul_f32_e32 v180, 0xbfb8aa3b, v163
	s_nop 0
	v_pk_mul_f32 v[176:177], v[68:69], v[180:181] op_sel_hi:[1,0]
	v_pk_mul_f32 v[178:179], v[70:71], v[180:181] op_sel_hi:[1,0]
	v_exp_f32_e32 v176, v176
	v_exp_f32_e32 v177, v177
	v_exp_f32_e32 v178, v178
	v_exp_f32_e32 v179, v179
	v_pk_add_f32 v[176:177], v[176:177], 1.0 op_sel_hi:[1,0]
	s_nop 0
	v_rcp_f32_e32 v176, v176
	v_pk_add_f32 v[178:179], v[178:179], 1.0 op_sel_hi:[1,0]
	v_rcp_f32_e32 v177, v177
	v_rcp_f32_e32 v178, v178
	v_rcp_f32_e32 v179, v179
	v_pk_mul_f32 v[176:177], v[182:183], v[176:177] op_sel_hi:[0,1]
	v_pk_mul_f32 v[176:177], v[80:81], v[176:177]
	v_pk_mul_f32 v[178:179], v[182:183], v[178:179] op_sel_hi:[0,1]
	v_pk_mul_f32 v[178:179], v[82:83], v[178:179]
	v_cvt_pk_bf16_f32 v176, v176, v177
	s_nop 0
	v_cvt_pk_bf16_f32 v177, v178, v179
	v_pk_mul_f32 v[178:179], v[64:65], v[180:181] op_sel_hi:[1,0]
	v_pk_mul_f32 v[180:181], v[66:67], v[180:181] op_sel_hi:[1,0]
	v_exp_f32_e32 v178, v178
	v_exp_f32_e32 v179, v179
	v_exp_f32_e32 v180, v180
	v_exp_f32_e32 v181, v181
	v_pk_add_f32 v[178:179], v[178:179], 1.0 op_sel_hi:[1,0]
	s_nop 0
	v_rcp_f32_e32 v178, v178
	v_pk_add_f32 v[180:181], v[180:181], 1.0 op_sel_hi:[1,0]
	v_rcp_f32_e32 v179, v179
	v_rcp_f32_e32 v180, v180
	v_rcp_f32_e32 v181, v181
	v_pk_mul_f32 v[178:179], v[182:183], v[178:179] op_sel_hi:[0,1]
	v_pk_mul_f32 v[178:179], v[72:73], v[178:179]
	v_pk_mul_f32 v[180:181], v[182:183], v[180:181] op_sel_hi:[0,1]
	v_pk_mul_f32 v[180:181], v[74:75], v[180:181]
	v_cvt_pk_bf16_f32 v178, v178, v179
	v_mov_b32_e32 v182, v143
	v_cvt_pk_bf16_f32 v179, v180, v181
	v_add_co_u32_e32 v180, vcc, s0, v170
	s_mov_b32 s0, 0x48000
	s_nop 0
	v_addc_co_u32_e32 v181, vcc, 0, v171, vcc
	global_store_dwordx4 v[180:181], v[176:179], off offset:1024 sc1 nt
	v_mul_f32_e32 v180, 0xbfb8aa3b, v142
	s_nop 0
	v_pk_mul_f32 v[176:177], v[52:53], v[180:181] op_sel_hi:[1,0]
	v_pk_mul_f32 v[178:179], v[54:55], v[180:181] op_sel_hi:[1,0]
	v_exp_f32_e32 v176, v176
	v_exp_f32_e32 v177, v177
	v_exp_f32_e32 v178, v178
	v_exp_f32_e32 v179, v179
	v_pk_add_f32 v[176:177], v[176:177], 1.0 op_sel_hi:[1,0]
	s_nop 0
	v_rcp_f32_e32 v176, v176
	v_pk_add_f32 v[178:179], v[178:179], 1.0 op_sel_hi:[1,0]
	v_rcp_f32_e32 v177, v177
	v_rcp_f32_e32 v178, v178
	v_rcp_f32_e32 v179, v179
	v_pk_mul_f32 v[176:177], v[142:143], v[176:177] op_sel_hi:[0,1]
	v_pk_mul_f32 v[176:177], v[60:61], v[176:177]
	v_pk_mul_f32 v[178:179], v[142:143], v[178:179] op_sel_hi:[0,1]
	v_pk_mul_f32 v[178:179], v[62:63], v[178:179]
	v_cvt_pk_bf16_f32 v176, v176, v177
	s_nop 0
	v_cvt_pk_bf16_f32 v177, v178, v179
	v_pk_mul_f32 v[178:179], v[44:45], v[180:181] op_sel_hi:[1,0]
	v_pk_mul_f32 v[180:181], v[46:47], v[180:181] op_sel_hi:[1,0]
	v_exp_f32_e32 v178, v178
	v_exp_f32_e32 v179, v179
	v_exp_f32_e32 v180, v180
	v_exp_f32_e32 v181, v181
	v_pk_add_f32 v[178:179], v[178:179], 1.0 op_sel_hi:[1,0]
	s_nop 0
	v_rcp_f32_e32 v178, v178
	v_pk_add_f32 v[180:181], v[180:181], 1.0 op_sel_hi:[1,0]
	v_rcp_f32_e32 v179, v179
	v_rcp_f32_e32 v180, v180
	v_rcp_f32_e32 v181, v181
	v_pk_mul_f32 v[178:179], v[142:143], v[178:179] op_sel_hi:[0,1]
	v_pk_mul_f32 v[178:179], v[56:57], v[178:179]
	v_pk_mul_f32 v[180:181], v[142:143], v[180:181] op_sel_hi:[0,1]
	v_pk_mul_f32 v[180:181], v[58:59], v[180:181]
	v_cvt_pk_bf16_f32 v178, v178, v179
	s_nop 0
	v_cvt_pk_bf16_f32 v179, v180, v181
	v_add_co_u32_e32 v180, vcc, s87, v170
	s_nop 1
	v_addc_co_u32_e32 v181, vcc, 0, v171, vcc
	global_store_dwordx4 v[180:181], v[176:179], off offset:1024 sc1 nt
	v_mul_f32_e32 v180, 0xbfb8aa3b, v143
	s_nop 0
	v_pk_mul_f32 v[176:177], v[36:37], v[180:181] op_sel_hi:[1,0]
	v_pk_mul_f32 v[178:179], v[38:39], v[180:181] op_sel_hi:[1,0]
	v_exp_f32_e32 v176, v176
	v_exp_f32_e32 v177, v177
	v_exp_f32_e32 v178, v178
	v_exp_f32_e32 v179, v179
	v_pk_add_f32 v[176:177], v[176:177], 1.0 op_sel_hi:[1,0]
	s_nop 0
	v_rcp_f32_e32 v176, v176
	v_pk_add_f32 v[178:179], v[178:179], 1.0 op_sel_hi:[1,0]
	v_rcp_f32_e32 v177, v177
	v_rcp_f32_e32 v178, v178
	v_rcp_f32_e32 v179, v179
	v_pk_mul_f32 v[176:177], v[182:183], v[176:177] op_sel_hi:[0,1]
	v_pk_mul_f32 v[176:177], v[48:49], v[176:177]
	v_pk_mul_f32 v[178:179], v[182:183], v[178:179] op_sel_hi:[0,1]
; __device__ __forceinline__ unsigned cvt_pk_bf16(float lo, float hi) { unsigned r; asm volatile("v_cvt_pk_bf16_f32 %0, %1, %2" : "=v"(r) : "v"(lo), "v"(hi)); return r; }
;     __device__ __forceinline__ void operator()(const f32x4 (&acc)[2][2][4][2], const Unit& u, int ui, int wr, int wc, int fr, int fq) const {
;     ...
;                 for (int m = 0; m < 4; ++m) { const float r = rs[ai][m]; bf16_t* rowp = UG + (size_t)(row0 + ai * HALF + m * 16) * 1024 + 512 + (u.pn - 2) * HALF + cw;
;                     const float c1 = r * -1.44269504089f; u32x4 w;
; #pragma unroll
;                     for (int n = 0; n < 2; ++n)
; #pragma unroll
;                         for (int p = 0; p < 2; ++p) { const f32x2 av = (f32x2){acc[ai][0][m][n][2 * p], acc[ai][0][m][n][2 * p + 1]}, gt = (f32x2){acc[ai][1][m][n][2 * p], acc[ai][1][m][n][2 * p + 1]};
;                             const f32x2 t = gt * c1; f32x2 d; d.x = __builtin_amdgcn_exp2f(t.x); d.y = __builtin_amdgcn_exp2f(t.y); d = d + 1.0f;
;                             f32x2 q; q.x = __builtin_amdgcn_rcpf(d.x); q.y = __builtin_amdgcn_rcpf(d.y);
;                             const f32x2 hh = av * (q * r); w[2 * n + p] = cvt_pk_bf16(hh.x, hh.y); }
;                     *(u32x4*)rowp = w; }
	v_pk_mul_f32 v[178:179], v[50:51], v[178:179]
	v_cvt_pk_bf16_f32 v176, v176, v177
	s_nop 0
	v_cvt_pk_bf16_f32 v177, v178, v179
	v_pk_mul_f32 v[178:179], v[28:29], v[180:181] op_sel_hi:[1,0]
	v_pk_mul_f32 v[180:181], v[30:31], v[180:181] op_sel_hi:[1,0]
	v_exp_f32_e32 v178, v178
	v_exp_f32_e32 v179, v179
	v_exp_f32_e32 v180, v180
	v_exp_f32_e32 v181, v181
	v_pk_add_f32 v[178:179], v[178:179], 1.0 op_sel_hi:[1,0]
	s_nop 0
	v_rcp_f32_e32 v178, v178
	v_pk_add_f32 v[180:181], v[180:181], 1.0 op_sel_hi:[1,0]
	v_rcp_f32_e32 v179, v179
	v_rcp_f32_e32 v180, v180
	v_rcp_f32_e32 v181, v181
	v_pk_mul_f32 v[178:179], v[182:183], v[178:179] op_sel_hi:[0,1]
	v_pk_mul_f32 v[178:179], v[40:41], v[178:179]
	v_pk_mul_f32 v[180:181], v[182:183], v[180:181] op_sel_hi:[0,1]
	v_pk_mul_f32 v[180:181], v[42:43], v[180:181]
	v_cvt_pk_bf16_f32 v178, v178, v179
	v_mov_b32_e32 v182, v141
	v_cvt_pk_bf16_f32 v179, v180, v181
	v_add_co_u32_e32 v180, vcc, s0, v170
	s_mov_b32 s0, 0x50000
	s_nop 0
	v_addc_co_u32_e32 v181, vcc, 0, v171, vcc
	global_store_dwordx4 v[180:181], v[176:179], off offset:1024 sc1 nt
	v_mul_f32_e32 v180, 0xbfb8aa3b, v140
	s_nop 0
	v_pk_mul_f32 v[176:177], v[20:21], v[180:181] op_sel_hi:[1,0]
	v_pk_mul_f32 v[178:179], v[22:23], v[180:181] op_sel_hi:[1,0]
	v_exp_f32_e32 v176, v176
	v_exp_f32_e32 v177, v177
	v_exp_f32_e32 v178, v178
	v_exp_f32_e32 v179, v179
	v_pk_add_f32 v[176:177], v[176:177], 1.0 op_sel_hi:[1,0]
	s_nop 0
	v_rcp_f32_e32 v176, v176
	v_pk_add_f32 v[178:179], v[178:179], 1.0 op_sel_hi:[1,0]
	v_rcp_f32_e32 v177, v177
	v_rcp_f32_e32 v178, v178
	v_rcp_f32_e32 v179, v179
	v_pk_mul_f32 v[176:177], v[140:141], v[176:177] op_sel_hi:[0,1]
	v_pk_mul_f32 v[176:177], v[32:33], v[176:177]
	v_pk_mul_f32 v[178:179], v[140:141], v[178:179] op_sel_hi:[0,1]
	v_pk_mul_f32 v[178:179], v[34:35], v[178:179]
	v_cvt_pk_bf16_f32 v176, v176, v177
	s_nop 0
	v_cvt_pk_bf16_f32 v177, v178, v179
	v_pk_mul_f32 v[178:179], v[12:13], v[180:181] op_sel_hi:[1,0]
	v_pk_mul_f32 v[180:181], v[14:15], v[180:181] op_sel_hi:[1,0]
	v_exp_f32_e32 v178, v178
	v_exp_f32_e32 v179, v179
	v_exp_f32_e32 v180, v180
	v_exp_f32_e32 v181, v181
	v_pk_add_f32 v[178:179], v[178:179], 1.0 op_sel_hi:[1,0]
	s_nop 0
	v_rcp_f32_e32 v178, v178
	v_pk_add_f32 v[180:181], v[180:181], 1.0 op_sel_hi:[1,0]
	v_rcp_f32_e32 v179, v179
	v_rcp_f32_e32 v180, v180
	v_rcp_f32_e32 v181, v181
	v_pk_mul_f32 v[178:179], v[140:141], v[178:179] op_sel_hi:[0,1]
	v_pk_mul_f32 v[178:179], v[24:25], v[178:179]
	v_pk_mul_f32 v[180:181], v[140:141], v[180:181] op_sel_hi:[0,1]
	v_pk_mul_f32 v[180:181], v[26:27], v[180:181]
	v_cvt_pk_bf16_f32 v178, v178, v179
	s_nop 0
	v_cvt_pk_bf16_f32 v179, v180, v181
	v_add_co_u32_e32 v180, vcc, s0, v170
	s_nop 1
	v_addc_co_u32_e32 v181, vcc, 0, v171, vcc
	global_store_dwordx4 v[180:181], v[176:179], off offset:1024 sc1 nt
	v_mul_f32_e32 v180, 0xbfb8aa3b, v141
	v_add_co_u32_e32 v170, vcc, 0x58000, v170
	v_pk_mul_f32 v[176:177], v[4:5], v[180:181] op_sel_hi:[1,0]
	v_pk_mul_f32 v[178:179], v[6:7], v[180:181] op_sel_hi:[1,0]
	v_exp_f32_e32 v176, v176
	v_exp_f32_e32 v177, v177
	v_exp_f32_e32 v178, v178
	v_exp_f32_e32 v179, v179
	v_addc_co_u32_e32 v171, vcc, 0, v171, vcc
	v_pk_add_f32 v[176:177], v[176:177], 1.0 op_sel_hi:[1,0]
	v_pk_add_f32 v[178:179], v[178:179], 1.0 op_sel_hi:[1,0]
	v_rcp_f32_e32 v176, v176
	v_rcp_f32_e32 v177, v177
	v_rcp_f32_e32 v178, v178
	v_rcp_f32_e32 v179, v179
	v_pk_mul_f32 v[176:177], v[182:183], v[176:177] op_sel_hi:[0,1]
	v_pk_mul_f32 v[176:177], v[16:17], v[176:177]
	v_pk_mul_f32 v[178:179], v[182:183], v[178:179] op_sel_hi:[0,1]
	v_pk_mul_f32 v[178:179], v[18:19], v[178:179]
	v_cvt_pk_bf16_f32 v176, v176, v177
	s_nop 0
	v_cvt_pk_bf16_f32 v177, v178, v179
	v_pk_mul_f32 v[178:179], v[0:1], v[180:181] op_sel_hi:[1,0]
	v_pk_mul_f32 v[180:181], v[2:3], v[180:181] op_sel_hi:[1,0]
	v_exp_f32_e32 v178, v178
	v_exp_f32_e32 v179, v179
	v_exp_f32_e32 v180, v180
	v_exp_f32_e32 v181, v181
	v_pk_add_f32 v[178:179], v[178:179], 1.0 op_sel_hi:[1,0]
	s_nop 0
	v_rcp_f32_e32 v178, v178
	v_rcp_f32_e32 v179, v179
	v_pk_add_f32 v[180:181], v[180:181], 1.0 op_sel_hi:[1,0]
	v_pk_mul_f32 v[178:179], v[182:183], v[178:179] op_sel_hi:[0,1]
	v_rcp_f32_e32 v180, v180
	v_rcp_f32_e32 v181, v181
	v_pk_mul_f32 v[178:179], v[8:9], v[178:179]
	v_pk_mul_f32 v[180:181], v[182:183], v[180:181] op_sel_hi:[0,1]
	v_cvt_pk_bf16_f32 v178, v178, v179
	v_pk_mul_f32 v[180:181], v[10:11], v[180:181]
	s_nop 0
	v_cvt_pk_bf16_f32 v179, v180, v181
	global_store_dwordx4 v[170:171], v[176:179], off offset:1024 sc1 nt
	s_cbranch_execz .LBB0_799

; __device__ __forceinline__ u32x4 pack8(const f32x4& a, const f32x4& b) { u32x4 w; w.x = cvt_pk_bf16(a[0], a[1]); w.y = cvt_pk_bf16(a[2], a[3]); w.z = cvt_pk_bf16(b[0], b[1]); w.w = cvt_pk_bf16(b[2], b[3]); return w; }
;     __device__ __forceinline__ void operator()(const f32x4 (&acc)[2][2][4][2], const Unit& u, int ui, int wr, int wc, int fr, int fq) const {
;     ...
;         if (u.pn < 2) {
; #pragma unroll
;             for (int ai = 0; ai < 2; ++ai)
; #pragma unroll
;                 for (int m = 0; m < 4; ++m) { const float r = rs[ai][m]; bf16_t* rowp = UG + (size_t)(row0 + ai * HALF + m * 16) * 1024 + u.pn * BM + cw;
; #pragma unroll
;                     for (int bj = 0; bj < 2; ++bj) *(u32x4*)(rowp + bj * HALF) = pack8(acc[ai][bj][m][0] * r, acc[ai][bj][m][1] * r); }
.LBB0_799:
	s_lshl_b32 s0, s44, 8
	v_lshlrev_b64 v[166:167], 11, v[166:167]
	s_ashr_i32 s1, s0, 31
	v_lshl_add_u64 v[166:167], s[20:21], 0, v[166:167]
	v_lshl_add_u64 v[166:167], s[0:1], 1, v[166:167]
	v_lshl_add_u64 v[166:167], v[168:169], 1, v[166:167]
	s_waitcnt lgkmcnt(0)
	v_pk_mul_f32 v[126:127], v[126:127], v[164:165] op_sel_hi:[1,0]
	v_pk_mul_f32 v[124:125], v[124:125], v[164:165] op_sel_hi:[1,0]
	v_pk_mul_f32 v[168:169], v[122:123], v[164:165] op_sel_hi:[1,0]
	v_pk_mul_f32 v[122:123], v[120:121], v[164:165] op_sel_hi:[1,0]
	v_cvt_pk_bf16_f32 v120, v124, v125
	v_cvt_pk_bf16_f32 v121, v126, v127
	v_pk_mul_f32 v[118:119], v[118:119], v[164:165] op_sel_hi:[1,0]
	v_cvt_pk_bf16_f32 v122, v122, v123
	v_cvt_pk_bf16_f32 v123, v168, v169
	global_store_dwordx4 v[166:167], v[120:123], off sc1 nt
	v_pk_mul_f32 v[116:117], v[116:117], v[164:165] op_sel_hi:[1,0]
	s_mov_b32 s0, 0x8000
	v_pk_mul_f32 v[120:121], v[110:111], v[164:165] op_sel_hi:[1,0]
	v_pk_mul_f32 v[110:111], v[108:109], v[164:165] op_sel_hi:[1,0]
	v_cvt_pk_bf16_f32 v108, v116, v117
	v_cvt_pk_bf16_f32 v109, v118, v119
	v_pk_mul_f32 v[96:97], v[96:97], v[162:163] op_sel_hi:[1,0]
	v_cvt_pk_bf16_f32 v110, v110, v111
	v_cvt_pk_bf16_f32 v111, v120, v121
	global_store_dwordx4 v[166:167], v[108:111], off offset:256 sc1 nt
	v_pk_mul_f32 v[86:87], v[86:87], v[162:163] op_sel_hi:[1,0]
	v_pk_mul_f32 v[84:85], v[84:85], v[162:163] op_sel_hi:[1,0]
	v_mov_b32_e32 v110, v165
	v_pk_mul_f32 v[112:113], v[112:113], v[110:111] op_sel_hi:[1,0]
	v_pk_mul_f32 v[116:117], v[106:107], v[110:111] op_sel_hi:[1,0]
	v_pk_mul_f32 v[106:107], v[104:105], v[110:111] op_sel_hi:[1,0]
	v_cvt_pk_bf16_f32 v104, v112, v113
	v_add_co_u32_e32 v112, vcc, s0, v166
	v_pk_mul_f32 v[114:115], v[114:115], v[110:111] op_sel_hi:[1,0]
	s_nop 0
	v_addc_co_u32_e32 v113, vcc, 0, v167, vcc
	v_cvt_pk_bf16_f32 v105, v114, v115
	v_cvt_pk_bf16_f32 v106, v106, v107
	v_cvt_pk_bf16_f32 v107, v116, v117
	global_store_dwordx4 v[112:113], v[104:107], off sc1 nt
	v_lshl_add_u64 v[108:109], v[166:167], 0, s[56:57]
	v_pk_mul_f32 v[102:103], v[102:103], v[110:111] op_sel_hi:[1,0]
	v_pk_mul_f32 v[104:105], v[94:95], v[110:111] op_sel_hi:[1,0]
	v_pk_mul_f32 v[94:95], v[92:93], v[110:111] op_sel_hi:[1,0]
	v_pk_mul_f32 v[100:101], v[100:101], v[110:111] op_sel_hi:[1,0]
	s_mov_b64 s[0:1], 0x10000
	v_cvt_pk_bf16_f32 v92, v100, v101
	v_cvt_pk_bf16_f32 v93, v102, v103
	v_cvt_pk_bf16_f32 v94, v94, v95
	v_cvt_pk_bf16_f32 v95, v104, v105
	global_store_dwordx4 v[108:109], v[92:95], off offset:256 sc1 nt
	v_pk_mul_f32 v[60:61], v[60:61], v[142:143] op_sel_hi:[1,0]
	v_pk_mul_f32 v[62:63], v[62:63], v[142:143] op_sel_hi:[1,0]
	v_lshl_add_u64 v[92:93], v[166:167], 0, s[0:1]
	v_pk_mul_f32 v[94:95], v[98:99], v[162:163] op_sel_hi:[1,0]
	s_mov_b32 s0, 0x10000
	v_pk_mul_f32 v[98:99], v[90:91], v[162:163] op_sel_hi:[1,0]
	v_pk_mul_f32 v[90:91], v[88:89], v[162:163] op_sel_hi:[1,0]
	v_cvt_pk_bf16_f32 v88, v96, v97
	v_cvt_pk_bf16_f32 v89, v94, v95
	v_add_co_u32_e32 v94, vcc, s0, v166
	v_cvt_pk_bf16_f32 v90, v90, v91
	v_cvt_pk_bf16_f32 v91, v98, v99
	s_mov_b64 s[0:1], 0x18000
	s_nop 0
	v_addc_co_u32_e32 v95, vcc, 0, v167, vcc
	global_store_dwordx4 v[94:95], v[88:91], off sc1 nt
	v_pk_mul_f32 v[54:55], v[54:55], v[142:143] op_sel_hi:[1,0]
	v_pk_mul_f32 v[52:53], v[52:53], v[142:143] op_sel_hi:[1,0]
	v_pk_mul_f32 v[88:89], v[78:79], v[162:163] op_sel_hi:[1,0]
	v_pk_mul_f32 v[78:79], v[76:77], v[162:163] op_sel_hi:[1,0]
	v_cvt_pk_bf16_f32 v76, v84, v85
	v_cvt_pk_bf16_f32 v77, v86, v87
	v_pk_mul_f32 v[32:33], v[32:33], v[140:141] op_sel_hi:[1,0]
	v_cvt_pk_bf16_f32 v78, v78, v79
	v_cvt_pk_bf16_f32 v79, v88, v89
	global_store_dwordx4 v[92:93], v[76:79], off offset:256 sc1 nt
	v_pk_mul_f32 v[22:23], v[22:23], v[140:141] op_sel_hi:[1,0]
	v_pk_mul_f32 v[20:21], v[20:21], v[140:141] op_sel_hi:[1,0]
	v_mov_b32_e32 v78, v163
	v_lshl_add_u64 v[76:77], v[166:167], 0, s[0:1]
	v_pk_mul_f32 v[80:81], v[80:81], v[78:79] op_sel_hi:[1,0]
	s_mov_b32 s0, 0x18000
	v_pk_mul_f32 v[84:85], v[74:75], v[78:79] op_sel_hi:[1,0]
	v_pk_mul_f32 v[74:75], v[72:73], v[78:79] op_sel_hi:[1,0]
	v_cvt_pk_bf16_f32 v72, v80, v81
	v_add_co_u32_e32 v80, vcc, s0, v166
	v_pk_mul_f32 v[82:83], v[82:83], v[78:79] op_sel_hi:[1,0]
	s_nop 0
	v_addc_co_u32_e32 v81, vcc, 0, v167, vcc
	v_cvt_pk_bf16_f32 v73, v82, v83
	v_cvt_pk_bf16_f32 v74, v74, v75
	v_cvt_pk_bf16_f32 v75, v84, v85
; __device__ __forceinline__ u32x4 pack8(const f32x4& a, const f32x4& b) { u32x4 w; w.x = cvt_pk_bf16(a[0], a[1]); w.y = cvt_pk_bf16(a[2], a[3]); w.z = cvt_pk_bf16(b[0], b[1]); w.w = cvt_pk_bf16(b[2], b[3]); return w; }
;     __device__ __forceinline__ void operator()(const f32x4 (&acc)[2][2][4][2], const Unit& u, int ui, int wr, int wc, int fr, int fq) const {
;     ...
;         if (u.pn < 2) {
; #pragma unroll
;             for (int ai = 0; ai < 2; ++ai)
; #pragma unroll
;                 for (int m = 0; m < 4; ++m) { const float r = rs[ai][m]; bf16_t* rowp = UG + (size_t)(row0 + ai * HALF + m * 16) * 1024 + u.pn * BM + cw;
; #pragma unroll
;                     for (int bj = 0; bj < 2; ++bj) *(u32x4*)(rowp + bj * HALF) = pack8(acc[ai][bj][m][0] * r, acc[ai][bj][m][1] * r); }
	global_store_dwordx4 v[80:81], v[72:75], off sc1 nt
	v_pk_mul_f32 v[70:71], v[70:71], v[78:79] op_sel_hi:[1,0]
	v_pk_mul_f32 v[68:69], v[68:69], v[78:79] op_sel_hi:[1,0]
	v_pk_mul_f32 v[72:73], v[66:67], v[78:79] op_sel_hi:[1,0]
	v_pk_mul_f32 v[66:67], v[64:65], v[78:79] op_sel_hi:[1,0]
	v_cvt_pk_bf16_f32 v64, v68, v69
	v_cvt_pk_bf16_f32 v65, v70, v71
	s_mov_b64 s[0:1], 0x40000
	v_cvt_pk_bf16_f32 v66, v66, v67
	v_cvt_pk_bf16_f32 v67, v72, v73
	global_store_dwordx4 v[76:77], v[64:67], off offset:256 sc1 nt
	s_nop 1
	v_pk_mul_f32 v[66:67], v[58:59], v[142:143] op_sel_hi:[1,0]
	v_pk_mul_f32 v[58:59], v[56:57], v[142:143] op_sel_hi:[1,0]
	v_cvt_pk_bf16_f32 v56, v60, v61
	v_add_co_u32_e32 v60, vcc, s87, v166
	v_cvt_pk_bf16_f32 v57, v62, v63
	v_cvt_pk_bf16_f32 v58, v58, v59
	v_cvt_pk_bf16_f32 v59, v66, v67
	v_lshl_add_u64 v[64:65], v[166:167], 0, s[0:1]
	s_nop 0
	v_addc_co_u32_e32 v61, vcc, 0, v167, vcc
	global_store_dwordx4 v[60:61], v[56:59], off sc1 nt
	s_mov_b64 s[0:1], 0x48000
	s_nop 0
	v_pk_mul_f32 v[56:57], v[46:47], v[142:143] op_sel_hi:[1,0]
	v_pk_mul_f32 v[46:47], v[44:45], v[142:143] op_sel_hi:[1,0]
	v_cvt_pk_bf16_f32 v44, v52, v53
	v_cvt_pk_bf16_f32 v45, v54, v55
	s_nop 0
	v_cvt_pk_bf16_f32 v46, v46, v47
	v_cvt_pk_bf16_f32 v47, v56, v57
	global_store_dwordx4 v[64:65], v[44:47], off offset:256 sc1 nt
	s_nop 1
	v_mov_b32_e32 v46, v143
	v_lshl_add_u64 v[44:45], v[166:167], 0, s[0:1]
	v_pk_mul_f32 v[48:49], v[48:49], v[46:47] op_sel_hi:[1,0]
	s_mov_b32 s0, 0x48000
	v_pk_mul_f32 v[52:53], v[42:43], v[46:47] op_sel_hi:[1,0]
	v_pk_mul_f32 v[42:43], v[40:41], v[46:47] op_sel_hi:[1,0]
	v_cvt_pk_bf16_f32 v40, v48, v49
	v_add_co_u32_e32 v48, vcc, s0, v166
	v_pk_mul_f32 v[50:51], v[50:51], v[46:47] op_sel_hi:[1,0]
	s_nop 0
	v_addc_co_u32_e32 v49, vcc, 0, v167, vcc
	v_cvt_pk_bf16_f32 v41, v50, v51
	v_cvt_pk_bf16_f32 v42, v42, v43
	v_cvt_pk_bf16_f32 v43, v52, v53
	global_store_dwordx4 v[48:49], v[40:43], off sc1 nt
	v_pk_mul_f32 v[38:39], v[38:39], v[46:47] op_sel_hi:[1,0]
	v_pk_mul_f32 v[36:37], v[36:37], v[46:47] op_sel_hi:[1,0]
	v_pk_mul_f32 v[40:41], v[30:31], v[46:47] op_sel_hi:[1,0]
	v_pk_mul_f32 v[30:31], v[28:29], v[46:47] op_sel_hi:[1,0]
	v_cvt_pk_bf16_f32 v28, v36, v37
	v_cvt_pk_bf16_f32 v29, v38, v39
	s_mov_b64 s[0:1], 0x50000
	v_cvt_pk_bf16_f32 v30, v30, v31
	v_cvt_pk_bf16_f32 v31, v40, v41
	global_store_dwordx4 v[44:45], v[28:31], off offset:256 sc1 nt
	s_nop 1
	v_lshl_add_u64 v[28:29], v[166:167], 0, s[0:1]
	v_pk_mul_f32 v[30:31], v[34:35], v[140:141] op_sel_hi:[1,0]
	s_mov_b32 s0, 0x50000
	v_pk_mul_f32 v[34:35], v[26:27], v[140:141] op_sel_hi:[1,0]
	v_pk_mul_f32 v[26:27], v[24:25], v[140:141] op_sel_hi:[1,0]
	v_cvt_pk_bf16_f32 v24, v32, v33
	v_cvt_pk_bf16_f32 v25, v30, v31
	v_add_co_u32_e32 v30, vcc, s0, v166
	v_cvt_pk_bf16_f32 v26, v26, v27
	v_cvt_pk_bf16_f32 v27, v34, v35
	s_mov_b64 s[0:1], 0x58000
	s_nop 0
	v_addc_co_u32_e32 v31, vcc, 0, v167, vcc
	global_store_dwordx4 v[30:31], v[24:27], off sc1 nt
	s_nop 1
	v_pk_mul_f32 v[24:25], v[14:15], v[140:141] op_sel_hi:[1,0]
	v_pk_mul_f32 v[14:15], v[12:13], v[140:141] op_sel_hi:[1,0]
	v_cvt_pk_bf16_f32 v12, v20, v21
	v_cvt_pk_bf16_f32 v13, v22, v23
	s_nop 0
	v_cvt_pk_bf16_f32 v14, v14, v15
	v_cvt_pk_bf16_f32 v15, v24, v25
	global_store_dwordx4 v[28:29], v[12:15], off offset:256 sc1 nt
	s_nop 1
	v_mov_b32_e32 v14, v141
	v_lshl_add_u64 v[12:13], v[166:167], 0, s[0:1]
	v_pk_mul_f32 v[16:17], v[16:17], v[14:15] op_sel_hi:[1,0]
	s_mov_b32 s0, 0x58000
	v_pk_mul_f32 v[20:21], v[10:11], v[14:15] op_sel_hi:[1,0]
	v_pk_mul_f32 v[10:11], v[8:9], v[14:15] op_sel_hi:[1,0]
	v_cvt_pk_bf16_f32 v8, v16, v17
	v_add_co_u32_e32 v16, vcc, s0, v166
	v_pk_mul_f32 v[18:19], v[18:19], v[14:15] op_sel_hi:[1,0]
	s_nop 0
	v_addc_co_u32_e32 v17, vcc, 0, v167, vcc
	v_cvt_pk_bf16_f32 v9, v18, v19
	v_cvt_pk_bf16_f32 v10, v10, v11
	v_cvt_pk_bf16_f32 v11, v20, v21
	global_store_dwordx4 v[16:17], v[8:11], off sc1 nt
	v_pk_mul_f32 v[6:7], v[6:7], v[14:15] op_sel_hi:[1,0]
	v_pk_mul_f32 v[4:5], v[4:5], v[14:15] op_sel_hi:[1,0]
	v_pk_mul_f32 v[8:9], v[2:3], v[14:15] op_sel_hi:[1,0]
	v_pk_mul_f32 v[2:3], v[0:1], v[14:15] op_sel_hi:[1,0]
	v_cvt_pk_bf16_f32 v0, v4, v5
	v_cvt_pk_bf16_f32 v1, v6, v7
	s_nop 0
	v_cvt_pk_bf16_f32 v2, v2, v3
	v_cvt_pk_bf16_f32 v3, v8, v9
	global_store_dwordx4 v[12:13], v[0:3], off offset:256 sc1 nt
	s_andn2_b64 vcc, exec, s[8:9]
	s_mov_b64 s[0:1], -1
	s_cbranch_vccnz .LBB0_788
